# v15 + nt on dead-after-read loads: split-K slabs, S5 local end states, V stat partials
# speedup vs baseline: 1.0062x; 1.0016x over previous
.LBB0_577:
	global_load_dwordx2 v[4:5], v[2:3], off nt
	s_waitcnt vmcnt(0) lgkmcnt(0)
	ds_bpermute_b32 v6, v8, v4
	ds_bpermute_b32 v7, v8, v5
	s_waitcnt lgkmcnt(0)
	v_pk_add_f32 v[4:5], v[4:5], v[6:7]
	ds_bpermute_b32 v6, v9, v4
	ds_bpermute_b32 v7, v9, v5
	s_waitcnt lgkmcnt(0)
	v_pk_add_f32 v[4:5], v[4:5], v[6:7]
	ds_bpermute_b32 v6, v10, v4
	ds_bpermute_b32 v7, v10, v5
	s_waitcnt lgkmcnt(0)
	v_pk_add_f32 v[4:5], v[4:5], v[6:7]
	ds_bpermute_b32 v6, v11, v4
	ds_bpermute_b32 v7, v11, v5
	s_waitcnt lgkmcnt(0)
	v_pk_add_f32 v[4:5], v[4:5], v[6:7]
	ds_bpermute_b32 v6, v12, v4
	ds_bpermute_b32 v7, v12, v5
	s_waitcnt lgkmcnt(0)
	v_pk_add_f32 v[4:5], v[4:5], v[6:7]
	ds_bpermute_b32 v6, v13, v4
	ds_bpermute_b32 v7, v13, v5
	s_and_saveexec_b64 s[8:9], s[2:3]
	s_cbranch_execz .LBB0_576
	s_waitcnt lgkmcnt(0)
	v_pk_add_f32 v[4:5], v[4:5], v[6:7]
	s_mov_b32 s4, 0x39800000
	v_pk_mul_f32 v[4:5], v[4:5], s[4:5] op_sel_hi:[1,0]
	s_mov_b32 s1, 0xf800000
	v_fma_f32 v5, -v4, v4, v5
	v_add_f32_e32 v5, 0x358637bd, v5
	v_mul_f32_e32 v6, 0x4f800000, v5
	v_cmp_gt_f32_e32 vcc, s1, v5
	s_nop 1
	v_cndmask_b32_e32 v5, v5, v6, vcc
	v_sqrt_f32_e32 v6, v5
	s_nop 0
	v_add_u32_e32 v7, -1, v6
	v_fma_f32 v15, -v7, v6, v5
	v_add_u32_e32 v14, 1, v6
	v_cmp_ge_f32_e64 s[4:5], 0, v15
	s_nop 1
	v_cndmask_b32_e64 v7, v6, v7, s[4:5]
	v_fma_f32 v6, -v14, v6, v5
	v_cmp_lt_f32_e64 s[4:5], 0, v6
	s_nop 1
	v_cndmask_b32_e64 v6, v7, v14, s[4:5]
	v_mul_f32_e32 v7, 0x37800000, v6
	v_cndmask_b32_e32 v6, v6, v7, vcc
	v_cmp_class_f32_e32 vcc, v5, v0
	s_nop 1
	v_cndmask_b32_e32 v5, v6, v5, vcc
	v_div_scale_f32 v6, s[4:5], v5, v5, 1.0
	v_rcp_f32_e32 v7, v6
	s_nop 0
	v_fma_f32 v14, -v6, v7, 1.0
	v_fmac_f32_e32 v7, v14, v7
	v_div_scale_f32 v14, vcc, 1.0, v5, 1.0
	v_mul_f32_e32 v15, v14, v7
	v_fma_f32 v16, -v6, v15, v14
	v_fmac_f32_e32 v15, v16, v7
	v_fma_f32 v6, -v6, v15, v14
	v_div_fmas_f32 v6, v6, v7, v15
	v_div_fixup_f32 v5, v6, v5, 1.0
	global_store_dwordx2 v203, v[4:5], s[6:7]
	s_branch .LBB0_576

.LBB0_771:
	s_add_i32 s14, s4, s94
	s_cmpk_lt_i32 s14, 0x4200
	s_cselect_b64 s[8:9], -1, 0
	s_and_b64 s[0:1], s[8:9], exec
	s_cselect_b32 s6, s14, s4
	s_ashr_i32 s7, s6, 31
	s_lshl_b64 s[0:1], s[6:7], 12
	v_lshl_add_u64 v[32:33], v[80:81], 0, s[0:1]
	s_waitcnt vmcnt(0)
	global_load_dwordx4 v[62:65], v[32:33], off
	global_load_dwordx4 v[58:61], v[32:33], off offset:1024
	global_load_dwordx4 v[54:57], v[32:33], off offset:2048
	global_load_dwordx4 v[50:53], v[32:33], off offset:3072
	v_cvt_f32_f16_sdwa v167, v46 dst_sel:DWORD dst_unused:UNUSED_PAD src0_sel:WORD_1
	v_cvt_f32_f16_e32 v166, v46
	v_cvt_f32_f16_sdwa v163, v47 dst_sel:DWORD dst_unused:UNUSED_PAD src0_sel:WORD_1
	v_cvt_f32_f16_e32 v162, v47
	v_cvt_f32_f16_sdwa v161, v48 dst_sel:DWORD dst_unused:UNUSED_PAD src0_sel:WORD_1
	v_cvt_f32_f16_e32 v160, v48
	v_cvt_f32_f16_sdwa v165, v49 dst_sel:DWORD dst_unused:UNUSED_PAD src0_sel:WORD_1
	v_cvt_f32_f16_e32 v164, v49
	v_cvt_f32_f16_sdwa v155, v42 dst_sel:DWORD dst_unused:UNUSED_PAD src0_sel:WORD_1
	v_cvt_f32_f16_e32 v154, v42
	v_cvt_f32_f16_sdwa v157, v43 dst_sel:DWORD dst_unused:UNUSED_PAD src0_sel:WORD_1
	v_cvt_f32_f16_e32 v156, v43
	v_cvt_f32_f16_sdwa v153, v44 dst_sel:DWORD dst_unused:UNUSED_PAD src0_sel:WORD_1
	v_cvt_f32_f16_e32 v152, v44
	v_cvt_f32_f16_sdwa v159, v45 dst_sel:DWORD dst_unused:UNUSED_PAD src0_sel:WORD_1
	v_cvt_f32_f16_e32 v158, v45
	v_cvt_f32_f16_sdwa v45, v38 dst_sel:DWORD dst_unused:UNUSED_PAD src0_sel:WORD_1
	v_cvt_f32_f16_e32 v44, v38
	v_cvt_f32_f16_sdwa v47, v39 dst_sel:DWORD dst_unused:UNUSED_PAD src0_sel:WORD_1
	v_cvt_f32_f16_e32 v46, v39
	v_cvt_f32_f16_sdwa v43, v40 dst_sel:DWORD dst_unused:UNUSED_PAD src0_sel:WORD_1
	v_cvt_f32_f16_e32 v42, v40
	v_cvt_f32_f16_sdwa v49, v41 dst_sel:DWORD dst_unused:UNUSED_PAD src0_sel:WORD_1
	v_cvt_f32_f16_e32 v48, v41
	v_cvt_f32_f16_sdwa v39, v34 dst_sel:DWORD dst_unused:UNUSED_PAD src0_sel:WORD_1
	v_cvt_f32_f16_e32 v38, v34
	v_cvt_f32_f16_sdwa v41, v35 dst_sel:DWORD dst_unused:UNUSED_PAD src0_sel:WORD_1
	v_cvt_f32_f16_e32 v40, v35
	v_cvt_f32_f16_sdwa v33, v36 dst_sel:DWORD dst_unused:UNUSED_PAD src0_sel:WORD_1
	v_cvt_f32_f16_e32 v32, v36
	v_cvt_f32_f16_sdwa v35, v37 dst_sel:DWORD dst_unused:UNUSED_PAD src0_sel:WORD_1
	v_cvt_f32_f16_e32 v34, v37
	s_cmpk_gt_i32 s4, 0x3fff
	s_cselect_b64 s[2:3], -1, 0
	s_cmpk_lt_i32 s4, 0x4000
	s_cbranch_scc1 .LBB0_773
	s_add_i32 s86, s4, 0xffffc000
	s_lshl_b64 s[0:1], s[86:87], 13
	v_lshl_add_u64 v[36:37], v[82:83], 0, s[0:1]
	global_load_dwordx4 v[190:193], v[36:37], off nt
	global_load_dwordx4 v[194:197], v[36:37], off offset:16 nt
	global_load_dwordx4 v[198:201], v[36:37], off offset:2048 nt
	global_load_dwordx4 v[204:207], v[36:37], off offset:2064 nt
	s_mov_b64 s[0:1], 0x400000
	v_lshl_add_u64 v[232:233], v[36:37], 0, s[0:1]
	global_load_dwordx4 v[208:211], v[232:233], off nt
	global_load_dwordx4 v[212:215], v[232:233], off offset:16 nt
	global_load_dwordx4 v[216:219], v[232:233], off offset:2048 nt
	global_load_dwordx4 v[220:223], v[232:233], off offset:2064 nt
	s_mov_b64 s[0:1], 0x800000
	v_lshl_add_u64 v[232:233], v[36:37], 0, s[0:1]
	global_load_dwordx4 v[224:227], v[232:233], off nt
	global_load_dwordx4 v[228:231], v[232:233], off offset:16 nt
	global_load_dwordx4 v[238:241], v[232:233], off offset:2048 nt
	global_load_dwordx4 v[242:245], v[232:233], off offset:2064 nt
	s_waitcnt vmcnt(8)
	v_mov_b64_e32 v[174:175], v[190:191]
	v_mov_b64_e32 v[176:177], v[192:193]
	v_mov_b64_e32 v[178:179], v[194:195]
	v_mov_b64_e32 v[180:181], v[196:197]
	v_mov_b64_e32 v[182:183], v[198:199]
	v_mov_b64_e32 v[184:185], v[200:201]
	v_mov_b64_e32 v[186:187], v[204:205]
	v_mov_b64_e32 v[188:189], v[206:207]
	s_mov_b64 s[0:1], 0xc00000
	v_lshl_add_u64 v[232:233], v[36:37], 0, s[0:1]
	global_load_dwordx4 v[190:193], v[232:233], off nt
	global_load_dwordx4 v[194:197], v[232:233], off offset:16 nt
	global_load_dwordx4 v[198:201], v[232:233], off offset:2048 nt
	global_load_dwordx4 v[204:207], v[232:233], off offset:2064 nt
	s_waitcnt vmcnt(8)
	v_pk_add_f32 v[174:175], v[174:175], v[208:209]
	v_pk_add_f32 v[176:177], v[176:177], v[210:211]
	v_pk_add_f32 v[178:179], v[178:179], v[212:213]
	v_pk_add_f32 v[180:181], v[180:181], v[214:215]
	v_pk_add_f32 v[182:183], v[182:183], v[216:217]
	v_pk_add_f32 v[184:185], v[184:185], v[218:219]
	v_pk_add_f32 v[186:187], v[186:187], v[220:221]
	v_pk_add_f32 v[188:189], v[188:189], v[222:223]
	s_mov_b64 s[0:1], 0x1000000
	v_lshl_add_u64 v[232:233], v[36:37], 0, s[0:1]
	global_load_dwordx4 v[208:211], v[232:233], off nt
	global_load_dwordx4 v[212:215], v[232:233], off offset:16 nt
	global_load_dwordx4 v[216:219], v[232:233], off offset:2048 nt
	global_load_dwordx4 v[220:223], v[232:233], off offset:2064 nt
	s_waitcnt vmcnt(8)
	v_pk_add_f32 v[174:175], v[174:175], v[224:225]
	v_pk_add_f32 v[176:177], v[176:177], v[226:227]
	v_pk_add_f32 v[178:179], v[178:179], v[228:229]
	v_pk_add_f32 v[180:181], v[180:181], v[230:231]
	v_pk_add_f32 v[182:183], v[182:183], v[238:239]
	v_pk_add_f32 v[184:185], v[184:185], v[240:241]
	v_pk_add_f32 v[186:187], v[186:187], v[242:243]
	v_pk_add_f32 v[188:189], v[188:189], v[244:245]
	s_mov_b64 s[0:1], 0x1400000
	v_lshl_add_u64 v[232:233], v[36:37], 0, s[0:1]
	global_load_dwordx4 v[224:227], v[232:233], off nt
	global_load_dwordx4 v[228:231], v[232:233], off offset:16 nt
	global_load_dwordx4 v[238:241], v[232:233], off offset:2048 nt
	global_load_dwordx4 v[242:245], v[232:233], off offset:2064 nt
	s_waitcnt vmcnt(8)
	v_pk_add_f32 v[174:175], v[174:175], v[190:191]
	v_pk_add_f32 v[176:177], v[176:177], v[192:193]
	v_pk_add_f32 v[178:179], v[178:179], v[194:195]
	v_pk_add_f32 v[180:181], v[180:181], v[196:197]
	v_pk_add_f32 v[182:183], v[182:183], v[198:199]
	v_pk_add_f32 v[184:185], v[184:185], v[200:201]
	v_pk_add_f32 v[186:187], v[186:187], v[204:205]
	v_pk_add_f32 v[188:189], v[188:189], v[206:207]
	s_mov_b64 s[0:1], 0x1800000
	v_lshl_add_u64 v[232:233], v[36:37], 0, s[0:1]
	global_load_dwordx4 v[190:193], v[232:233], off nt
	global_load_dwordx4 v[194:197], v[232:233], off offset:16 nt
	global_load_dwordx4 v[198:201], v[232:233], off offset:2048 nt
	global_load_dwordx4 v[204:207], v[232:233], off offset:2064 nt
	s_waitcnt vmcnt(8)
	v_pk_add_f32 v[174:175], v[174:175], v[208:209]
	v_pk_add_f32 v[176:177], v[176:177], v[210:211]
	v_pk_add_f32 v[178:179], v[178:179], v[212:213]
	v_pk_add_f32 v[180:181], v[180:181], v[214:215]
	v_pk_add_f32 v[182:183], v[182:183], v[216:217]
	v_pk_add_f32 v[184:185], v[184:185], v[218:219]
	v_pk_add_f32 v[186:187], v[186:187], v[220:221]
	v_pk_add_f32 v[188:189], v[188:189], v[222:223]
	s_mov_b64 s[0:1], 0x1c00000
	v_lshl_add_u64 v[232:233], v[36:37], 0, s[0:1]
	global_load_dwordx4 v[208:211], v[232:233], off nt
	global_load_dwordx4 v[212:215], v[232:233], off offset:16 nt
	global_load_dwordx4 v[216:219], v[232:233], off offset:2048 nt
	global_load_dwordx4 v[220:223], v[232:233], off offset:2064 nt
	s_waitcnt vmcnt(8)
	v_pk_add_f32 v[174:175], v[174:175], v[224:225]
	v_pk_add_f32 v[176:177], v[176:177], v[226:227]
	v_pk_add_f32 v[178:179], v[178:179], v[228:229]
	v_pk_add_f32 v[180:181], v[180:181], v[230:231]
	v_pk_add_f32 v[182:183], v[182:183], v[238:239]
	v_pk_add_f32 v[184:185], v[184:185], v[240:241]
	v_pk_add_f32 v[186:187], v[186:187], v[242:243]
	v_pk_add_f32 v[188:189], v[188:189], v[244:245]
	global_load_dwordx4 v[224:227], v[74:75], off
	global_load_dwordx4 v[228:231], v[74:75], off offset:16
	global_load_dwordx4 v[238:241], v[74:75], off offset:2048
	global_load_dwordx4 v[242:245], v[74:75], off offset:2064
	s_waitcnt vmcnt(8)
	v_pk_add_f32 v[174:175], v[174:175], v[190:191]
	v_pk_add_f32 v[176:177], v[176:177], v[192:193]
	v_pk_add_f32 v[178:179], v[178:179], v[194:195]
	v_pk_add_f32 v[180:181], v[180:181], v[196:197]
	v_pk_add_f32 v[182:183], v[182:183], v[198:199]
	v_pk_add_f32 v[184:185], v[184:185], v[200:201]
	v_pk_add_f32 v[186:187], v[186:187], v[204:205]
	v_pk_add_f32 v[188:189], v[188:189], v[206:207]
	s_mov_b64 s[0:1], 0x1000
	v_lshl_add_u64 v[232:233], v[36:37], 0, s[0:1]
	global_load_dwordx4 v[190:193], v[232:233], off nt
	global_load_dwordx4 v[194:197], v[232:233], off offset:16 nt
	global_load_dwordx4 v[198:201], v[232:233], off offset:2048 nt
	global_load_dwordx4 v[204:207], v[232:233], off offset:2064 nt
	s_waitcnt vmcnt(8)
	v_pk_add_f32 v[174:175], v[174:175], v[208:209]
	v_pk_add_f32 v[176:177], v[176:177], v[210:211]
	v_pk_add_f32 v[178:179], v[178:179], v[212:213]
	v_pk_add_f32 v[180:181], v[180:181], v[214:215]
	v_pk_add_f32 v[182:183], v[182:183], v[216:217]
	v_pk_add_f32 v[184:185], v[184:185], v[218:219]
	v_pk_add_f32 v[186:187], v[186:187], v[220:221]
	v_pk_add_f32 v[188:189], v[188:189], v[222:223]
	s_mov_b64 s[0:1], 0x401000
	v_lshl_add_u64 v[232:233], v[36:37], 0, s[0:1]
	global_load_dwordx4 v[208:211], v[232:233], off nt
	global_load_dwordx4 v[212:215], v[232:233], off offset:16 nt
	global_load_dwordx4 v[216:219], v[232:233], off offset:2048 nt
	global_load_dwordx4 v[220:223], v[232:233], off offset:2064 nt
	s_waitcnt vmcnt(8)
	v_pk_fma_f32 v[166:167], v[174:175], v[224:225], v[166:167]
	v_pk_fma_f32 v[162:163], v[176:177], v[226:227], v[162:163]
	v_pk_fma_f32 v[160:161], v[178:179], v[228:229], v[160:161]
	v_pk_fma_f32 v[164:165], v[180:181], v[230:231], v[164:165]
	v_pk_fma_f32 v[154:155], v[182:183], v[238:239], v[154:155]
	v_pk_fma_f32 v[156:157], v[184:185], v[240:241], v[156:157]
	v_pk_fma_f32 v[152:153], v[186:187], v[242:243], v[152:153]
	v_pk_fma_f32 v[158:159], v[188:189], v[244:245], v[158:159]
	s_mov_b64 s[0:1], 0x801000
	v_lshl_add_u64 v[232:233], v[36:37], 0, s[0:1]
	global_load_dwordx4 v[224:227], v[232:233], off nt
	global_load_dwordx4 v[228:231], v[232:233], off offset:16 nt
	global_load_dwordx4 v[238:241], v[232:233], off offset:2048 nt
	global_load_dwordx4 v[242:245], v[232:233], off offset:2064 nt
	s_waitcnt vmcnt(8)
	v_mov_b64_e32 v[174:175], v[190:191]
	v_mov_b64_e32 v[176:177], v[192:193]
	v_mov_b64_e32 v[178:179], v[194:195]
	v_mov_b64_e32 v[180:181], v[196:197]
	v_mov_b64_e32 v[182:183], v[198:199]
	v_mov_b64_e32 v[184:185], v[200:201]
	v_mov_b64_e32 v[186:187], v[204:205]
	v_mov_b64_e32 v[188:189], v[206:207]
	s_mov_b64 s[0:1], 0xc01000
	v_lshl_add_u64 v[232:233], v[36:37], 0, s[0:1]
	global_load_dwordx4 v[190:193], v[232:233], off nt
	global_load_dwordx4 v[194:197], v[232:233], off offset:16 nt
	global_load_dwordx4 v[198:201], v[232:233], off offset:2048 nt
	global_load_dwordx4 v[204:207], v[232:233], off offset:2064 nt
	s_waitcnt vmcnt(8)
	v_pk_add_f32 v[174:175], v[174:175], v[208:209]
	v_pk_add_f32 v[176:177], v[176:177], v[210:211]
	v_pk_add_f32 v[178:179], v[178:179], v[212:213]
	v_pk_add_f32 v[180:181], v[180:181], v[214:215]
	v_pk_add_f32 v[182:183], v[182:183], v[216:217]
	v_pk_add_f32 v[184:185], v[184:185], v[218:219]
	v_pk_add_f32 v[186:187], v[186:187], v[220:221]
	v_pk_add_f32 v[188:189], v[188:189], v[222:223]
	s_mov_b64 s[0:1], 0x1001000
	v_lshl_add_u64 v[232:233], v[36:37], 0, s[0:1]
	global_load_dwordx4 v[208:211], v[232:233], off nt
	global_load_dwordx4 v[212:215], v[232:233], off offset:16 nt
	global_load_dwordx4 v[216:219], v[232:233], off offset:2048 nt
	global_load_dwordx4 v[220:223], v[232:233], off offset:2064 nt
	s_waitcnt vmcnt(8)
	v_pk_add_f32 v[174:175], v[174:175], v[224:225]
	v_pk_add_f32 v[176:177], v[176:177], v[226:227]
	v_pk_add_f32 v[178:179], v[178:179], v[228:229]
	v_pk_add_f32 v[180:181], v[180:181], v[230:231]
	v_pk_add_f32 v[182:183], v[182:183], v[238:239]
	v_pk_add_f32 v[184:185], v[184:185], v[240:241]
	v_pk_add_f32 v[186:187], v[186:187], v[242:243]
	v_pk_add_f32 v[188:189], v[188:189], v[244:245]
	s_mov_b64 s[0:1], 0x1401000
	v_lshl_add_u64 v[232:233], v[36:37], 0, s[0:1]
	global_load_dwordx4 v[224:227], v[232:233], off nt
	global_load_dwordx4 v[228:231], v[232:233], off offset:16 nt
	global_load_dwordx4 v[238:241], v[232:233], off offset:2048 nt
	global_load_dwordx4 v[242:245], v[232:233], off offset:2064 nt
	s_waitcnt vmcnt(8)
	v_pk_add_f32 v[174:175], v[174:175], v[190:191]
	v_pk_add_f32 v[176:177], v[176:177], v[192:193]
	v_pk_add_f32 v[178:179], v[178:179], v[194:195]
	v_pk_add_f32 v[180:181], v[180:181], v[196:197]
	v_pk_add_f32 v[182:183], v[182:183], v[198:199]
	v_pk_add_f32 v[184:185], v[184:185], v[200:201]
	v_pk_add_f32 v[186:187], v[186:187], v[204:205]
	v_pk_add_f32 v[188:189], v[188:189], v[206:207]
	s_mov_b64 s[0:1], 0x1801000
	v_lshl_add_u64 v[232:233], v[36:37], 0, s[0:1]
	global_load_dwordx4 v[190:193], v[232:233], off nt
	global_load_dwordx4 v[194:197], v[232:233], off offset:16 nt
	global_load_dwordx4 v[198:201], v[232:233], off offset:2048 nt
	global_load_dwordx4 v[204:207], v[232:233], off offset:2064 nt
	s_waitcnt vmcnt(8)
	v_pk_add_f32 v[174:175], v[174:175], v[208:209]
	v_pk_add_f32 v[176:177], v[176:177], v[210:211]
	v_pk_add_f32 v[178:179], v[178:179], v[212:213]
	v_pk_add_f32 v[180:181], v[180:181], v[214:215]
	v_pk_add_f32 v[182:183], v[182:183], v[216:217]
	v_pk_add_f32 v[184:185], v[184:185], v[218:219]
	v_pk_add_f32 v[186:187], v[186:187], v[220:221]
	v_pk_add_f32 v[188:189], v[188:189], v[222:223]
	s_mov_b64 s[0:1], 0x1c01000
	v_lshl_add_u64 v[232:233], v[36:37], 0, s[0:1]
	global_load_dwordx4 v[208:211], v[232:233], off nt
	global_load_dwordx4 v[212:215], v[232:233], off offset:16 nt
	global_load_dwordx4 v[216:219], v[232:233], off offset:2048 nt
	global_load_dwordx4 v[220:223], v[232:233], off offset:2064 nt
	s_waitcnt vmcnt(8)
	v_pk_add_f32 v[174:175], v[174:175], v[224:225]
	v_pk_add_f32 v[176:177], v[176:177], v[226:227]
	v_pk_add_f32 v[178:179], v[178:179], v[228:229]
	v_pk_add_f32 v[180:181], v[180:181], v[230:231]
	v_pk_add_f32 v[182:183], v[182:183], v[238:239]
	v_pk_add_f32 v[184:185], v[184:185], v[240:241]
	v_pk_add_f32 v[186:187], v[186:187], v[242:243]
	v_pk_add_f32 v[188:189], v[188:189], v[244:245]
	global_load_dwordx4 v[224:227], v[76:77], off
	global_load_dwordx4 v[228:231], v[76:77], off offset:16
	global_load_dwordx4 v[238:241], v[78:79], off
	global_load_dwordx4 v[242:245], v[78:79], off offset:16
	s_waitcnt vmcnt(8)
	v_pk_add_f32 v[174:175], v[174:175], v[190:191]
	v_pk_add_f32 v[176:177], v[176:177], v[192:193]
	v_pk_add_f32 v[178:179], v[178:179], v[194:195]
	v_pk_add_f32 v[180:181], v[180:181], v[196:197]
	v_pk_add_f32 v[182:183], v[182:183], v[198:199]
	v_pk_add_f32 v[184:185], v[184:185], v[200:201]
	v_pk_add_f32 v[186:187], v[186:187], v[204:205]
	v_pk_add_f32 v[188:189], v[188:189], v[206:207]
	s_waitcnt vmcnt(4)
	v_pk_add_f32 v[174:175], v[174:175], v[208:209]
	v_pk_add_f32 v[176:177], v[176:177], v[210:211]
	v_pk_add_f32 v[178:179], v[178:179], v[212:213]
	v_pk_add_f32 v[180:181], v[180:181], v[214:215]
	v_pk_add_f32 v[182:183], v[182:183], v[216:217]
	v_pk_add_f32 v[184:185], v[184:185], v[218:219]
	v_pk_add_f32 v[186:187], v[186:187], v[220:221]
	v_pk_add_f32 v[188:189], v[188:189], v[222:223]
	s_waitcnt vmcnt(0)
	v_pk_fma_f32 v[44:45], v[174:175], v[224:225], v[44:45]
	v_pk_fma_f32 v[46:47], v[176:177], v[226:227], v[46:47]
	v_pk_fma_f32 v[42:43], v[178:179], v[228:229], v[42:43]
	v_pk_fma_f32 v[48:49], v[180:181], v[230:231], v[48:49]
	v_pk_fma_f32 v[38:39], v[182:183], v[238:239], v[38:39]
	v_pk_fma_f32 v[40:41], v[184:185], v[240:241], v[40:41]
	v_pk_fma_f32 v[32:33], v[186:187], v[242:243], v[32:33]
	v_pk_fma_f32 v[34:35], v[188:189], v[244:245], v[34:35]

.LBB0_777:
	s_add_i32 s0, s75, s4
	s_cmpk_lt_i32 s0, 0x4200
	s_cselect_b32 s0, s0, s4
	s_ashr_i32 s1, s0, 31
	s_lshl_b64 s[0:1], s[0:1], 12
	v_lshl_add_u64 v[32:33], v[80:81], 0, s[0:1]
	global_load_dwordx4 v[46:49], v[32:33], off
	global_load_dwordx4 v[42:45], v[32:33], off offset:1024
	global_load_dwordx4 v[38:41], v[32:33], off offset:2048
	global_load_dwordx4 v[34:37], v[32:33], off offset:3072
	s_waitcnt vmcnt(4)
	s_andn2_b64 vcc, exec, s[8:9]
	s_cbranch_vccnz .LBB0_767
	v_cvt_f32_f16_sdwa v167, v62 dst_sel:DWORD dst_unused:UNUSED_PAD src0_sel:WORD_1
	v_cvt_f32_f16_e32 v166, v62
	v_cvt_f32_f16_sdwa v163, v63 dst_sel:DWORD dst_unused:UNUSED_PAD src0_sel:WORD_1
	v_cvt_f32_f16_e32 v162, v63
	v_cvt_f32_f16_sdwa v161, v64 dst_sel:DWORD dst_unused:UNUSED_PAD src0_sel:WORD_1
	v_cvt_f32_f16_e32 v160, v64
	v_cvt_f32_f16_sdwa v165, v65 dst_sel:DWORD dst_unused:UNUSED_PAD src0_sel:WORD_1
	v_cvt_f32_f16_e32 v164, v65
	v_cvt_f32_f16_sdwa v155, v58 dst_sel:DWORD dst_unused:UNUSED_PAD src0_sel:WORD_1
	v_cvt_f32_f16_e32 v154, v58
	v_cvt_f32_f16_sdwa v157, v59 dst_sel:DWORD dst_unused:UNUSED_PAD src0_sel:WORD_1
	v_cvt_f32_f16_e32 v156, v59
	v_cvt_f32_f16_sdwa v153, v60 dst_sel:DWORD dst_unused:UNUSED_PAD src0_sel:WORD_1
	v_cvt_f32_f16_e32 v152, v60
	v_cvt_f32_f16_sdwa v159, v61 dst_sel:DWORD dst_unused:UNUSED_PAD src0_sel:WORD_1
	v_cvt_f32_f16_e32 v158, v61
	v_cvt_f32_f16_sdwa v61, v54 dst_sel:DWORD dst_unused:UNUSED_PAD src0_sel:WORD_1
	v_cvt_f32_f16_e32 v60, v54
	v_cvt_f32_f16_sdwa v63, v55 dst_sel:DWORD dst_unused:UNUSED_PAD src0_sel:WORD_1
	v_cvt_f32_f16_e32 v62, v55
	v_cvt_f32_f16_sdwa v59, v56 dst_sel:DWORD dst_unused:UNUSED_PAD src0_sel:WORD_1
	v_cvt_f32_f16_e32 v58, v56
	v_cvt_f32_f16_sdwa v65, v57 dst_sel:DWORD dst_unused:UNUSED_PAD src0_sel:WORD_1
	v_cvt_f32_f16_e32 v64, v57
	v_cvt_f32_f16_sdwa v55, v50 dst_sel:DWORD dst_unused:UNUSED_PAD src0_sel:WORD_1
	v_cvt_f32_f16_e32 v54, v50
	v_cvt_f32_f16_sdwa v57, v51 dst_sel:DWORD dst_unused:UNUSED_PAD src0_sel:WORD_1
	v_cvt_f32_f16_e32 v56, v51
	v_cvt_f32_f16_sdwa v33, v52 dst_sel:DWORD dst_unused:UNUSED_PAD src0_sel:WORD_1
	v_cvt_f32_f16_e32 v32, v52
	v_cvt_f32_f16_sdwa v51, v53 dst_sel:DWORD dst_unused:UNUSED_PAD src0_sel:WORD_1
	v_cvt_f32_f16_e32 v50, v53
	s_cmpk_gt_i32 s14, 0x3fff
	s_cselect_b64 s[2:3], -1, 0
	s_cmpk_lt_i32 s14, 0x4000
	s_cbranch_scc1 .LBB0_780
	s_add_i32 s86, s14, 0xffffc000
	s_lshl_b64 s[0:1], s[86:87], 13
	v_lshl_add_u64 v[52:53], v[82:83], 0, s[0:1]
	global_load_dwordx4 v[190:193], v[52:53], off nt
	global_load_dwordx4 v[194:197], v[52:53], off offset:16 nt
	global_load_dwordx4 v[198:201], v[52:53], off offset:2048 nt
	global_load_dwordx4 v[204:207], v[52:53], off offset:2064 nt
	s_mov_b64 s[0:1], 0x400000
	v_lshl_add_u64 v[232:233], v[52:53], 0, s[0:1]
	global_load_dwordx4 v[208:211], v[232:233], off nt
	global_load_dwordx4 v[212:215], v[232:233], off offset:16 nt
	global_load_dwordx4 v[216:219], v[232:233], off offset:2048 nt
	global_load_dwordx4 v[220:223], v[232:233], off offset:2064 nt
	s_mov_b64 s[0:1], 0x800000
	v_lshl_add_u64 v[232:233], v[52:53], 0, s[0:1]
	global_load_dwordx4 v[224:227], v[232:233], off nt
	global_load_dwordx4 v[228:231], v[232:233], off offset:16 nt
	global_load_dwordx4 v[238:241], v[232:233], off offset:2048 nt
	global_load_dwordx4 v[242:245], v[232:233], off offset:2064 nt
	s_waitcnt vmcnt(8)
	v_mov_b64_e32 v[174:175], v[190:191]
	v_mov_b64_e32 v[176:177], v[192:193]
	v_mov_b64_e32 v[178:179], v[194:195]
	v_mov_b64_e32 v[180:181], v[196:197]
	v_mov_b64_e32 v[182:183], v[198:199]
	v_mov_b64_e32 v[184:185], v[200:201]
	v_mov_b64_e32 v[186:187], v[204:205]
	v_mov_b64_e32 v[188:189], v[206:207]
	s_mov_b64 s[0:1], 0xc00000
	v_lshl_add_u64 v[232:233], v[52:53], 0, s[0:1]
	global_load_dwordx4 v[190:193], v[232:233], off nt
	global_load_dwordx4 v[194:197], v[232:233], off offset:16 nt
	global_load_dwordx4 v[198:201], v[232:233], off offset:2048 nt
	global_load_dwordx4 v[204:207], v[232:233], off offset:2064 nt
	s_waitcnt vmcnt(8)
	v_pk_add_f32 v[174:175], v[174:175], v[208:209]
	v_pk_add_f32 v[176:177], v[176:177], v[210:211]
	v_pk_add_f32 v[178:179], v[178:179], v[212:213]
	v_pk_add_f32 v[180:181], v[180:181], v[214:215]
	v_pk_add_f32 v[182:183], v[182:183], v[216:217]
	v_pk_add_f32 v[184:185], v[184:185], v[218:219]
	v_pk_add_f32 v[186:187], v[186:187], v[220:221]
	v_pk_add_f32 v[188:189], v[188:189], v[222:223]
	s_mov_b64 s[0:1], 0x1000000
	v_lshl_add_u64 v[232:233], v[52:53], 0, s[0:1]
	global_load_dwordx4 v[208:211], v[232:233], off nt
	global_load_dwordx4 v[212:215], v[232:233], off offset:16 nt
	global_load_dwordx4 v[216:219], v[232:233], off offset:2048 nt
	global_load_dwordx4 v[220:223], v[232:233], off offset:2064 nt
	s_waitcnt vmcnt(8)
	v_pk_add_f32 v[174:175], v[174:175], v[224:225]
	v_pk_add_f32 v[176:177], v[176:177], v[226:227]
	v_pk_add_f32 v[178:179], v[178:179], v[228:229]
	v_pk_add_f32 v[180:181], v[180:181], v[230:231]
	v_pk_add_f32 v[182:183], v[182:183], v[238:239]
	v_pk_add_f32 v[184:185], v[184:185], v[240:241]
	v_pk_add_f32 v[186:187], v[186:187], v[242:243]
	v_pk_add_f32 v[188:189], v[188:189], v[244:245]
	s_mov_b64 s[0:1], 0x1400000
	v_lshl_add_u64 v[232:233], v[52:53], 0, s[0:1]
	global_load_dwordx4 v[224:227], v[232:233], off nt
	global_load_dwordx4 v[228:231], v[232:233], off offset:16 nt
	global_load_dwordx4 v[238:241], v[232:233], off offset:2048 nt
	global_load_dwordx4 v[242:245], v[232:233], off offset:2064 nt
	s_waitcnt vmcnt(8)
	v_pk_add_f32 v[174:175], v[174:175], v[190:191]
	v_pk_add_f32 v[176:177], v[176:177], v[192:193]
	v_pk_add_f32 v[178:179], v[178:179], v[194:195]
	v_pk_add_f32 v[180:181], v[180:181], v[196:197]
	v_pk_add_f32 v[182:183], v[182:183], v[198:199]
	v_pk_add_f32 v[184:185], v[184:185], v[200:201]
	v_pk_add_f32 v[186:187], v[186:187], v[204:205]
	v_pk_add_f32 v[188:189], v[188:189], v[206:207]
	s_mov_b64 s[0:1], 0x1800000
	v_lshl_add_u64 v[232:233], v[52:53], 0, s[0:1]
	global_load_dwordx4 v[190:193], v[232:233], off nt
	global_load_dwordx4 v[194:197], v[232:233], off offset:16 nt
	global_load_dwordx4 v[198:201], v[232:233], off offset:2048 nt
	global_load_dwordx4 v[204:207], v[232:233], off offset:2064 nt
	s_waitcnt vmcnt(8)
	v_pk_add_f32 v[174:175], v[174:175], v[208:209]
	v_pk_add_f32 v[176:177], v[176:177], v[210:211]
	v_pk_add_f32 v[178:179], v[178:179], v[212:213]
	v_pk_add_f32 v[180:181], v[180:181], v[214:215]
	v_pk_add_f32 v[182:183], v[182:183], v[216:217]
	v_pk_add_f32 v[184:185], v[184:185], v[218:219]
	v_pk_add_f32 v[186:187], v[186:187], v[220:221]
	v_pk_add_f32 v[188:189], v[188:189], v[222:223]
	s_mov_b64 s[0:1], 0x1c00000
	v_lshl_add_u64 v[232:233], v[52:53], 0, s[0:1]
	global_load_dwordx4 v[208:211], v[232:233], off nt
	global_load_dwordx4 v[212:215], v[232:233], off offset:16 nt
	global_load_dwordx4 v[216:219], v[232:233], off offset:2048 nt
	global_load_dwordx4 v[220:223], v[232:233], off offset:2064 nt
	s_waitcnt vmcnt(8)
	v_pk_add_f32 v[174:175], v[174:175], v[224:225]
	v_pk_add_f32 v[176:177], v[176:177], v[226:227]
	v_pk_add_f32 v[178:179], v[178:179], v[228:229]
	v_pk_add_f32 v[180:181], v[180:181], v[230:231]
	v_pk_add_f32 v[182:183], v[182:183], v[238:239]
	v_pk_add_f32 v[184:185], v[184:185], v[240:241]
	v_pk_add_f32 v[186:187], v[186:187], v[242:243]
	v_pk_add_f32 v[188:189], v[188:189], v[244:245]
	global_load_dwordx4 v[224:227], v[74:75], off
	global_load_dwordx4 v[228:231], v[74:75], off offset:16
	global_load_dwordx4 v[238:241], v[74:75], off offset:2048
	global_load_dwordx4 v[242:245], v[74:75], off offset:2064
	s_waitcnt vmcnt(8)
	v_pk_add_f32 v[174:175], v[174:175], v[190:191]
	v_pk_add_f32 v[176:177], v[176:177], v[192:193]
	v_pk_add_f32 v[178:179], v[178:179], v[194:195]
	v_pk_add_f32 v[180:181], v[180:181], v[196:197]
	v_pk_add_f32 v[182:183], v[182:183], v[198:199]
	v_pk_add_f32 v[184:185], v[184:185], v[200:201]
	v_pk_add_f32 v[186:187], v[186:187], v[204:205]
	v_pk_add_f32 v[188:189], v[188:189], v[206:207]
	s_mov_b64 s[0:1], 0x1000
	v_lshl_add_u64 v[232:233], v[52:53], 0, s[0:1]
	global_load_dwordx4 v[190:193], v[232:233], off nt
	global_load_dwordx4 v[194:197], v[232:233], off offset:16 nt
	global_load_dwordx4 v[198:201], v[232:233], off offset:2048 nt
	global_load_dwordx4 v[204:207], v[232:233], off offset:2064 nt
	s_waitcnt vmcnt(8)
	v_pk_add_f32 v[174:175], v[174:175], v[208:209]
	v_pk_add_f32 v[176:177], v[176:177], v[210:211]
	v_pk_add_f32 v[178:179], v[178:179], v[212:213]
	v_pk_add_f32 v[180:181], v[180:181], v[214:215]
	v_pk_add_f32 v[182:183], v[182:183], v[216:217]
	v_pk_add_f32 v[184:185], v[184:185], v[218:219]
	v_pk_add_f32 v[186:187], v[186:187], v[220:221]
	v_pk_add_f32 v[188:189], v[188:189], v[222:223]
	s_mov_b64 s[0:1], 0x401000
	v_lshl_add_u64 v[232:233], v[52:53], 0, s[0:1]
	global_load_dwordx4 v[208:211], v[232:233], off nt
	global_load_dwordx4 v[212:215], v[232:233], off offset:16 nt
	global_load_dwordx4 v[216:219], v[232:233], off offset:2048 nt
	global_load_dwordx4 v[220:223], v[232:233], off offset:2064 nt
	s_waitcnt vmcnt(8)
	v_pk_fma_f32 v[166:167], v[174:175], v[224:225], v[166:167]
	v_pk_fma_f32 v[162:163], v[176:177], v[226:227], v[162:163]
	v_pk_fma_f32 v[160:161], v[178:179], v[228:229], v[160:161]
	v_pk_fma_f32 v[164:165], v[180:181], v[230:231], v[164:165]
	v_pk_fma_f32 v[154:155], v[182:183], v[238:239], v[154:155]
	v_pk_fma_f32 v[156:157], v[184:185], v[240:241], v[156:157]
	v_pk_fma_f32 v[152:153], v[186:187], v[242:243], v[152:153]
	v_pk_fma_f32 v[158:159], v[188:189], v[244:245], v[158:159]
	s_mov_b64 s[0:1], 0x801000
	v_lshl_add_u64 v[232:233], v[52:53], 0, s[0:1]
	global_load_dwordx4 v[224:227], v[232:233], off nt
	global_load_dwordx4 v[228:231], v[232:233], off offset:16 nt
	global_load_dwordx4 v[238:241], v[232:233], off offset:2048 nt
	global_load_dwordx4 v[242:245], v[232:233], off offset:2064 nt
	s_waitcnt vmcnt(8)
	v_mov_b64_e32 v[174:175], v[190:191]
	v_mov_b64_e32 v[176:177], v[192:193]
	v_mov_b64_e32 v[178:179], v[194:195]
	v_mov_b64_e32 v[180:181], v[196:197]
	v_mov_b64_e32 v[182:183], v[198:199]
	v_mov_b64_e32 v[184:185], v[200:201]
	v_mov_b64_e32 v[186:187], v[204:205]
	v_mov_b64_e32 v[188:189], v[206:207]
	s_mov_b64 s[0:1], 0xc01000
	v_lshl_add_u64 v[232:233], v[52:53], 0, s[0:1]
	global_load_dwordx4 v[190:193], v[232:233], off nt
	global_load_dwordx4 v[194:197], v[232:233], off offset:16 nt
	global_load_dwordx4 v[198:201], v[232:233], off offset:2048 nt
	global_load_dwordx4 v[204:207], v[232:233], off offset:2064 nt
	s_waitcnt vmcnt(8)
	v_pk_add_f32 v[174:175], v[174:175], v[208:209]
	v_pk_add_f32 v[176:177], v[176:177], v[210:211]
	v_pk_add_f32 v[178:179], v[178:179], v[212:213]
	v_pk_add_f32 v[180:181], v[180:181], v[214:215]
	v_pk_add_f32 v[182:183], v[182:183], v[216:217]
	v_pk_add_f32 v[184:185], v[184:185], v[218:219]
	v_pk_add_f32 v[186:187], v[186:187], v[220:221]
	v_pk_add_f32 v[188:189], v[188:189], v[222:223]
	s_mov_b64 s[0:1], 0x1001000
	v_lshl_add_u64 v[232:233], v[52:53], 0, s[0:1]
	global_load_dwordx4 v[208:211], v[232:233], off nt
	global_load_dwordx4 v[212:215], v[232:233], off offset:16 nt
	global_load_dwordx4 v[216:219], v[232:233], off offset:2048 nt
	global_load_dwordx4 v[220:223], v[232:233], off offset:2064 nt
	s_waitcnt vmcnt(8)
	v_pk_add_f32 v[174:175], v[174:175], v[224:225]
	v_pk_add_f32 v[176:177], v[176:177], v[226:227]
	v_pk_add_f32 v[178:179], v[178:179], v[228:229]
	v_pk_add_f32 v[180:181], v[180:181], v[230:231]
	v_pk_add_f32 v[182:183], v[182:183], v[238:239]
	v_pk_add_f32 v[184:185], v[184:185], v[240:241]
	v_pk_add_f32 v[186:187], v[186:187], v[242:243]
	v_pk_add_f32 v[188:189], v[188:189], v[244:245]
	s_mov_b64 s[0:1], 0x1401000
	v_lshl_add_u64 v[232:233], v[52:53], 0, s[0:1]
	global_load_dwordx4 v[224:227], v[232:233], off nt
	global_load_dwordx4 v[228:231], v[232:233], off offset:16 nt
	global_load_dwordx4 v[238:241], v[232:233], off offset:2048 nt
	global_load_dwordx4 v[242:245], v[232:233], off offset:2064 nt
	s_waitcnt vmcnt(8)
	v_pk_add_f32 v[174:175], v[174:175], v[190:191]
	v_pk_add_f32 v[176:177], v[176:177], v[192:193]
	v_pk_add_f32 v[178:179], v[178:179], v[194:195]
	v_pk_add_f32 v[180:181], v[180:181], v[196:197]
	v_pk_add_f32 v[182:183], v[182:183], v[198:199]
	v_pk_add_f32 v[184:185], v[184:185], v[200:201]
	v_pk_add_f32 v[186:187], v[186:187], v[204:205]
	v_pk_add_f32 v[188:189], v[188:189], v[206:207]
	s_mov_b64 s[0:1], 0x1801000
	v_lshl_add_u64 v[232:233], v[52:53], 0, s[0:1]
	global_load_dwordx4 v[190:193], v[232:233], off nt
	global_load_dwordx4 v[194:197], v[232:233], off offset:16 nt
	global_load_dwordx4 v[198:201], v[232:233], off offset:2048 nt
	global_load_dwordx4 v[204:207], v[232:233], off offset:2064 nt
	s_waitcnt vmcnt(8)
	v_pk_add_f32 v[174:175], v[174:175], v[208:209]
	v_pk_add_f32 v[176:177], v[176:177], v[210:211]
	v_pk_add_f32 v[178:179], v[178:179], v[212:213]
	v_pk_add_f32 v[180:181], v[180:181], v[214:215]
	v_pk_add_f32 v[182:183], v[182:183], v[216:217]
	v_pk_add_f32 v[184:185], v[184:185], v[218:219]
	v_pk_add_f32 v[186:187], v[186:187], v[220:221]
	v_pk_add_f32 v[188:189], v[188:189], v[222:223]
	s_mov_b64 s[0:1], 0x1c01000
	v_lshl_add_u64 v[232:233], v[52:53], 0, s[0:1]
	global_load_dwordx4 v[208:211], v[232:233], off nt
	global_load_dwordx4 v[212:215], v[232:233], off offset:16 nt
	global_load_dwordx4 v[216:219], v[232:233], off offset:2048 nt
	global_load_dwordx4 v[220:223], v[232:233], off offset:2064 nt
	s_waitcnt vmcnt(8)
	v_pk_add_f32 v[174:175], v[174:175], v[224:225]
	v_pk_add_f32 v[176:177], v[176:177], v[226:227]
	v_pk_add_f32 v[178:179], v[178:179], v[228:229]
	v_pk_add_f32 v[180:181], v[180:181], v[230:231]
	v_pk_add_f32 v[182:183], v[182:183], v[238:239]
	v_pk_add_f32 v[184:185], v[184:185], v[240:241]
	v_pk_add_f32 v[186:187], v[186:187], v[242:243]
	v_pk_add_f32 v[188:189], v[188:189], v[244:245]
	global_load_dwordx4 v[224:227], v[76:77], off
	global_load_dwordx4 v[228:231], v[76:77], off offset:16
	global_load_dwordx4 v[238:241], v[78:79], off
	global_load_dwordx4 v[242:245], v[78:79], off offset:16
	s_waitcnt vmcnt(8)
	v_pk_add_f32 v[174:175], v[174:175], v[190:191]
	v_pk_add_f32 v[176:177], v[176:177], v[192:193]
	v_pk_add_f32 v[178:179], v[178:179], v[194:195]
	v_pk_add_f32 v[180:181], v[180:181], v[196:197]
	v_pk_add_f32 v[182:183], v[182:183], v[198:199]
	v_pk_add_f32 v[184:185], v[184:185], v[200:201]
	v_pk_add_f32 v[186:187], v[186:187], v[204:205]
	v_pk_add_f32 v[188:189], v[188:189], v[206:207]
	s_waitcnt vmcnt(4)
	v_pk_add_f32 v[174:175], v[174:175], v[208:209]
	v_pk_add_f32 v[176:177], v[176:177], v[210:211]
	v_pk_add_f32 v[178:179], v[178:179], v[212:213]
	v_pk_add_f32 v[180:181], v[180:181], v[214:215]
	v_pk_add_f32 v[182:183], v[182:183], v[216:217]
	v_pk_add_f32 v[184:185], v[184:185], v[218:219]
	v_pk_add_f32 v[186:187], v[186:187], v[220:221]
	v_pk_add_f32 v[188:189], v[188:189], v[222:223]
	s_waitcnt vmcnt(0)
	v_pk_fma_f32 v[60:61], v[174:175], v[224:225], v[60:61]
	v_pk_fma_f32 v[62:63], v[176:177], v[226:227], v[62:63]
	v_pk_fma_f32 v[58:59], v[178:179], v[228:229], v[58:59]
	v_pk_fma_f32 v[64:65], v[180:181], v[230:231], v[64:65]
	v_pk_fma_f32 v[54:55], v[182:183], v[238:239], v[54:55]
	v_pk_fma_f32 v[56:57], v[184:185], v[240:241], v[56:57]
	v_pk_fma_f32 v[32:33], v[186:187], v[242:243], v[32:33]
	v_pk_fma_f32 v[50:51], v[188:189], v[244:245], v[50:51]

.LBB0_1049:
	s_add_i32 s16, s8, s94
	s_cmpk_lt_i32 s16, 0x4200
	s_cselect_b64 s[14:15], -1, 0
	s_and_b64 s[0:1], s[14:15], exec
	s_cselect_b32 s10, s16, s8
	s_ashr_i32 s11, s10, 31
	s_lshl_b64 s[0:1], s[10:11], 12
	v_lshl_add_u64 v[32:33], v[80:81], 0, s[0:1]
	s_waitcnt vmcnt(0)
	global_load_dwordx4 v[62:65], v[32:33], off
	global_load_dwordx4 v[58:61], v[32:33], off offset:1024
	global_load_dwordx4 v[54:57], v[32:33], off offset:2048
	global_load_dwordx4 v[50:53], v[32:33], off offset:3072
	v_cvt_f32_f16_sdwa v167, v46 dst_sel:DWORD dst_unused:UNUSED_PAD src0_sel:WORD_1
	v_cvt_f32_f16_e32 v166, v46
	v_cvt_f32_f16_sdwa v163, v47 dst_sel:DWORD dst_unused:UNUSED_PAD src0_sel:WORD_1
	v_cvt_f32_f16_e32 v162, v47
	v_cvt_f32_f16_sdwa v161, v48 dst_sel:DWORD dst_unused:UNUSED_PAD src0_sel:WORD_1
	v_cvt_f32_f16_e32 v160, v48
	v_cvt_f32_f16_sdwa v165, v49 dst_sel:DWORD dst_unused:UNUSED_PAD src0_sel:WORD_1
	v_cvt_f32_f16_e32 v164, v49
	v_cvt_f32_f16_sdwa v155, v42 dst_sel:DWORD dst_unused:UNUSED_PAD src0_sel:WORD_1
	v_cvt_f32_f16_e32 v154, v42
	v_cvt_f32_f16_sdwa v157, v43 dst_sel:DWORD dst_unused:UNUSED_PAD src0_sel:WORD_1
	v_cvt_f32_f16_e32 v156, v43
	v_cvt_f32_f16_sdwa v153, v44 dst_sel:DWORD dst_unused:UNUSED_PAD src0_sel:WORD_1
	v_cvt_f32_f16_e32 v152, v44
	v_cvt_f32_f16_sdwa v159, v45 dst_sel:DWORD dst_unused:UNUSED_PAD src0_sel:WORD_1
	v_cvt_f32_f16_e32 v158, v45
	v_cvt_f32_f16_sdwa v45, v38 dst_sel:DWORD dst_unused:UNUSED_PAD src0_sel:WORD_1
	v_cvt_f32_f16_e32 v44, v38
	v_cvt_f32_f16_sdwa v47, v39 dst_sel:DWORD dst_unused:UNUSED_PAD src0_sel:WORD_1
	v_cvt_f32_f16_e32 v46, v39
	v_cvt_f32_f16_sdwa v43, v40 dst_sel:DWORD dst_unused:UNUSED_PAD src0_sel:WORD_1
	v_cvt_f32_f16_e32 v42, v40
	v_cvt_f32_f16_sdwa v49, v41 dst_sel:DWORD dst_unused:UNUSED_PAD src0_sel:WORD_1
	v_cvt_f32_f16_e32 v48, v41
	v_cvt_f32_f16_sdwa v39, v34 dst_sel:DWORD dst_unused:UNUSED_PAD src0_sel:WORD_1
	v_cvt_f32_f16_e32 v38, v34
	v_cvt_f32_f16_sdwa v41, v35 dst_sel:DWORD dst_unused:UNUSED_PAD src0_sel:WORD_1
	v_cvt_f32_f16_e32 v40, v35
	v_cvt_f32_f16_sdwa v33, v36 dst_sel:DWORD dst_unused:UNUSED_PAD src0_sel:WORD_1
	v_cvt_f32_f16_e32 v32, v36
	v_cvt_f32_f16_sdwa v35, v37 dst_sel:DWORD dst_unused:UNUSED_PAD src0_sel:WORD_1
	v_cvt_f32_f16_e32 v34, v37
	s_cmpk_gt_i32 s8, 0x3fff
	s_cselect_b64 s[2:3], -1, 0
	s_cmpk_lt_i32 s8, 0x4000
	s_cbranch_scc1 .LBB0_1051
	s_add_i32 s86, s8, 0xffffc000
	s_lshl_b64 s[0:1], s[86:87], 13
	v_lshl_add_u64 v[36:37], v[82:83], 0, s[0:1]
	global_load_dwordx4 v[190:193], v[36:37], off nt
	global_load_dwordx4 v[194:197], v[36:37], off offset:16 nt
	global_load_dwordx4 v[198:201], v[36:37], off offset:2048 nt
	global_load_dwordx4 v[204:207], v[36:37], off offset:2064 nt
	s_mov_b64 s[0:1], 0x400000
	v_lshl_add_u64 v[232:233], v[36:37], 0, s[0:1]
	global_load_dwordx4 v[208:211], v[232:233], off nt
	global_load_dwordx4 v[212:215], v[232:233], off offset:16 nt
	global_load_dwordx4 v[216:219], v[232:233], off offset:2048 nt
	global_load_dwordx4 v[220:223], v[232:233], off offset:2064 nt
	s_mov_b64 s[0:1], 0x800000
	v_lshl_add_u64 v[232:233], v[36:37], 0, s[0:1]
	global_load_dwordx4 v[224:227], v[232:233], off nt
	global_load_dwordx4 v[228:231], v[232:233], off offset:16 nt
	global_load_dwordx4 v[238:241], v[232:233], off offset:2048 nt
	global_load_dwordx4 v[242:245], v[232:233], off offset:2064 nt
	s_waitcnt vmcnt(8)
	v_mov_b64_e32 v[174:175], v[190:191]
	v_mov_b64_e32 v[176:177], v[192:193]
	v_mov_b64_e32 v[178:179], v[194:195]
	v_mov_b64_e32 v[180:181], v[196:197]
	v_mov_b64_e32 v[182:183], v[198:199]
	v_mov_b64_e32 v[184:185], v[200:201]
	v_mov_b64_e32 v[186:187], v[204:205]
	v_mov_b64_e32 v[188:189], v[206:207]
	s_mov_b64 s[0:1], 0xc00000
	v_lshl_add_u64 v[232:233], v[36:37], 0, s[0:1]
	global_load_dwordx4 v[190:193], v[232:233], off nt
	global_load_dwordx4 v[194:197], v[232:233], off offset:16 nt
	global_load_dwordx4 v[198:201], v[232:233], off offset:2048 nt
	global_load_dwordx4 v[204:207], v[232:233], off offset:2064 nt
	s_waitcnt vmcnt(8)
	v_pk_add_f32 v[174:175], v[174:175], v[208:209]
	v_pk_add_f32 v[176:177], v[176:177], v[210:211]
	v_pk_add_f32 v[178:179], v[178:179], v[212:213]
	v_pk_add_f32 v[180:181], v[180:181], v[214:215]
	v_pk_add_f32 v[182:183], v[182:183], v[216:217]
	v_pk_add_f32 v[184:185], v[184:185], v[218:219]
	v_pk_add_f32 v[186:187], v[186:187], v[220:221]
	v_pk_add_f32 v[188:189], v[188:189], v[222:223]
	s_mov_b64 s[0:1], 0x1000000
	v_lshl_add_u64 v[232:233], v[36:37], 0, s[0:1]
	global_load_dwordx4 v[208:211], v[232:233], off nt
	global_load_dwordx4 v[212:215], v[232:233], off offset:16 nt
	global_load_dwordx4 v[216:219], v[232:233], off offset:2048 nt
	global_load_dwordx4 v[220:223], v[232:233], off offset:2064 nt
	s_waitcnt vmcnt(8)
	v_pk_add_f32 v[174:175], v[174:175], v[224:225]
	v_pk_add_f32 v[176:177], v[176:177], v[226:227]
	v_pk_add_f32 v[178:179], v[178:179], v[228:229]
	v_pk_add_f32 v[180:181], v[180:181], v[230:231]
	v_pk_add_f32 v[182:183], v[182:183], v[238:239]
	v_pk_add_f32 v[184:185], v[184:185], v[240:241]
	v_pk_add_f32 v[186:187], v[186:187], v[242:243]
	v_pk_add_f32 v[188:189], v[188:189], v[244:245]
	s_mov_b64 s[0:1], 0x1400000
	v_lshl_add_u64 v[232:233], v[36:37], 0, s[0:1]
	global_load_dwordx4 v[224:227], v[232:233], off nt
	global_load_dwordx4 v[228:231], v[232:233], off offset:16 nt
	global_load_dwordx4 v[238:241], v[232:233], off offset:2048 nt
	global_load_dwordx4 v[242:245], v[232:233], off offset:2064 nt
	s_waitcnt vmcnt(8)
	v_pk_add_f32 v[174:175], v[174:175], v[190:191]
	v_pk_add_f32 v[176:177], v[176:177], v[192:193]
	v_pk_add_f32 v[178:179], v[178:179], v[194:195]
	v_pk_add_f32 v[180:181], v[180:181], v[196:197]
	v_pk_add_f32 v[182:183], v[182:183], v[198:199]
	v_pk_add_f32 v[184:185], v[184:185], v[200:201]
	v_pk_add_f32 v[186:187], v[186:187], v[204:205]
	v_pk_add_f32 v[188:189], v[188:189], v[206:207]
	s_mov_b64 s[0:1], 0x1800000
	v_lshl_add_u64 v[232:233], v[36:37], 0, s[0:1]
	global_load_dwordx4 v[190:193], v[232:233], off nt
	global_load_dwordx4 v[194:197], v[232:233], off offset:16 nt
	global_load_dwordx4 v[198:201], v[232:233], off offset:2048 nt
	global_load_dwordx4 v[204:207], v[232:233], off offset:2064 nt
	s_waitcnt vmcnt(8)
	v_pk_add_f32 v[174:175], v[174:175], v[208:209]
	v_pk_add_f32 v[176:177], v[176:177], v[210:211]
	v_pk_add_f32 v[178:179], v[178:179], v[212:213]
	v_pk_add_f32 v[180:181], v[180:181], v[214:215]
	v_pk_add_f32 v[182:183], v[182:183], v[216:217]
	v_pk_add_f32 v[184:185], v[184:185], v[218:219]
	v_pk_add_f32 v[186:187], v[186:187], v[220:221]
	v_pk_add_f32 v[188:189], v[188:189], v[222:223]
	s_mov_b64 s[0:1], 0x1c00000
	v_lshl_add_u64 v[232:233], v[36:37], 0, s[0:1]
	global_load_dwordx4 v[208:211], v[232:233], off nt
	global_load_dwordx4 v[212:215], v[232:233], off offset:16 nt
	global_load_dwordx4 v[216:219], v[232:233], off offset:2048 nt
	global_load_dwordx4 v[220:223], v[232:233], off offset:2064 nt
	s_waitcnt vmcnt(8)
	v_pk_add_f32 v[174:175], v[174:175], v[224:225]
	v_pk_add_f32 v[176:177], v[176:177], v[226:227]
	v_pk_add_f32 v[178:179], v[178:179], v[228:229]
	v_pk_add_f32 v[180:181], v[180:181], v[230:231]
	v_pk_add_f32 v[182:183], v[182:183], v[238:239]
	v_pk_add_f32 v[184:185], v[184:185], v[240:241]
	v_pk_add_f32 v[186:187], v[186:187], v[242:243]
	v_pk_add_f32 v[188:189], v[188:189], v[244:245]
	s_mov_b64 s[0:1], 0x2000000
	v_lshl_add_u64 v[232:233], v[36:37], 0, s[0:1]
	global_load_dwordx4 v[224:227], v[232:233], off nt
	global_load_dwordx4 v[228:231], v[232:233], off offset:16 nt
	global_load_dwordx4 v[238:241], v[232:233], off offset:2048 nt
	global_load_dwordx4 v[242:245], v[232:233], off offset:2064 nt
	s_waitcnt vmcnt(8)
	v_pk_add_f32 v[174:175], v[174:175], v[190:191]
	v_pk_add_f32 v[176:177], v[176:177], v[192:193]
	v_pk_add_f32 v[178:179], v[178:179], v[194:195]
	v_pk_add_f32 v[180:181], v[180:181], v[196:197]
	v_pk_add_f32 v[182:183], v[182:183], v[198:199]
	v_pk_add_f32 v[184:185], v[184:185], v[200:201]
	v_pk_add_f32 v[186:187], v[186:187], v[204:205]
	v_pk_add_f32 v[188:189], v[188:189], v[206:207]
	s_mov_b64 s[0:1], 0x2400000
	v_lshl_add_u64 v[232:233], v[36:37], 0, s[0:1]
	global_load_dwordx4 v[190:193], v[232:233], off nt
	global_load_dwordx4 v[194:197], v[232:233], off offset:16 nt
	global_load_dwordx4 v[198:201], v[232:233], off offset:2048 nt
	global_load_dwordx4 v[204:207], v[232:233], off offset:2064 nt
	s_waitcnt vmcnt(8)
	v_pk_add_f32 v[174:175], v[174:175], v[208:209]
	v_pk_add_f32 v[176:177], v[176:177], v[210:211]
	v_pk_add_f32 v[178:179], v[178:179], v[212:213]
	v_pk_add_f32 v[180:181], v[180:181], v[214:215]
	v_pk_add_f32 v[182:183], v[182:183], v[216:217]
	v_pk_add_f32 v[184:185], v[184:185], v[218:219]
	v_pk_add_f32 v[186:187], v[186:187], v[220:221]
	v_pk_add_f32 v[188:189], v[188:189], v[222:223]
	s_mov_b64 s[0:1], 0x2800000
	v_lshl_add_u64 v[232:233], v[36:37], 0, s[0:1]
	global_load_dwordx4 v[208:211], v[232:233], off nt
	global_load_dwordx4 v[212:215], v[232:233], off offset:16 nt
	global_load_dwordx4 v[216:219], v[232:233], off offset:2048 nt
	global_load_dwordx4 v[220:223], v[232:233], off offset:2064 nt
	s_waitcnt vmcnt(8)
	v_pk_add_f32 v[174:175], v[174:175], v[224:225]
	v_pk_add_f32 v[176:177], v[176:177], v[226:227]
	v_pk_add_f32 v[178:179], v[178:179], v[228:229]
	v_pk_add_f32 v[180:181], v[180:181], v[230:231]
	v_pk_add_f32 v[182:183], v[182:183], v[238:239]
	v_pk_add_f32 v[184:185], v[184:185], v[240:241]
	v_pk_add_f32 v[186:187], v[186:187], v[242:243]
	v_pk_add_f32 v[188:189], v[188:189], v[244:245]
	global_load_dwordx4 v[224:227], v[74:75], off
	global_load_dwordx4 v[228:231], v[74:75], off offset:16
	global_load_dwordx4 v[238:241], v[74:75], off offset:2048
	global_load_dwordx4 v[242:245], v[74:75], off offset:2064
	s_waitcnt vmcnt(8)
	v_pk_add_f32 v[174:175], v[174:175], v[190:191]
	v_pk_add_f32 v[176:177], v[176:177], v[192:193]
	v_pk_add_f32 v[178:179], v[178:179], v[194:195]
	v_pk_add_f32 v[180:181], v[180:181], v[196:197]
	v_pk_add_f32 v[182:183], v[182:183], v[198:199]
	v_pk_add_f32 v[184:185], v[184:185], v[200:201]
	v_pk_add_f32 v[186:187], v[186:187], v[204:205]
	v_pk_add_f32 v[188:189], v[188:189], v[206:207]
	s_mov_b64 s[0:1], 0x1000
	v_lshl_add_u64 v[232:233], v[36:37], 0, s[0:1]
	global_load_dwordx4 v[190:193], v[232:233], off nt
	global_load_dwordx4 v[194:197], v[232:233], off offset:16 nt
	global_load_dwordx4 v[198:201], v[232:233], off offset:2048 nt
	global_load_dwordx4 v[204:207], v[232:233], off offset:2064 nt
	s_waitcnt vmcnt(8)
	v_pk_add_f32 v[174:175], v[174:175], v[208:209]
	v_pk_add_f32 v[176:177], v[176:177], v[210:211]
	v_pk_add_f32 v[178:179], v[178:179], v[212:213]
	v_pk_add_f32 v[180:181], v[180:181], v[214:215]
	v_pk_add_f32 v[182:183], v[182:183], v[216:217]
	v_pk_add_f32 v[184:185], v[184:185], v[218:219]
	v_pk_add_f32 v[186:187], v[186:187], v[220:221]
	v_pk_add_f32 v[188:189], v[188:189], v[222:223]
	s_mov_b64 s[0:1], 0x401000
	v_lshl_add_u64 v[232:233], v[36:37], 0, s[0:1]
	global_load_dwordx4 v[208:211], v[232:233], off nt
	global_load_dwordx4 v[212:215], v[232:233], off offset:16 nt
	global_load_dwordx4 v[216:219], v[232:233], off offset:2048 nt
	global_load_dwordx4 v[220:223], v[232:233], off offset:2064 nt
	s_waitcnt vmcnt(8)
	v_pk_fma_f32 v[166:167], v[174:175], v[224:225], v[166:167]
	v_pk_fma_f32 v[162:163], v[176:177], v[226:227], v[162:163]
	v_pk_fma_f32 v[160:161], v[178:179], v[228:229], v[160:161]
	v_pk_fma_f32 v[164:165], v[180:181], v[230:231], v[164:165]
	v_pk_fma_f32 v[154:155], v[182:183], v[238:239], v[154:155]
	v_pk_fma_f32 v[156:157], v[184:185], v[240:241], v[156:157]
	v_pk_fma_f32 v[152:153], v[186:187], v[242:243], v[152:153]
	v_pk_fma_f32 v[158:159], v[188:189], v[244:245], v[158:159]
	s_mov_b64 s[0:1], 0x801000
	v_lshl_add_u64 v[232:233], v[36:37], 0, s[0:1]
	global_load_dwordx4 v[224:227], v[232:233], off nt
	global_load_dwordx4 v[228:231], v[232:233], off offset:16 nt
	global_load_dwordx4 v[238:241], v[232:233], off offset:2048 nt
	global_load_dwordx4 v[242:245], v[232:233], off offset:2064 nt
	s_waitcnt vmcnt(8)
	v_mov_b64_e32 v[174:175], v[190:191]
	v_mov_b64_e32 v[176:177], v[192:193]
	v_mov_b64_e32 v[178:179], v[194:195]
	v_mov_b64_e32 v[180:181], v[196:197]
	v_mov_b64_e32 v[182:183], v[198:199]
	v_mov_b64_e32 v[184:185], v[200:201]
	v_mov_b64_e32 v[186:187], v[204:205]
	v_mov_b64_e32 v[188:189], v[206:207]
	s_mov_b64 s[0:1], 0xc01000
	v_lshl_add_u64 v[232:233], v[36:37], 0, s[0:1]
	global_load_dwordx4 v[190:193], v[232:233], off nt
	global_load_dwordx4 v[194:197], v[232:233], off offset:16 nt
	global_load_dwordx4 v[198:201], v[232:233], off offset:2048 nt
	global_load_dwordx4 v[204:207], v[232:233], off offset:2064 nt
	s_waitcnt vmcnt(8)
	v_pk_add_f32 v[174:175], v[174:175], v[208:209]
	v_pk_add_f32 v[176:177], v[176:177], v[210:211]
	v_pk_add_f32 v[178:179], v[178:179], v[212:213]
	v_pk_add_f32 v[180:181], v[180:181], v[214:215]
	v_pk_add_f32 v[182:183], v[182:183], v[216:217]
	v_pk_add_f32 v[184:185], v[184:185], v[218:219]
	v_pk_add_f32 v[186:187], v[186:187], v[220:221]
	v_pk_add_f32 v[188:189], v[188:189], v[222:223]
	s_mov_b64 s[0:1], 0x1001000
	v_lshl_add_u64 v[232:233], v[36:37], 0, s[0:1]
	global_load_dwordx4 v[208:211], v[232:233], off nt
	global_load_dwordx4 v[212:215], v[232:233], off offset:16 nt
	global_load_dwordx4 v[216:219], v[232:233], off offset:2048 nt
	global_load_dwordx4 v[220:223], v[232:233], off offset:2064 nt
	s_waitcnt vmcnt(8)
	v_pk_add_f32 v[174:175], v[174:175], v[224:225]
	v_pk_add_f32 v[176:177], v[176:177], v[226:227]
	v_pk_add_f32 v[178:179], v[178:179], v[228:229]
	v_pk_add_f32 v[180:181], v[180:181], v[230:231]
	v_pk_add_f32 v[182:183], v[182:183], v[238:239]
	v_pk_add_f32 v[184:185], v[184:185], v[240:241]
	v_pk_add_f32 v[186:187], v[186:187], v[242:243]
	v_pk_add_f32 v[188:189], v[188:189], v[244:245]
	s_mov_b64 s[0:1], 0x1401000
	v_lshl_add_u64 v[232:233], v[36:37], 0, s[0:1]
	global_load_dwordx4 v[224:227], v[232:233], off nt
	global_load_dwordx4 v[228:231], v[232:233], off offset:16 nt
	global_load_dwordx4 v[238:241], v[232:233], off offset:2048 nt
	global_load_dwordx4 v[242:245], v[232:233], off offset:2064 nt
	s_waitcnt vmcnt(8)
	v_pk_add_f32 v[174:175], v[174:175], v[190:191]
	v_pk_add_f32 v[176:177], v[176:177], v[192:193]
	v_pk_add_f32 v[178:179], v[178:179], v[194:195]
	v_pk_add_f32 v[180:181], v[180:181], v[196:197]
	v_pk_add_f32 v[182:183], v[182:183], v[198:199]
	v_pk_add_f32 v[184:185], v[184:185], v[200:201]
	v_pk_add_f32 v[186:187], v[186:187], v[204:205]
	v_pk_add_f32 v[188:189], v[188:189], v[206:207]
	s_mov_b64 s[0:1], 0x1801000
	v_lshl_add_u64 v[232:233], v[36:37], 0, s[0:1]
	global_load_dwordx4 v[190:193], v[232:233], off nt
	global_load_dwordx4 v[194:197], v[232:233], off offset:16 nt
	global_load_dwordx4 v[198:201], v[232:233], off offset:2048 nt
	global_load_dwordx4 v[204:207], v[232:233], off offset:2064 nt
	s_waitcnt vmcnt(8)
	v_pk_add_f32 v[174:175], v[174:175], v[208:209]
	v_pk_add_f32 v[176:177], v[176:177], v[210:211]
	v_pk_add_f32 v[178:179], v[178:179], v[212:213]
	v_pk_add_f32 v[180:181], v[180:181], v[214:215]
	v_pk_add_f32 v[182:183], v[182:183], v[216:217]
	v_pk_add_f32 v[184:185], v[184:185], v[218:219]
	v_pk_add_f32 v[186:187], v[186:187], v[220:221]
	v_pk_add_f32 v[188:189], v[188:189], v[222:223]
	s_mov_b64 s[0:1], 0x1c01000
	v_lshl_add_u64 v[232:233], v[36:37], 0, s[0:1]
	global_load_dwordx4 v[208:211], v[232:233], off nt
	global_load_dwordx4 v[212:215], v[232:233], off offset:16 nt
	global_load_dwordx4 v[216:219], v[232:233], off offset:2048 nt
	global_load_dwordx4 v[220:223], v[232:233], off offset:2064 nt
	s_waitcnt vmcnt(8)
	v_pk_add_f32 v[174:175], v[174:175], v[224:225]
	v_pk_add_f32 v[176:177], v[176:177], v[226:227]
	v_pk_add_f32 v[178:179], v[178:179], v[228:229]
	v_pk_add_f32 v[180:181], v[180:181], v[230:231]
	v_pk_add_f32 v[182:183], v[182:183], v[238:239]
	v_pk_add_f32 v[184:185], v[184:185], v[240:241]
	v_pk_add_f32 v[186:187], v[186:187], v[242:243]
	v_pk_add_f32 v[188:189], v[188:189], v[244:245]
	s_mov_b64 s[0:1], 0x2001000
	v_lshl_add_u64 v[232:233], v[36:37], 0, s[0:1]
	global_load_dwordx4 v[224:227], v[232:233], off nt
	global_load_dwordx4 v[228:231], v[232:233], off offset:16 nt
	global_load_dwordx4 v[238:241], v[232:233], off offset:2048 nt
	global_load_dwordx4 v[242:245], v[232:233], off offset:2064 nt
	s_waitcnt vmcnt(8)
	v_pk_add_f32 v[174:175], v[174:175], v[190:191]
	v_pk_add_f32 v[176:177], v[176:177], v[192:193]
	v_pk_add_f32 v[178:179], v[178:179], v[194:195]
	v_pk_add_f32 v[180:181], v[180:181], v[196:197]
	v_pk_add_f32 v[182:183], v[182:183], v[198:199]
	v_pk_add_f32 v[184:185], v[184:185], v[200:201]
	v_pk_add_f32 v[186:187], v[186:187], v[204:205]
	v_pk_add_f32 v[188:189], v[188:189], v[206:207]
	s_mov_b64 s[0:1], 0x2401000
	v_lshl_add_u64 v[232:233], v[36:37], 0, s[0:1]
	global_load_dwordx4 v[190:193], v[232:233], off nt
	global_load_dwordx4 v[194:197], v[232:233], off offset:16 nt
	global_load_dwordx4 v[198:201], v[232:233], off offset:2048 nt
	global_load_dwordx4 v[204:207], v[232:233], off offset:2064 nt
	s_waitcnt vmcnt(8)
	v_pk_add_f32 v[174:175], v[174:175], v[208:209]
	v_pk_add_f32 v[176:177], v[176:177], v[210:211]
	v_pk_add_f32 v[178:179], v[178:179], v[212:213]
	v_pk_add_f32 v[180:181], v[180:181], v[214:215]
	v_pk_add_f32 v[182:183], v[182:183], v[216:217]
	v_pk_add_f32 v[184:185], v[184:185], v[218:219]
	v_pk_add_f32 v[186:187], v[186:187], v[220:221]
	v_pk_add_f32 v[188:189], v[188:189], v[222:223]
	s_mov_b64 s[0:1], 0x2801000
	v_lshl_add_u64 v[232:233], v[36:37], 0, s[0:1]
	global_load_dwordx4 v[208:211], v[232:233], off nt
	global_load_dwordx4 v[212:215], v[232:233], off offset:16 nt
	global_load_dwordx4 v[216:219], v[232:233], off offset:2048 nt
	global_load_dwordx4 v[220:223], v[232:233], off offset:2064 nt
	s_waitcnt vmcnt(8)
	v_pk_add_f32 v[174:175], v[174:175], v[224:225]
	v_pk_add_f32 v[176:177], v[176:177], v[226:227]
	v_pk_add_f32 v[178:179], v[178:179], v[228:229]
	v_pk_add_f32 v[180:181], v[180:181], v[230:231]
	v_pk_add_f32 v[182:183], v[182:183], v[238:239]
	v_pk_add_f32 v[184:185], v[184:185], v[240:241]
	v_pk_add_f32 v[186:187], v[186:187], v[242:243]
	v_pk_add_f32 v[188:189], v[188:189], v[244:245]
	global_load_dwordx4 v[224:227], v[76:77], off
	global_load_dwordx4 v[228:231], v[76:77], off offset:16
	global_load_dwordx4 v[238:241], v[78:79], off
	global_load_dwordx4 v[242:245], v[78:79], off offset:16
	s_waitcnt vmcnt(8)
	v_pk_add_f32 v[174:175], v[174:175], v[190:191]
	v_pk_add_f32 v[176:177], v[176:177], v[192:193]
	v_pk_add_f32 v[178:179], v[178:179], v[194:195]
	v_pk_add_f32 v[180:181], v[180:181], v[196:197]
	v_pk_add_f32 v[182:183], v[182:183], v[198:199]
	v_pk_add_f32 v[184:185], v[184:185], v[200:201]
	v_pk_add_f32 v[186:187], v[186:187], v[204:205]
	v_pk_add_f32 v[188:189], v[188:189], v[206:207]
	s_waitcnt vmcnt(4)
	v_pk_add_f32 v[174:175], v[174:175], v[208:209]
	v_pk_add_f32 v[176:177], v[176:177], v[210:211]
	v_pk_add_f32 v[178:179], v[178:179], v[212:213]
	v_pk_add_f32 v[180:181], v[180:181], v[214:215]
	v_pk_add_f32 v[182:183], v[182:183], v[216:217]
	v_pk_add_f32 v[184:185], v[184:185], v[218:219]
	v_pk_add_f32 v[186:187], v[186:187], v[220:221]
	v_pk_add_f32 v[188:189], v[188:189], v[222:223]
	s_waitcnt vmcnt(0)
	v_pk_fma_f32 v[44:45], v[174:175], v[224:225], v[44:45]
	v_pk_fma_f32 v[46:47], v[176:177], v[226:227], v[46:47]
	v_pk_fma_f32 v[42:43], v[178:179], v[228:229], v[42:43]
	v_pk_fma_f32 v[48:49], v[180:181], v[230:231], v[48:49]
	v_pk_fma_f32 v[38:39], v[182:183], v[238:239], v[38:39]
	v_pk_fma_f32 v[40:41], v[184:185], v[240:241], v[40:41]
	v_pk_fma_f32 v[32:33], v[186:187], v[242:243], v[32:33]
	v_pk_fma_f32 v[34:35], v[188:189], v[244:245], v[34:35]

.LBB0_1055:
	s_add_i32 s0, s75, s8
	s_cmpk_lt_i32 s0, 0x4200
	s_cselect_b32 s0, s0, s8
	s_ashr_i32 s1, s0, 31
	s_lshl_b64 s[0:1], s[0:1], 12
	v_lshl_add_u64 v[32:33], v[80:81], 0, s[0:1]
	global_load_dwordx4 v[46:49], v[32:33], off
	global_load_dwordx4 v[42:45], v[32:33], off offset:1024
	global_load_dwordx4 v[38:41], v[32:33], off offset:2048
	global_load_dwordx4 v[34:37], v[32:33], off offset:3072
	s_waitcnt vmcnt(4)
	s_andn2_b64 vcc, exec, s[14:15]
	s_cbranch_vccnz .LBB0_1045
	v_cvt_f32_f16_sdwa v167, v62 dst_sel:DWORD dst_unused:UNUSED_PAD src0_sel:WORD_1
	v_cvt_f32_f16_e32 v166, v62
	v_cvt_f32_f16_sdwa v163, v63 dst_sel:DWORD dst_unused:UNUSED_PAD src0_sel:WORD_1
	v_cvt_f32_f16_e32 v162, v63
	v_cvt_f32_f16_sdwa v161, v64 dst_sel:DWORD dst_unused:UNUSED_PAD src0_sel:WORD_1
	v_cvt_f32_f16_e32 v160, v64
	v_cvt_f32_f16_sdwa v165, v65 dst_sel:DWORD dst_unused:UNUSED_PAD src0_sel:WORD_1
	v_cvt_f32_f16_e32 v164, v65
	v_cvt_f32_f16_sdwa v155, v58 dst_sel:DWORD dst_unused:UNUSED_PAD src0_sel:WORD_1
	v_cvt_f32_f16_e32 v154, v58
	v_cvt_f32_f16_sdwa v157, v59 dst_sel:DWORD dst_unused:UNUSED_PAD src0_sel:WORD_1
	v_cvt_f32_f16_e32 v156, v59
	v_cvt_f32_f16_sdwa v153, v60 dst_sel:DWORD dst_unused:UNUSED_PAD src0_sel:WORD_1
	v_cvt_f32_f16_e32 v152, v60
	v_cvt_f32_f16_sdwa v159, v61 dst_sel:DWORD dst_unused:UNUSED_PAD src0_sel:WORD_1
	v_cvt_f32_f16_e32 v158, v61
	v_cvt_f32_f16_sdwa v61, v54 dst_sel:DWORD dst_unused:UNUSED_PAD src0_sel:WORD_1
	v_cvt_f32_f16_e32 v60, v54
	v_cvt_f32_f16_sdwa v63, v55 dst_sel:DWORD dst_unused:UNUSED_PAD src0_sel:WORD_1
	v_cvt_f32_f16_e32 v62, v55
	v_cvt_f32_f16_sdwa v59, v56 dst_sel:DWORD dst_unused:UNUSED_PAD src0_sel:WORD_1
	v_cvt_f32_f16_e32 v58, v56
	v_cvt_f32_f16_sdwa v65, v57 dst_sel:DWORD dst_unused:UNUSED_PAD src0_sel:WORD_1
	v_cvt_f32_f16_e32 v64, v57
	v_cvt_f32_f16_sdwa v55, v50 dst_sel:DWORD dst_unused:UNUSED_PAD src0_sel:WORD_1
	v_cvt_f32_f16_e32 v54, v50
	v_cvt_f32_f16_sdwa v57, v51 dst_sel:DWORD dst_unused:UNUSED_PAD src0_sel:WORD_1
	v_cvt_f32_f16_e32 v56, v51
	v_cvt_f32_f16_sdwa v33, v52 dst_sel:DWORD dst_unused:UNUSED_PAD src0_sel:WORD_1
	v_cvt_f32_f16_e32 v32, v52
	v_cvt_f32_f16_sdwa v51, v53 dst_sel:DWORD dst_unused:UNUSED_PAD src0_sel:WORD_1
	v_cvt_f32_f16_e32 v50, v53
	s_cmpk_gt_i32 s16, 0x3fff
	s_cselect_b64 s[2:3], -1, 0
	s_cmpk_lt_i32 s16, 0x4000
	s_cbranch_scc1 .LBB0_1058
	s_add_i32 s86, s16, 0xffffc000
	s_lshl_b64 s[0:1], s[86:87], 13
	v_lshl_add_u64 v[52:53], v[82:83], 0, s[0:1]
	global_load_dwordx4 v[190:193], v[52:53], off nt
	global_load_dwordx4 v[194:197], v[52:53], off offset:16 nt
	global_load_dwordx4 v[198:201], v[52:53], off offset:2048 nt
	global_load_dwordx4 v[204:207], v[52:53], off offset:2064 nt
	s_mov_b64 s[0:1], 0x400000
	v_lshl_add_u64 v[232:233], v[52:53], 0, s[0:1]
	global_load_dwordx4 v[208:211], v[232:233], off nt
	global_load_dwordx4 v[212:215], v[232:233], off offset:16 nt
	global_load_dwordx4 v[216:219], v[232:233], off offset:2048 nt
	global_load_dwordx4 v[220:223], v[232:233], off offset:2064 nt
	s_mov_b64 s[0:1], 0x800000
	v_lshl_add_u64 v[232:233], v[52:53], 0, s[0:1]
	global_load_dwordx4 v[224:227], v[232:233], off nt
	global_load_dwordx4 v[228:231], v[232:233], off offset:16 nt
	global_load_dwordx4 v[238:241], v[232:233], off offset:2048 nt
	global_load_dwordx4 v[242:245], v[232:233], off offset:2064 nt
	s_waitcnt vmcnt(8)
	v_mov_b64_e32 v[174:175], v[190:191]
	v_mov_b64_e32 v[176:177], v[192:193]
	v_mov_b64_e32 v[178:179], v[194:195]
	v_mov_b64_e32 v[180:181], v[196:197]
	v_mov_b64_e32 v[182:183], v[198:199]
	v_mov_b64_e32 v[184:185], v[200:201]
	v_mov_b64_e32 v[186:187], v[204:205]
	v_mov_b64_e32 v[188:189], v[206:207]
	s_mov_b64 s[0:1], 0xc00000
	v_lshl_add_u64 v[232:233], v[52:53], 0, s[0:1]
	global_load_dwordx4 v[190:193], v[232:233], off nt
	global_load_dwordx4 v[194:197], v[232:233], off offset:16 nt
	global_load_dwordx4 v[198:201], v[232:233], off offset:2048 nt
	global_load_dwordx4 v[204:207], v[232:233], off offset:2064 nt
	s_waitcnt vmcnt(8)
	v_pk_add_f32 v[174:175], v[174:175], v[208:209]
	v_pk_add_f32 v[176:177], v[176:177], v[210:211]
	v_pk_add_f32 v[178:179], v[178:179], v[212:213]
	v_pk_add_f32 v[180:181], v[180:181], v[214:215]
	v_pk_add_f32 v[182:183], v[182:183], v[216:217]
	v_pk_add_f32 v[184:185], v[184:185], v[218:219]
	v_pk_add_f32 v[186:187], v[186:187], v[220:221]
	v_pk_add_f32 v[188:189], v[188:189], v[222:223]
	s_mov_b64 s[0:1], 0x1000000
	v_lshl_add_u64 v[232:233], v[52:53], 0, s[0:1]
	global_load_dwordx4 v[208:211], v[232:233], off nt
	global_load_dwordx4 v[212:215], v[232:233], off offset:16 nt
	global_load_dwordx4 v[216:219], v[232:233], off offset:2048 nt
	global_load_dwordx4 v[220:223], v[232:233], off offset:2064 nt
	s_waitcnt vmcnt(8)
	v_pk_add_f32 v[174:175], v[174:175], v[224:225]
	v_pk_add_f32 v[176:177], v[176:177], v[226:227]
	v_pk_add_f32 v[178:179], v[178:179], v[228:229]
	v_pk_add_f32 v[180:181], v[180:181], v[230:231]
	v_pk_add_f32 v[182:183], v[182:183], v[238:239]
	v_pk_add_f32 v[184:185], v[184:185], v[240:241]
	v_pk_add_f32 v[186:187], v[186:187], v[242:243]
	v_pk_add_f32 v[188:189], v[188:189], v[244:245]
	s_mov_b64 s[0:1], 0x1400000
	v_lshl_add_u64 v[232:233], v[52:53], 0, s[0:1]
	global_load_dwordx4 v[224:227], v[232:233], off nt
	global_load_dwordx4 v[228:231], v[232:233], off offset:16 nt
	global_load_dwordx4 v[238:241], v[232:233], off offset:2048 nt
	global_load_dwordx4 v[242:245], v[232:233], off offset:2064 nt
	s_waitcnt vmcnt(8)
	v_pk_add_f32 v[174:175], v[174:175], v[190:191]
	v_pk_add_f32 v[176:177], v[176:177], v[192:193]
	v_pk_add_f32 v[178:179], v[178:179], v[194:195]
	v_pk_add_f32 v[180:181], v[180:181], v[196:197]
	v_pk_add_f32 v[182:183], v[182:183], v[198:199]
	v_pk_add_f32 v[184:185], v[184:185], v[200:201]
	v_pk_add_f32 v[186:187], v[186:187], v[204:205]
	v_pk_add_f32 v[188:189], v[188:189], v[206:207]
	s_mov_b64 s[0:1], 0x1800000
	v_lshl_add_u64 v[232:233], v[52:53], 0, s[0:1]
	global_load_dwordx4 v[190:193], v[232:233], off nt
	global_load_dwordx4 v[194:197], v[232:233], off offset:16 nt
	global_load_dwordx4 v[198:201], v[232:233], off offset:2048 nt
	global_load_dwordx4 v[204:207], v[232:233], off offset:2064 nt
	s_waitcnt vmcnt(8)
	v_pk_add_f32 v[174:175], v[174:175], v[208:209]
	v_pk_add_f32 v[176:177], v[176:177], v[210:211]
	v_pk_add_f32 v[178:179], v[178:179], v[212:213]
	v_pk_add_f32 v[180:181], v[180:181], v[214:215]
	v_pk_add_f32 v[182:183], v[182:183], v[216:217]
	v_pk_add_f32 v[184:185], v[184:185], v[218:219]
	v_pk_add_f32 v[186:187], v[186:187], v[220:221]
	v_pk_add_f32 v[188:189], v[188:189], v[222:223]
	s_mov_b64 s[0:1], 0x1c00000
	v_lshl_add_u64 v[232:233], v[52:53], 0, s[0:1]
	global_load_dwordx4 v[208:211], v[232:233], off nt
	global_load_dwordx4 v[212:215], v[232:233], off offset:16 nt
	global_load_dwordx4 v[216:219], v[232:233], off offset:2048 nt
	global_load_dwordx4 v[220:223], v[232:233], off offset:2064 nt
	s_waitcnt vmcnt(8)
	v_pk_add_f32 v[174:175], v[174:175], v[224:225]
	v_pk_add_f32 v[176:177], v[176:177], v[226:227]
	v_pk_add_f32 v[178:179], v[178:179], v[228:229]
	v_pk_add_f32 v[180:181], v[180:181], v[230:231]
	v_pk_add_f32 v[182:183], v[182:183], v[238:239]
	v_pk_add_f32 v[184:185], v[184:185], v[240:241]
	v_pk_add_f32 v[186:187], v[186:187], v[242:243]
	v_pk_add_f32 v[188:189], v[188:189], v[244:245]
	s_mov_b64 s[0:1], 0x2000000
	v_lshl_add_u64 v[232:233], v[52:53], 0, s[0:1]
	global_load_dwordx4 v[224:227], v[232:233], off nt
	global_load_dwordx4 v[228:231], v[232:233], off offset:16 nt
	global_load_dwordx4 v[238:241], v[232:233], off offset:2048 nt
	global_load_dwordx4 v[242:245], v[232:233], off offset:2064 nt
	s_waitcnt vmcnt(8)
	v_pk_add_f32 v[174:175], v[174:175], v[190:191]
	v_pk_add_f32 v[176:177], v[176:177], v[192:193]
	v_pk_add_f32 v[178:179], v[178:179], v[194:195]
	v_pk_add_f32 v[180:181], v[180:181], v[196:197]
	v_pk_add_f32 v[182:183], v[182:183], v[198:199]
	v_pk_add_f32 v[184:185], v[184:185], v[200:201]
	v_pk_add_f32 v[186:187], v[186:187], v[204:205]
	v_pk_add_f32 v[188:189], v[188:189], v[206:207]
	s_mov_b64 s[0:1], 0x2400000
	v_lshl_add_u64 v[232:233], v[52:53], 0, s[0:1]
	global_load_dwordx4 v[190:193], v[232:233], off nt
	global_load_dwordx4 v[194:197], v[232:233], off offset:16 nt
	global_load_dwordx4 v[198:201], v[232:233], off offset:2048 nt
	global_load_dwordx4 v[204:207], v[232:233], off offset:2064 nt
	s_waitcnt vmcnt(8)
	v_pk_add_f32 v[174:175], v[174:175], v[208:209]
	v_pk_add_f32 v[176:177], v[176:177], v[210:211]
	v_pk_add_f32 v[178:179], v[178:179], v[212:213]
	v_pk_add_f32 v[180:181], v[180:181], v[214:215]
	v_pk_add_f32 v[182:183], v[182:183], v[216:217]
	v_pk_add_f32 v[184:185], v[184:185], v[218:219]
	v_pk_add_f32 v[186:187], v[186:187], v[220:221]
	v_pk_add_f32 v[188:189], v[188:189], v[222:223]
	s_mov_b64 s[0:1], 0x2800000
	v_lshl_add_u64 v[232:233], v[52:53], 0, s[0:1]
	global_load_dwordx4 v[208:211], v[232:233], off nt
	global_load_dwordx4 v[212:215], v[232:233], off offset:16 nt
	global_load_dwordx4 v[216:219], v[232:233], off offset:2048 nt
	global_load_dwordx4 v[220:223], v[232:233], off offset:2064 nt
	s_waitcnt vmcnt(8)
	v_pk_add_f32 v[174:175], v[174:175], v[224:225]
	v_pk_add_f32 v[176:177], v[176:177], v[226:227]
	v_pk_add_f32 v[178:179], v[178:179], v[228:229]
	v_pk_add_f32 v[180:181], v[180:181], v[230:231]
	v_pk_add_f32 v[182:183], v[182:183], v[238:239]
	v_pk_add_f32 v[184:185], v[184:185], v[240:241]
	v_pk_add_f32 v[186:187], v[186:187], v[242:243]
	v_pk_add_f32 v[188:189], v[188:189], v[244:245]
	global_load_dwordx4 v[224:227], v[74:75], off
	global_load_dwordx4 v[228:231], v[74:75], off offset:16
	global_load_dwordx4 v[238:241], v[74:75], off offset:2048
	global_load_dwordx4 v[242:245], v[74:75], off offset:2064
	s_waitcnt vmcnt(8)
	v_pk_add_f32 v[174:175], v[174:175], v[190:191]
	v_pk_add_f32 v[176:177], v[176:177], v[192:193]
	v_pk_add_f32 v[178:179], v[178:179], v[194:195]
	v_pk_add_f32 v[180:181], v[180:181], v[196:197]
	v_pk_add_f32 v[182:183], v[182:183], v[198:199]
	v_pk_add_f32 v[184:185], v[184:185], v[200:201]
	v_pk_add_f32 v[186:187], v[186:187], v[204:205]
	v_pk_add_f32 v[188:189], v[188:189], v[206:207]
	s_mov_b64 s[0:1], 0x1000
	v_lshl_add_u64 v[232:233], v[52:53], 0, s[0:1]
	global_load_dwordx4 v[190:193], v[232:233], off nt
	global_load_dwordx4 v[194:197], v[232:233], off offset:16 nt
	global_load_dwordx4 v[198:201], v[232:233], off offset:2048 nt
	global_load_dwordx4 v[204:207], v[232:233], off offset:2064 nt
	s_waitcnt vmcnt(8)
	v_pk_add_f32 v[174:175], v[174:175], v[208:209]
	v_pk_add_f32 v[176:177], v[176:177], v[210:211]
	v_pk_add_f32 v[178:179], v[178:179], v[212:213]
	v_pk_add_f32 v[180:181], v[180:181], v[214:215]
	v_pk_add_f32 v[182:183], v[182:183], v[216:217]
	v_pk_add_f32 v[184:185], v[184:185], v[218:219]
	v_pk_add_f32 v[186:187], v[186:187], v[220:221]
	v_pk_add_f32 v[188:189], v[188:189], v[222:223]
	s_mov_b64 s[0:1], 0x401000
	v_lshl_add_u64 v[232:233], v[52:53], 0, s[0:1]
	global_load_dwordx4 v[208:211], v[232:233], off nt
	global_load_dwordx4 v[212:215], v[232:233], off offset:16 nt
	global_load_dwordx4 v[216:219], v[232:233], off offset:2048 nt
	global_load_dwordx4 v[220:223], v[232:233], off offset:2064 nt
	s_waitcnt vmcnt(8)
	v_pk_fma_f32 v[166:167], v[174:175], v[224:225], v[166:167]
	v_pk_fma_f32 v[162:163], v[176:177], v[226:227], v[162:163]
	v_pk_fma_f32 v[160:161], v[178:179], v[228:229], v[160:161]
	v_pk_fma_f32 v[164:165], v[180:181], v[230:231], v[164:165]
	v_pk_fma_f32 v[154:155], v[182:183], v[238:239], v[154:155]
	v_pk_fma_f32 v[156:157], v[184:185], v[240:241], v[156:157]
	v_pk_fma_f32 v[152:153], v[186:187], v[242:243], v[152:153]
	v_pk_fma_f32 v[158:159], v[188:189], v[244:245], v[158:159]
	s_mov_b64 s[0:1], 0x801000
	v_lshl_add_u64 v[232:233], v[52:53], 0, s[0:1]
	global_load_dwordx4 v[224:227], v[232:233], off nt
	global_load_dwordx4 v[228:231], v[232:233], off offset:16 nt
	global_load_dwordx4 v[238:241], v[232:233], off offset:2048 nt
	global_load_dwordx4 v[242:245], v[232:233], off offset:2064 nt
	s_waitcnt vmcnt(8)
	v_mov_b64_e32 v[174:175], v[190:191]
	v_mov_b64_e32 v[176:177], v[192:193]
	v_mov_b64_e32 v[178:179], v[194:195]
	v_mov_b64_e32 v[180:181], v[196:197]
	v_mov_b64_e32 v[182:183], v[198:199]
	v_mov_b64_e32 v[184:185], v[200:201]
	v_mov_b64_e32 v[186:187], v[204:205]
	v_mov_b64_e32 v[188:189], v[206:207]
	s_mov_b64 s[0:1], 0xc01000
	v_lshl_add_u64 v[232:233], v[52:53], 0, s[0:1]
	global_load_dwordx4 v[190:193], v[232:233], off nt
	global_load_dwordx4 v[194:197], v[232:233], off offset:16 nt
	global_load_dwordx4 v[198:201], v[232:233], off offset:2048 nt
	global_load_dwordx4 v[204:207], v[232:233], off offset:2064 nt
	s_waitcnt vmcnt(8)
	v_pk_add_f32 v[174:175], v[174:175], v[208:209]
	v_pk_add_f32 v[176:177], v[176:177], v[210:211]
	v_pk_add_f32 v[178:179], v[178:179], v[212:213]
	v_pk_add_f32 v[180:181], v[180:181], v[214:215]
	v_pk_add_f32 v[182:183], v[182:183], v[216:217]
	v_pk_add_f32 v[184:185], v[184:185], v[218:219]
	v_pk_add_f32 v[186:187], v[186:187], v[220:221]
	v_pk_add_f32 v[188:189], v[188:189], v[222:223]
	s_mov_b64 s[0:1], 0x1001000
	v_lshl_add_u64 v[232:233], v[52:53], 0, s[0:1]
	global_load_dwordx4 v[208:211], v[232:233], off nt
	global_load_dwordx4 v[212:215], v[232:233], off offset:16 nt
	global_load_dwordx4 v[216:219], v[232:233], off offset:2048 nt
	global_load_dwordx4 v[220:223], v[232:233], off offset:2064 nt
	s_waitcnt vmcnt(8)
	v_pk_add_f32 v[174:175], v[174:175], v[224:225]
	v_pk_add_f32 v[176:177], v[176:177], v[226:227]
	v_pk_add_f32 v[178:179], v[178:179], v[228:229]
	v_pk_add_f32 v[180:181], v[180:181], v[230:231]
	v_pk_add_f32 v[182:183], v[182:183], v[238:239]
	v_pk_add_f32 v[184:185], v[184:185], v[240:241]
	v_pk_add_f32 v[186:187], v[186:187], v[242:243]
	v_pk_add_f32 v[188:189], v[188:189], v[244:245]
	s_mov_b64 s[0:1], 0x1401000
	v_lshl_add_u64 v[232:233], v[52:53], 0, s[0:1]
	global_load_dwordx4 v[224:227], v[232:233], off nt
	global_load_dwordx4 v[228:231], v[232:233], off offset:16 nt
	global_load_dwordx4 v[238:241], v[232:233], off offset:2048 nt
	global_load_dwordx4 v[242:245], v[232:233], off offset:2064 nt
	s_waitcnt vmcnt(8)
	v_pk_add_f32 v[174:175], v[174:175], v[190:191]
	v_pk_add_f32 v[176:177], v[176:177], v[192:193]
	v_pk_add_f32 v[178:179], v[178:179], v[194:195]
	v_pk_add_f32 v[180:181], v[180:181], v[196:197]
	v_pk_add_f32 v[182:183], v[182:183], v[198:199]
	v_pk_add_f32 v[184:185], v[184:185], v[200:201]
	v_pk_add_f32 v[186:187], v[186:187], v[204:205]
	v_pk_add_f32 v[188:189], v[188:189], v[206:207]
	s_mov_b64 s[0:1], 0x1801000
	v_lshl_add_u64 v[232:233], v[52:53], 0, s[0:1]
	global_load_dwordx4 v[190:193], v[232:233], off nt
	global_load_dwordx4 v[194:197], v[232:233], off offset:16 nt
	global_load_dwordx4 v[198:201], v[232:233], off offset:2048 nt
	global_load_dwordx4 v[204:207], v[232:233], off offset:2064 nt
	s_waitcnt vmcnt(8)
	v_pk_add_f32 v[174:175], v[174:175], v[208:209]
	v_pk_add_f32 v[176:177], v[176:177], v[210:211]
	v_pk_add_f32 v[178:179], v[178:179], v[212:213]
	v_pk_add_f32 v[180:181], v[180:181], v[214:215]
	v_pk_add_f32 v[182:183], v[182:183], v[216:217]
	v_pk_add_f32 v[184:185], v[184:185], v[218:219]
	v_pk_add_f32 v[186:187], v[186:187], v[220:221]
	v_pk_add_f32 v[188:189], v[188:189], v[222:223]
	s_mov_b64 s[0:1], 0x1c01000
	v_lshl_add_u64 v[232:233], v[52:53], 0, s[0:1]
	global_load_dwordx4 v[208:211], v[232:233], off nt
	global_load_dwordx4 v[212:215], v[232:233], off offset:16 nt
	global_load_dwordx4 v[216:219], v[232:233], off offset:2048 nt
	global_load_dwordx4 v[220:223], v[232:233], off offset:2064 nt
	s_waitcnt vmcnt(8)
	v_pk_add_f32 v[174:175], v[174:175], v[224:225]
	v_pk_add_f32 v[176:177], v[176:177], v[226:227]
	v_pk_add_f32 v[178:179], v[178:179], v[228:229]
	v_pk_add_f32 v[180:181], v[180:181], v[230:231]
	v_pk_add_f32 v[182:183], v[182:183], v[238:239]
	v_pk_add_f32 v[184:185], v[184:185], v[240:241]
	v_pk_add_f32 v[186:187], v[186:187], v[242:243]
	v_pk_add_f32 v[188:189], v[188:189], v[244:245]
	s_mov_b64 s[0:1], 0x2001000
	v_lshl_add_u64 v[232:233], v[52:53], 0, s[0:1]
	global_load_dwordx4 v[224:227], v[232:233], off nt
	global_load_dwordx4 v[228:231], v[232:233], off offset:16 nt
	global_load_dwordx4 v[238:241], v[232:233], off offset:2048 nt
	global_load_dwordx4 v[242:245], v[232:233], off offset:2064 nt
	s_waitcnt vmcnt(8)
	v_pk_add_f32 v[174:175], v[174:175], v[190:191]
	v_pk_add_f32 v[176:177], v[176:177], v[192:193]
	v_pk_add_f32 v[178:179], v[178:179], v[194:195]
	v_pk_add_f32 v[180:181], v[180:181], v[196:197]
	v_pk_add_f32 v[182:183], v[182:183], v[198:199]
	v_pk_add_f32 v[184:185], v[184:185], v[200:201]
	v_pk_add_f32 v[186:187], v[186:187], v[204:205]
	v_pk_add_f32 v[188:189], v[188:189], v[206:207]
	s_mov_b64 s[0:1], 0x2401000
	v_lshl_add_u64 v[232:233], v[52:53], 0, s[0:1]
	global_load_dwordx4 v[190:193], v[232:233], off nt
	global_load_dwordx4 v[194:197], v[232:233], off offset:16 nt
	global_load_dwordx4 v[198:201], v[232:233], off offset:2048 nt
	global_load_dwordx4 v[204:207], v[232:233], off offset:2064 nt
	s_waitcnt vmcnt(8)
	v_pk_add_f32 v[174:175], v[174:175], v[208:209]
	v_pk_add_f32 v[176:177], v[176:177], v[210:211]
	v_pk_add_f32 v[178:179], v[178:179], v[212:213]
	v_pk_add_f32 v[180:181], v[180:181], v[214:215]
	v_pk_add_f32 v[182:183], v[182:183], v[216:217]
	v_pk_add_f32 v[184:185], v[184:185], v[218:219]
	v_pk_add_f32 v[186:187], v[186:187], v[220:221]
	v_pk_add_f32 v[188:189], v[188:189], v[222:223]
	s_mov_b64 s[0:1], 0x2801000
	v_lshl_add_u64 v[232:233], v[52:53], 0, s[0:1]
	global_load_dwordx4 v[208:211], v[232:233], off nt
	global_load_dwordx4 v[212:215], v[232:233], off offset:16 nt
	global_load_dwordx4 v[216:219], v[232:233], off offset:2048 nt
	global_load_dwordx4 v[220:223], v[232:233], off offset:2064 nt
	s_waitcnt vmcnt(8)
	v_pk_add_f32 v[174:175], v[174:175], v[224:225]
	v_pk_add_f32 v[176:177], v[176:177], v[226:227]
	v_pk_add_f32 v[178:179], v[178:179], v[228:229]
	v_pk_add_f32 v[180:181], v[180:181], v[230:231]
	v_pk_add_f32 v[182:183], v[182:183], v[238:239]
	v_pk_add_f32 v[184:185], v[184:185], v[240:241]
	v_pk_add_f32 v[186:187], v[186:187], v[242:243]
	v_pk_add_f32 v[188:189], v[188:189], v[244:245]
	global_load_dwordx4 v[224:227], v[76:77], off
	global_load_dwordx4 v[228:231], v[76:77], off offset:16
	global_load_dwordx4 v[238:241], v[78:79], off
	global_load_dwordx4 v[242:245], v[78:79], off offset:16
	s_waitcnt vmcnt(8)
	v_pk_add_f32 v[174:175], v[174:175], v[190:191]
	v_pk_add_f32 v[176:177], v[176:177], v[192:193]
	v_pk_add_f32 v[178:179], v[178:179], v[194:195]
	v_pk_add_f32 v[180:181], v[180:181], v[196:197]
	v_pk_add_f32 v[182:183], v[182:183], v[198:199]
	v_pk_add_f32 v[184:185], v[184:185], v[200:201]
	v_pk_add_f32 v[186:187], v[186:187], v[204:205]
	v_pk_add_f32 v[188:189], v[188:189], v[206:207]
	s_waitcnt vmcnt(4)
	v_pk_add_f32 v[174:175], v[174:175], v[208:209]
	v_pk_add_f32 v[176:177], v[176:177], v[210:211]
	v_pk_add_f32 v[178:179], v[178:179], v[212:213]
	v_pk_add_f32 v[180:181], v[180:181], v[214:215]
	v_pk_add_f32 v[182:183], v[182:183], v[216:217]
	v_pk_add_f32 v[184:185], v[184:185], v[218:219]
	v_pk_add_f32 v[186:187], v[186:187], v[220:221]
	v_pk_add_f32 v[188:189], v[188:189], v[222:223]
	s_waitcnt vmcnt(0)
	v_pk_fma_f32 v[60:61], v[174:175], v[224:225], v[60:61]
	v_pk_fma_f32 v[62:63], v[176:177], v[226:227], v[62:63]
	v_pk_fma_f32 v[58:59], v[178:179], v[228:229], v[58:59]
	v_pk_fma_f32 v[64:65], v[180:181], v[230:231], v[64:65]
	v_pk_fma_f32 v[54:55], v[182:183], v[238:239], v[54:55]
	v_pk_fma_f32 v[56:57], v[184:185], v[240:241], v[56:57]
	v_pk_fma_f32 v[32:33], v[186:187], v[242:243], v[32:33]
	v_pk_fma_f32 v[50:51], v[188:189], v[244:245], v[50:51]

.LBB0_1302:
	s_bfe_u32 s27, s24, 0x10001
	s_ashr_i32 s26, s24, 2
	s_lshl_b32 s0, s27, 7
	s_add_i32 s1, s26, s4
	s_add_i32 s0, s1, s0
	s_ashr_i32 s1, s0, 31
	s_and_b32 s25, s24, 1
	s_lshl_b64 s[0:1], s[0:1], 9
	v_lshl_add_u64 v[6:7], v[4:5], 0, s[0:1]
	s_lshl_b32 s0, s26, 10
	s_lshl_b32 s1, s25, 9
	s_bfe_i32 s17, s24, 0x10001
	s_or_b32 s2, s0, s1
	s_cmp_eq_u32 s27, 0
	s_cselect_b64 s[20:21], -1, 0
	s_and_b64 s[0:1], s[20:21], exec
	s_cselect_b32 s3, s5, s22
	s_movk_i32 s8, 0x100
	s_cselect_b32 s0, s60, 0xffffff80
	s_cselect_b32 s16, s8, 0xffffff00
	s_add_i32 s2, s2, s3
	s_ashr_i32 s3, s2, 31
	s_lshl_b64 s[8:9], s[2:3], 9
	v_readlane_b32 s18, v252, 0
	v_readlane_b32 s19, v252, 1
	s_add_u32 s8, s18, s8
	s_addc_u32 s9, s19, s9
	s_lshl_b32 s18, s27, 8
	s_add_u32 s8, s8, s18
	s_addc_u32 s9, s9, 0
	s_lshl_b64 s[2:3], s[2:3], 10
	s_add_u32 s2, s78, s2
	s_addc_u32 s3, s79, s3
	s_mov_b32 s1, s17
	v_lshlrev_b32_e32 v202, 2, v2
	s_add_u32 s2, s2, s18
	v_lshl_add_u64 v[8:9], s[8:9], 0, v[202:203]
	s_addc_u32 s3, s3, 0
	s_lshl_b64 s[18:19], s[0:1], 2
	v_lshl_add_u64 v[8:9], v[8:9], 0, s[18:19]
	global_load_dwordx2 v[6:7], v[6:7], off
	s_nop 0
	global_load_dword v10, v202, s[8:9] nt
	global_load_dword v11, v[8:9], off nt
	v_lshl_add_u64 v[8:9], v[8:9], 0, s[18:19]
	global_load_dword v12, v[8:9], off nt
	v_lshl_add_u64 v[8:9], v[8:9], 0, s[18:19]
	global_load_dword v13, v[8:9], off nt
	v_lshl_add_u64 v[8:9], v[8:9], 0, s[18:19]
	global_load_dword v14, v[8:9], off nt
	v_lshl_add_u64 v[8:9], v[8:9], 0, s[18:19]
	global_load_dword v15, v[8:9], off nt
	v_lshl_add_u64 v[8:9], v[8:9], 0, s[18:19]
	global_load_dword v16, v[8:9], off nt
	v_lshl_add_u64 v[8:9], v[8:9], 0, s[18:19]
	global_load_dword v17, v[8:9], off nt
	v_lshl_add_u64 v[8:9], v[8:9], 0, s[18:19]
	global_load_dword v18, v[8:9], off nt
	v_lshl_add_u64 v[8:9], v[8:9], 0, s[18:19]
	global_load_dword v19, v[8:9], off nt
	v_lshl_add_u64 v[8:9], v[8:9], 0, s[18:19]
	global_load_dword v20, v[8:9], off nt
	v_lshl_add_u64 v[8:9], v[8:9], 0, s[18:19]
	global_load_dword v21, v[8:9], off nt
	v_lshl_add_u64 v[8:9], v[8:9], 0, s[18:19]
	global_load_dword v22, v[8:9], off nt
	v_lshl_add_u64 v[8:9], v[8:9], 0, s[18:19]
	global_load_dword v23, v[8:9], off nt
	v_lshl_add_u64 v[8:9], v[8:9], 0, s[18:19]
	global_load_dword v24, v[8:9], off nt
	v_lshl_add_u64 v[8:9], v[8:9], 0, s[18:19]
	global_load_dword v25, v[8:9], off nt
	v_lshl_add_u64 v[8:9], v[8:9], 0, s[18:19]
	global_load_dword v26, v[8:9], off nt
	v_lshl_add_u64 v[8:9], v[8:9], 0, s[18:19]
	global_load_dword v27, v[8:9], off nt
	v_lshl_add_u64 v[8:9], v[8:9], 0, s[18:19]
	global_load_dword v28, v[8:9], off nt
	v_lshl_add_u64 v[8:9], v[8:9], 0, s[18:19]
	global_load_dword v29, v[8:9], off nt
	v_lshl_add_u64 v[8:9], v[8:9], 0, s[18:19]
	global_load_dword v30, v[8:9], off nt
	v_lshl_add_u64 v[8:9], v[8:9], 0, s[18:19]
	global_load_dword v31, v[8:9], off nt
	v_lshl_add_u64 v[8:9], v[8:9], 0, s[18:19]
	global_load_dword v32, v[8:9], off nt
	v_lshl_add_u64 v[8:9], v[8:9], 0, s[18:19]
	global_load_dword v33, v[8:9], off nt
	v_lshl_add_u64 v[8:9], v[8:9], 0, s[18:19]
	global_load_dword v34, v[8:9], off nt
	v_lshl_add_u64 v[8:9], v[8:9], 0, s[18:19]
	global_load_dword v35, v[8:9], off nt
	v_lshl_add_u64 v[8:9], v[8:9], 0, s[18:19]
	global_load_dword v36, v[8:9], off nt
	v_lshl_add_u64 v[8:9], v[8:9], 0, s[18:19]
	global_load_dword v37, v[8:9], off nt
	v_lshl_add_u64 v[8:9], v[8:9], 0, s[18:19]
	global_load_dword v38, v[8:9], off nt
	v_lshl_add_u64 v[8:9], v[8:9], 0, s[18:19]
	global_load_dword v39, v[8:9], off nt
	v_lshl_add_u64 v[8:9], v[8:9], 0, s[18:19]
	global_load_dword v40, v[8:9], off nt
	v_lshl_add_u64 v[8:9], v[8:9], 0, s[18:19]
	global_load_dword v41, v[8:9], off nt
	v_lshl_add_u64 v[8:9], v[8:9], 0, s[18:19]
	global_load_dword v42, v[8:9], off nt
	v_lshl_add_u64 v[8:9], v[8:9], 0, s[18:19]
	global_load_dword v43, v[8:9], off nt
	v_lshl_add_u64 v[8:9], v[8:9], 0, s[18:19]
	global_load_dword v45, v[8:9], off nt
	v_lshl_add_u64 v[8:9], v[8:9], 0, s[18:19]
	global_load_dword v116, v[8:9], off nt
	v_lshl_add_u64 v[8:9], v[8:9], 0, s[18:19]
	global_load_dword v117, v[8:9], off nt
	v_lshl_add_u64 v[8:9], v[8:9], 0, s[18:19]
	global_load_dword v118, v[8:9], off nt
	v_lshl_add_u64 v[8:9], v[8:9], 0, s[18:19]
	global_load_dword v119, v[8:9], off nt
	v_lshl_add_u64 v[8:9], v[8:9], 0, s[18:19]
	global_load_dword v121, v[8:9], off nt
	v_lshl_add_u64 v[8:9], v[8:9], 0, s[18:19]
	global_load_dword v134, v[8:9], off nt
	v_lshl_add_u64 v[8:9], v[8:9], 0, s[18:19]
	global_load_dword v135, v[8:9], off nt
	v_lshl_add_u64 v[8:9], v[8:9], 0, s[18:19]
	global_load_dword v136, v[8:9], off nt
	v_lshl_add_u64 v[8:9], v[8:9], 0, s[18:19]
	global_load_dword v137, v[8:9], off nt
	v_lshl_add_u64 v[8:9], v[8:9], 0, s[18:19]
	global_load_dword v138, v[8:9], off nt
	v_lshl_add_u64 v[8:9], v[8:9], 0, s[18:19]
	global_load_dword v139, v[8:9], off nt
	v_lshl_add_u64 v[8:9], v[8:9], 0, s[18:19]
	global_load_dword v140, v[8:9], off nt
	v_lshl_add_u64 v[8:9], v[8:9], 0, s[18:19]
	global_load_dword v141, v[8:9], off nt
	v_lshl_add_u64 v[8:9], v[8:9], 0, s[18:19]
	global_load_dword v142, v[8:9], off nt
	v_lshl_add_u64 v[8:9], v[8:9], 0, s[18:19]
	global_load_dword v143, v[8:9], off nt
	v_lshl_add_u64 v[8:9], v[8:9], 0, s[18:19]
	global_load_dword v144, v[8:9], off nt
	v_lshl_add_u64 v[8:9], v[8:9], 0, s[18:19]
	global_load_dword v145, v[8:9], off nt
	v_lshl_add_u64 v[8:9], v[8:9], 0, s[18:19]
	global_load_dword v146, v[8:9], off nt
	v_lshl_add_u64 v[8:9], v[8:9], 0, s[18:19]
	global_load_dword v133, v[8:9], off nt
	v_lshl_add_u64 v[8:9], v[8:9], 0, s[18:19]
	global_load_dword v132, v[8:9], off nt
	v_lshl_add_u64 v[8:9], v[8:9], 0, s[18:19]
	global_load_dword v131, v[8:9], off nt
	v_lshl_add_u64 v[8:9], v[8:9], 0, s[18:19]
	global_load_dword v130, v[8:9], off nt
	v_lshl_add_u64 v[8:9], v[8:9], 0, s[18:19]
	global_load_dword v129, v[8:9], off nt
	v_lshl_add_u64 v[8:9], v[8:9], 0, s[18:19]
	global_load_dword v128, v[8:9], off nt
	v_lshl_add_u64 v[8:9], v[8:9], 0, s[18:19]
	global_load_dword v127, v[8:9], off nt
	v_lshl_add_u64 v[8:9], v[8:9], 0, s[18:19]
	global_load_dword v126, v[8:9], off nt
	v_lshl_add_u64 v[8:9], v[8:9], 0, s[18:19]
	global_load_dword v125, v[8:9], off nt
	v_lshl_add_u64 v[8:9], v[8:9], 0, s[18:19]
	global_load_dword v124, v[8:9], off nt
	v_lshl_add_u64 v[8:9], v[8:9], 0, s[18:19]
	global_load_dword v120, v[8:9], off nt
	v_lshl_add_u64 v[8:9], v[8:9], 0, s[18:19]
	v_lshl_add_u64 v[114:115], s[2:3], 0, v[202:203]
	v_cndmask_b32_e64 v8, 0, 1, s[10:11]
	s_mov_b64 s[2:3], -1
	v_cmp_ne_u32_e64 s[8:9], 1, v8
	s_andn2_b64 vcc, exec, s[10:11]
	s_waitcnt vmcnt(0)
	v_lshlrev_b32_e32 v112, 16, v10
	v_lshlrev_b32_e32 v110, 16, v11
	v_lshlrev_b32_e32 v108, 16, v12
	v_lshlrev_b32_e32 v106, 16, v13
	v_lshlrev_b32_e32 v104, 16, v14
	v_lshlrev_b32_e32 v102, 16, v15
	v_lshlrev_b32_e32 v100, 16, v16
	v_lshlrev_b32_e32 v98, 16, v17
	v_lshlrev_b32_e32 v96, 16, v18
	v_lshlrev_b32_e32 v94, 16, v19
	v_lshlrev_b32_e32 v92, 16, v20
	v_lshlrev_b32_e32 v90, 16, v21
	v_lshlrev_b32_e32 v88, 16, v22
	v_lshlrev_b32_e32 v86, 16, v23
	v_lshlrev_b32_e32 v84, 16, v24
	v_lshlrev_b32_e32 v82, 16, v25
	v_lshlrev_b32_e32 v80, 16, v26
	v_lshlrev_b32_e32 v78, 16, v27
	v_lshlrev_b32_e32 v76, 16, v28
	v_lshlrev_b32_e32 v74, 16, v29
	v_lshlrev_b32_e32 v72, 16, v30
	v_lshlrev_b32_e32 v70, 16, v31
	v_lshlrev_b32_e32 v68, 16, v32
	v_lshlrev_b32_e32 v66, 16, v33
	v_lshlrev_b32_e32 v64, 16, v34
	v_lshlrev_b32_e32 v62, 16, v35
	v_lshlrev_b32_e32 v60, 16, v36
	v_lshlrev_b32_e32 v58, 16, v37
	v_lshlrev_b32_e32 v54, 16, v38
	v_and_b32_e32 v113, 0xffff0000, v10
	v_and_b32_e32 v111, 0xffff0000, v11
	v_and_b32_e32 v109, 0xffff0000, v12
	v_and_b32_e32 v107, 0xffff0000, v13
	v_and_b32_e32 v105, 0xffff0000, v14
	v_and_b32_e32 v103, 0xffff0000, v15
	v_and_b32_e32 v101, 0xffff0000, v16
	v_and_b32_e32 v99, 0xffff0000, v17
	v_and_b32_e32 v97, 0xffff0000, v18
	v_and_b32_e32 v95, 0xffff0000, v19
	v_and_b32_e32 v93, 0xffff0000, v20
	v_and_b32_e32 v91, 0xffff0000, v21
	v_and_b32_e32 v89, 0xffff0000, v22
	v_and_b32_e32 v87, 0xffff0000, v23
	v_and_b32_e32 v85, 0xffff0000, v24
	v_and_b32_e32 v83, 0xffff0000, v25
	v_and_b32_e32 v81, 0xffff0000, v26
	v_and_b32_e32 v79, 0xffff0000, v27
	v_and_b32_e32 v77, 0xffff0000, v28
	v_and_b32_e32 v75, 0xffff0000, v29
	v_and_b32_e32 v73, 0xffff0000, v30
	v_and_b32_e32 v71, 0xffff0000, v31
	v_and_b32_e32 v69, 0xffff0000, v32
	v_and_b32_e32 v67, 0xffff0000, v33
	v_and_b32_e32 v65, 0xffff0000, v34
	v_and_b32_e32 v63, 0xffff0000, v35
	v_and_b32_e32 v61, 0xffff0000, v36
	v_and_b32_e32 v59, 0xffff0000, v37
	v_and_b32_e32 v55, 0xffff0000, v38
	v_lshlrev_b32_e32 v56, 16, v39
	v_and_b32_e32 v57, 0xffff0000, v39
	v_lshlrev_b32_e32 v52, 16, v40
	v_and_b32_e32 v53, 0xffff0000, v40
	v_lshlrev_b32_e32 v50, 16, v41
	v_and_b32_e32 v51, 0xffff0000, v41
	v_lshlrev_b32_e32 v48, 16, v42
	v_and_b32_e32 v49, 0xffff0000, v42
	v_lshlrev_b32_e32 v46, 16, v43
	v_and_b32_e32 v47, 0xffff0000, v43
	v_lshlrev_b32_e32 v44, 16, v45
	v_and_b32_e32 v45, 0xffff0000, v45
	v_lshlrev_b32_e32 v42, 16, v116
	v_and_b32_e32 v43, 0xffff0000, v116
	v_lshlrev_b32_e32 v40, 16, v117
	v_and_b32_e32 v41, 0xffff0000, v117
	v_lshlrev_b32_e32 v38, 16, v118
	v_and_b32_e32 v39, 0xffff0000, v118
	v_lshlrev_b32_e32 v36, 16, v119
	v_and_b32_e32 v37, 0xffff0000, v119
	v_lshlrev_b32_e32 v34, 16, v121
	v_and_b32_e32 v35, 0xffff0000, v121
	v_lshlrev_b32_e32 v32, 16, v134
	v_and_b32_e32 v33, 0xffff0000, v134
	v_lshlrev_b32_e32 v30, 16, v135
	v_and_b32_e32 v31, 0xffff0000, v135
	v_lshlrev_b32_e32 v28, 16, v136
	v_and_b32_e32 v29, 0xffff0000, v136
	v_lshlrev_b32_e32 v26, 16, v137
	v_and_b32_e32 v27, 0xffff0000, v137
	v_lshlrev_b32_e32 v24, 16, v138
	v_and_b32_e32 v25, 0xffff0000, v138
	v_lshlrev_b32_e32 v22, 16, v139
	v_and_b32_e32 v23, 0xffff0000, v139
	v_lshlrev_b32_e32 v20, 16, v140
	v_and_b32_e32 v21, 0xffff0000, v140
	v_lshlrev_b32_e32 v18, 16, v141
	v_and_b32_e32 v19, 0xffff0000, v141
	v_lshlrev_b32_e32 v16, 16, v142
	v_and_b32_e32 v17, 0xffff0000, v142
	v_lshlrev_b32_e32 v14, 16, v143
	v_and_b32_e32 v15, 0xffff0000, v143
	v_lshlrev_b32_e32 v12, 16, v144
	v_and_b32_e32 v13, 0xffff0000, v144
	v_lshlrev_b32_e32 v10, 16, v145
	v_and_b32_e32 v11, 0xffff0000, v145
	v_lshlrev_b32_e32 v8, 16, v146
	v_and_b32_e32 v9, 0xffff0000, v146
	s_cbranch_vccnz .LBB0_1304
	v_pk_mul_f32 v[118:119], v[6:7], 0 op_sel_hi:[1,0]
	v_and_b32_e32 v140, 0xffff0000, v132
	v_sub_f32_e32 v121, v118, v119
	v_add_f32_e32 v118, v118, v119
	v_add_f32_e32 v118, v118, v113
	v_add_f32_e32 v134, v121, v112
	v_pk_mul_f32 v[118:119], v[6:7], v[118:119] op_sel:[1,0] op_sel_hi:[0,0]
	v_pk_fma_f32 v[136:137], v[6:7], v[134:135], v[118:119] neg_lo:[0,0,1] neg_hi:[0,0,1]
	v_pk_fma_f32 v[118:119], v[6:7], v[134:135], v[118:119] op_sel_hi:[1,0,1]
	s_mov_b64 s[0:1], 0x200
	v_mov_b32_e32 v137, v119
	v_pk_add_f32 v[118:119], v[136:137], v[110:111]
	v_lshl_add_u64 v[116:117], v[114:115], 0, s[0:1]
	v_pk_mul_f32 v[134:135], v[6:7], v[118:119]
	v_pk_mul_f32 v[118:119], v[6:7], v[118:119] op_sel:[0,1] op_sel_hi:[1,0]
	v_sub_f32_e32 v121, v134, v135
	v_add_f32_e32 v118, v118, v119
	v_add_f32_e32 v118, v118, v109
	v_add_f32_e32 v134, v121, v108
	v_pk_mul_f32 v[118:119], v[6:7], v[118:119] op_sel:[1,0] op_sel_hi:[0,0]
	v_pk_fma_f32 v[136:137], v[6:7], v[134:135], v[118:119] neg_lo:[0,0,1] neg_hi:[0,0,1]
	v_pk_fma_f32 v[118:119], v[6:7], v[134:135], v[118:119] op_sel_hi:[1,0,1]
	s_mov_b64 s[2:3], 0
	v_mov_b32_e32 v137, v119
	v_pk_add_f32 v[118:119], v[136:137], v[106:107]
	s_nop 0
	v_pk_mul_f32 v[134:135], v[6:7], v[118:119]
	v_pk_mul_f32 v[118:119], v[6:7], v[118:119] op_sel:[0,1] op_sel_hi:[1,0]
	v_sub_f32_e32 v121, v134, v135
	v_add_f32_e32 v118, v118, v119
	v_add_f32_e32 v118, v118, v105
	v_add_f32_e32 v134, v121, v104
	v_pk_mul_f32 v[118:119], v[6:7], v[118:119] op_sel:[1,0] op_sel_hi:[0,0]
	v_pk_fma_f32 v[136:137], v[6:7], v[134:135], v[118:119] neg_lo:[0,0,1] neg_hi:[0,0,1]
	v_pk_fma_f32 v[118:119], v[6:7], v[134:135], v[118:119] op_sel_hi:[1,0,1]
	s_nop 0
	v_mov_b32_e32 v137, v119
	v_pk_add_f32 v[118:119], v[136:137], v[102:103]
	s_nop 0
	v_pk_mul_f32 v[134:135], v[6:7], v[118:119]
	v_pk_mul_f32 v[118:119], v[6:7], v[118:119] op_sel:[0,1] op_sel_hi:[1,0]
	v_sub_f32_e32 v121, v134, v135
	v_add_f32_e32 v118, v118, v119
	v_add_f32_e32 v118, v118, v101
	v_add_f32_e32 v134, v121, v100
	v_pk_mul_f32 v[118:119], v[6:7], v[118:119] op_sel:[1,0] op_sel_hi:[0,0]
	v_pk_fma_f32 v[136:137], v[6:7], v[134:135], v[118:119] neg_lo:[0,0,1] neg_hi:[0,0,1]
	v_pk_fma_f32 v[118:119], v[6:7], v[134:135], v[118:119] op_sel_hi:[1,0,1]
	s_nop 0
	v_mov_b32_e32 v137, v119
	v_pk_add_f32 v[118:119], v[136:137], v[98:99]
	s_nop 0
	v_pk_mul_f32 v[134:135], v[6:7], v[118:119]
	v_pk_mul_f32 v[118:119], v[6:7], v[118:119] op_sel:[0,1] op_sel_hi:[1,0]
	v_sub_f32_e32 v121, v134, v135
	v_add_f32_e32 v118, v118, v119
	v_add_f32_e32 v118, v118, v97
	v_add_f32_e32 v134, v121, v96
	v_pk_mul_f32 v[118:119], v[6:7], v[118:119] op_sel:[1,0] op_sel_hi:[0,0]
	v_pk_fma_f32 v[136:137], v[6:7], v[134:135], v[118:119] neg_lo:[0,0,1] neg_hi:[0,0,1]
	v_pk_fma_f32 v[118:119], v[6:7], v[134:135], v[118:119] op_sel_hi:[1,0,1]
	s_nop 0
	v_mov_b32_e32 v137, v119
	v_pk_add_f32 v[118:119], v[136:137], v[94:95]
	s_nop 0
	v_pk_mul_f32 v[134:135], v[6:7], v[118:119]
	v_pk_mul_f32 v[118:119], v[6:7], v[118:119] op_sel:[0,1] op_sel_hi:[1,0]
	v_sub_f32_e32 v121, v134, v135
	v_add_f32_e32 v118, v118, v119
	v_add_f32_e32 v118, v118, v93
	v_add_f32_e32 v134, v121, v92
	v_pk_mul_f32 v[118:119], v[6:7], v[118:119] op_sel:[1,0] op_sel_hi:[0,0]
	v_pk_fma_f32 v[136:137], v[6:7], v[134:135], v[118:119] neg_lo:[0,0,1] neg_hi:[0,0,1]
	v_pk_fma_f32 v[118:119], v[6:7], v[134:135], v[118:119] op_sel_hi:[1,0,1]
	s_nop 0
	v_mov_b32_e32 v137, v119
	v_pk_add_f32 v[118:119], v[136:137], v[90:91]
	s_nop 0
	v_pk_mul_f32 v[134:135], v[6:7], v[118:119]
	v_pk_mul_f32 v[118:119], v[6:7], v[118:119] op_sel:[0,1] op_sel_hi:[1,0]
	v_sub_f32_e32 v121, v134, v135
	v_add_f32_e32 v118, v118, v119
	v_add_f32_e32 v118, v118, v89
	v_add_f32_e32 v134, v121, v88
	v_pk_mul_f32 v[118:119], v[6:7], v[118:119] op_sel:[1,0] op_sel_hi:[0,0]
	v_pk_fma_f32 v[136:137], v[6:7], v[134:135], v[118:119] neg_lo:[0,0,1] neg_hi:[0,0,1]
	v_pk_fma_f32 v[118:119], v[6:7], v[134:135], v[118:119] op_sel_hi:[1,0,1]
	s_nop 0
	v_mov_b32_e32 v137, v119
	v_pk_add_f32 v[118:119], v[136:137], v[86:87]
	s_nop 0
	v_pk_mul_f32 v[134:135], v[6:7], v[118:119]
	v_pk_mul_f32 v[118:119], v[6:7], v[118:119] op_sel:[0,1] op_sel_hi:[1,0]
	v_sub_f32_e32 v121, v134, v135
	v_add_f32_e32 v118, v118, v119
	v_add_f32_e32 v118, v118, v85
	v_add_f32_e32 v134, v121, v84
	v_pk_mul_f32 v[118:119], v[6:7], v[118:119] op_sel:[1,0] op_sel_hi:[0,0]
	v_pk_fma_f32 v[136:137], v[6:7], v[134:135], v[118:119] neg_lo:[0,0,1] neg_hi:[0,0,1]
	v_pk_fma_f32 v[118:119], v[6:7], v[134:135], v[118:119] op_sel_hi:[1,0,1]
	s_nop 0
	v_mov_b32_e32 v137, v119
	v_pk_add_f32 v[118:119], v[136:137], v[82:83]
	s_nop 0
	v_pk_mul_f32 v[134:135], v[6:7], v[118:119]
	v_pk_mul_f32 v[118:119], v[6:7], v[118:119] op_sel:[0,1] op_sel_hi:[1,0]
	v_sub_f32_e32 v121, v134, v135
	v_add_f32_e32 v118, v118, v119
	v_add_f32_e32 v118, v118, v81
	v_add_f32_e32 v134, v121, v80
	v_pk_mul_f32 v[118:119], v[6:7], v[118:119] op_sel:[1,0] op_sel_hi:[0,0]
	v_pk_fma_f32 v[136:137], v[6:7], v[134:135], v[118:119] neg_lo:[0,0,1] neg_hi:[0,0,1]
	v_pk_fma_f32 v[118:119], v[6:7], v[134:135], v[118:119] op_sel_hi:[1,0,1]
	s_nop 0
	v_mov_b32_e32 v137, v119
	v_pk_add_f32 v[118:119], v[136:137], v[78:79]
	s_nop 0
	v_pk_mul_f32 v[134:135], v[6:7], v[118:119]
	v_pk_mul_f32 v[118:119], v[6:7], v[118:119] op_sel:[0,1] op_sel_hi:[1,0]
	v_sub_f32_e32 v121, v134, v135
	v_add_f32_e32 v118, v118, v119
	v_add_f32_e32 v118, v118, v77
	v_add_f32_e32 v134, v121, v76
	v_pk_mul_f32 v[118:119], v[6:7], v[118:119] op_sel:[1,0] op_sel_hi:[0,0]
	v_pk_fma_f32 v[136:137], v[6:7], v[134:135], v[118:119] neg_lo:[0,0,1] neg_hi:[0,0,1]
	v_pk_fma_f32 v[118:119], v[6:7], v[134:135], v[118:119] op_sel_hi:[1,0,1]
	s_nop 0
	v_mov_b32_e32 v137, v119
	v_pk_add_f32 v[118:119], v[136:137], v[74:75]
	s_nop 0
	v_pk_mul_f32 v[134:135], v[6:7], v[118:119]
	v_pk_mul_f32 v[118:119], v[6:7], v[118:119] op_sel:[0,1] op_sel_hi:[1,0]
	v_sub_f32_e32 v121, v134, v135
	v_add_f32_e32 v118, v118, v119
	v_add_f32_e32 v118, v118, v73
	v_add_f32_e32 v134, v121, v72
	v_pk_mul_f32 v[118:119], v[6:7], v[118:119] op_sel:[1,0] op_sel_hi:[0,0]
	v_pk_fma_f32 v[136:137], v[6:7], v[134:135], v[118:119] neg_lo:[0,0,1] neg_hi:[0,0,1]
	v_pk_fma_f32 v[118:119], v[6:7], v[134:135], v[118:119] op_sel_hi:[1,0,1]
	s_nop 0
	v_mov_b32_e32 v137, v119
	v_pk_add_f32 v[118:119], v[136:137], v[70:71]
	s_nop 0
	v_pk_mul_f32 v[134:135], v[6:7], v[118:119]
	v_pk_mul_f32 v[118:119], v[6:7], v[118:119] op_sel:[0,1] op_sel_hi:[1,0]
	v_sub_f32_e32 v121, v134, v135
	v_add_f32_e32 v118, v118, v119
	v_add_f32_e32 v118, v118, v69
	v_add_f32_e32 v134, v121, v68
	v_pk_mul_f32 v[118:119], v[6:7], v[118:119] op_sel:[1,0] op_sel_hi:[0,0]
	v_pk_fma_f32 v[136:137], v[6:7], v[134:135], v[118:119] neg_lo:[0,0,1] neg_hi:[0,0,1]
	v_pk_fma_f32 v[118:119], v[6:7], v[134:135], v[118:119] op_sel_hi:[1,0,1]
	s_nop 0
	v_mov_b32_e32 v137, v119
	v_pk_add_f32 v[118:119], v[136:137], v[66:67]
	s_nop 0
	v_pk_mul_f32 v[134:135], v[6:7], v[118:119]
	v_pk_mul_f32 v[118:119], v[6:7], v[118:119] op_sel:[0,1] op_sel_hi:[1,0]
	v_sub_f32_e32 v121, v134, v135
	v_add_f32_e32 v118, v118, v119
	v_add_f32_e32 v118, v118, v65
	v_add_f32_e32 v134, v121, v64
	v_pk_mul_f32 v[118:119], v[6:7], v[118:119] op_sel:[1,0] op_sel_hi:[0,0]
	v_pk_fma_f32 v[136:137], v[6:7], v[134:135], v[118:119] neg_lo:[0,0,1] neg_hi:[0,0,1]
	v_pk_fma_f32 v[118:119], v[6:7], v[134:135], v[118:119] op_sel_hi:[1,0,1]
	s_nop 0
	v_mov_b32_e32 v137, v119
	v_pk_add_f32 v[118:119], v[136:137], v[62:63]
	s_nop 0
	v_pk_mul_f32 v[134:135], v[6:7], v[118:119]
	v_pk_mul_f32 v[118:119], v[6:7], v[118:119] op_sel:[0,1] op_sel_hi:[1,0]
	v_sub_f32_e32 v121, v134, v135
	v_add_f32_e32 v118, v118, v119
	v_add_f32_e32 v118, v118, v61
	v_add_f32_e32 v134, v121, v60
	v_pk_mul_f32 v[118:119], v[6:7], v[118:119] op_sel:[1,0] op_sel_hi:[0,0]
	v_pk_fma_f32 v[136:137], v[6:7], v[134:135], v[118:119] neg_lo:[0,0,1] neg_hi:[0,0,1]
	v_pk_fma_f32 v[118:119], v[6:7], v[134:135], v[118:119] op_sel_hi:[1,0,1]
	s_nop 0
	v_mov_b32_e32 v137, v119
	v_pk_add_f32 v[118:119], v[136:137], v[58:59]
	s_nop 0
	v_pk_mul_f32 v[134:135], v[6:7], v[118:119]
	v_pk_mul_f32 v[118:119], v[6:7], v[118:119] op_sel:[0,1] op_sel_hi:[1,0]
	v_sub_f32_e32 v121, v134, v135
	v_add_f32_e32 v118, v118, v119
	v_add_f32_e32 v118, v118, v55
	v_add_f32_e32 v134, v121, v54
	v_pk_mul_f32 v[118:119], v[6:7], v[118:119] op_sel:[1,0] op_sel_hi:[0,0]
	v_pk_fma_f32 v[136:137], v[6:7], v[134:135], v[118:119] neg_lo:[0,0,1] neg_hi:[0,0,1]
	v_pk_fma_f32 v[118:119], v[6:7], v[134:135], v[118:119] op_sel_hi:[1,0,1]
	s_nop 0
	v_mov_b32_e32 v137, v119
	v_pk_add_f32 v[118:119], v[136:137], v[56:57]
	s_nop 0
	v_pk_mul_f32 v[134:135], v[6:7], v[118:119]
	v_pk_mul_f32 v[118:119], v[6:7], v[118:119] op_sel:[0,1] op_sel_hi:[1,0]
	v_sub_f32_e32 v121, v134, v135
	v_add_f32_e32 v118, v118, v119
	v_add_f32_e32 v118, v118, v53
	v_add_f32_e32 v134, v121, v52
	v_pk_mul_f32 v[118:119], v[6:7], v[118:119] op_sel:[1,0] op_sel_hi:[0,0]
	v_pk_fma_f32 v[136:137], v[6:7], v[134:135], v[118:119] neg_lo:[0,0,1] neg_hi:[0,0,1]
	v_pk_fma_f32 v[118:119], v[6:7], v[134:135], v[118:119] op_sel_hi:[1,0,1]
	s_nop 0
	v_mov_b32_e32 v137, v119
	v_pk_add_f32 v[118:119], v[136:137], v[50:51]
	s_nop 0
	v_pk_mul_f32 v[134:135], v[6:7], v[118:119]
	v_pk_mul_f32 v[118:119], v[6:7], v[118:119] op_sel:[0,1] op_sel_hi:[1,0]
	v_sub_f32_e32 v121, v134, v135
	v_add_f32_e32 v118, v118, v119
	v_add_f32_e32 v118, v118, v49
	v_add_f32_e32 v134, v121, v48
	v_pk_mul_f32 v[118:119], v[6:7], v[118:119] op_sel:[1,0] op_sel_hi:[0,0]
	v_pk_fma_f32 v[136:137], v[6:7], v[134:135], v[118:119] neg_lo:[0,0,1] neg_hi:[0,0,1]
	v_pk_fma_f32 v[118:119], v[6:7], v[134:135], v[118:119] op_sel_hi:[1,0,1]
	s_nop 0
	v_mov_b32_e32 v137, v119
	v_pk_add_f32 v[118:119], v[136:137], v[46:47]
	s_nop 0
	v_pk_mul_f32 v[134:135], v[6:7], v[118:119]
	v_pk_mul_f32 v[118:119], v[6:7], v[118:119] op_sel:[0,1] op_sel_hi:[1,0]
	v_sub_f32_e32 v121, v134, v135
	v_add_f32_e32 v118, v118, v119
	v_add_f32_e32 v118, v118, v45
	v_add_f32_e32 v134, v121, v44
	v_pk_mul_f32 v[118:119], v[6:7], v[118:119] op_sel:[1,0] op_sel_hi:[0,0]
	v_pk_fma_f32 v[136:137], v[6:7], v[134:135], v[118:119] neg_lo:[0,0,1] neg_hi:[0,0,1]
	v_pk_fma_f32 v[118:119], v[6:7], v[134:135], v[118:119] op_sel_hi:[1,0,1]
	s_nop 0
	v_mov_b32_e32 v137, v119
	v_pk_add_f32 v[118:119], v[136:137], v[42:43]
	s_nop 0
	v_pk_mul_f32 v[134:135], v[6:7], v[118:119]
	v_pk_mul_f32 v[118:119], v[6:7], v[118:119] op_sel:[0,1] op_sel_hi:[1,0]
	v_sub_f32_e32 v121, v134, v135
	v_add_f32_e32 v118, v118, v119
	v_add_f32_e32 v118, v118, v41
	v_add_f32_e32 v134, v121, v40
	v_pk_mul_f32 v[118:119], v[6:7], v[118:119] op_sel:[1,0] op_sel_hi:[0,0]
	v_pk_fma_f32 v[136:137], v[6:7], v[134:135], v[118:119] neg_lo:[0,0,1] neg_hi:[0,0,1]
	v_pk_fma_f32 v[118:119], v[6:7], v[134:135], v[118:119] op_sel_hi:[1,0,1]
	s_nop 0
	v_mov_b32_e32 v137, v119
	v_pk_add_f32 v[118:119], v[136:137], v[38:39]
	s_nop 0
	v_pk_mul_f32 v[134:135], v[6:7], v[118:119]
	v_pk_mul_f32 v[118:119], v[6:7], v[118:119] op_sel:[0,1] op_sel_hi:[1,0]
	v_sub_f32_e32 v121, v134, v135
	v_add_f32_e32 v118, v118, v119
	v_add_f32_e32 v118, v118, v37
	v_add_f32_e32 v134, v121, v36
	v_pk_mul_f32 v[118:119], v[6:7], v[118:119] op_sel:[1,0] op_sel_hi:[0,0]
	v_pk_fma_f32 v[136:137], v[6:7], v[134:135], v[118:119] neg_lo:[0,0,1] neg_hi:[0,0,1]
	v_pk_fma_f32 v[118:119], v[6:7], v[134:135], v[118:119] op_sel_hi:[1,0,1]
	s_nop 0
	v_mov_b32_e32 v137, v119
	v_pk_add_f32 v[118:119], v[136:137], v[34:35]
	s_nop 0
	v_pk_mul_f32 v[134:135], v[6:7], v[118:119]
	v_pk_mul_f32 v[118:119], v[6:7], v[118:119] op_sel:[0,1] op_sel_hi:[1,0]
	v_sub_f32_e32 v121, v134, v135
	v_add_f32_e32 v118, v118, v119
	v_add_f32_e32 v118, v118, v33
	v_add_f32_e32 v134, v121, v32
	v_pk_mul_f32 v[118:119], v[6:7], v[118:119] op_sel:[1,0] op_sel_hi:[0,0]
	v_pk_fma_f32 v[136:137], v[6:7], v[134:135], v[118:119] neg_lo:[0,0,1] neg_hi:[0,0,1]
	v_pk_fma_f32 v[118:119], v[6:7], v[134:135], v[118:119] op_sel_hi:[1,0,1]
	s_nop 0
	v_mov_b32_e32 v137, v119
	v_pk_add_f32 v[118:119], v[136:137], v[30:31]
	s_nop 0
	v_pk_mul_f32 v[134:135], v[6:7], v[118:119]
	v_pk_mul_f32 v[118:119], v[6:7], v[118:119] op_sel:[0,1] op_sel_hi:[1,0]
	v_sub_f32_e32 v121, v134, v135
	v_add_f32_e32 v118, v118, v119
	v_add_f32_e32 v118, v118, v29
	v_add_f32_e32 v134, v121, v28
	v_pk_mul_f32 v[118:119], v[6:7], v[118:119] op_sel:[1,0] op_sel_hi:[0,0]
	v_pk_fma_f32 v[136:137], v[6:7], v[134:135], v[118:119] neg_lo:[0,0,1] neg_hi:[0,0,1]
	v_pk_fma_f32 v[118:119], v[6:7], v[134:135], v[118:119] op_sel_hi:[1,0,1]
	s_nop 0
	v_mov_b32_e32 v137, v119
	v_pk_add_f32 v[118:119], v[136:137], v[26:27]
	s_nop 0
	v_pk_mul_f32 v[134:135], v[6:7], v[118:119]
	v_pk_mul_f32 v[118:119], v[6:7], v[118:119] op_sel:[0,1] op_sel_hi:[1,0]
	v_sub_f32_e32 v121, v134, v135
	v_add_f32_e32 v118, v118, v119
	v_add_f32_e32 v118, v118, v25
	v_add_f32_e32 v134, v121, v24
	v_pk_mul_f32 v[118:119], v[6:7], v[118:119] op_sel:[1,0] op_sel_hi:[0,0]
	v_pk_fma_f32 v[136:137], v[6:7], v[134:135], v[118:119] neg_lo:[0,0,1] neg_hi:[0,0,1]
	v_pk_fma_f32 v[118:119], v[6:7], v[134:135], v[118:119] op_sel_hi:[1,0,1]
	s_nop 0
	v_mov_b32_e32 v137, v119
	v_pk_add_f32 v[118:119], v[136:137], v[22:23]
	s_nop 0
	v_pk_mul_f32 v[134:135], v[6:7], v[118:119]
	v_pk_mul_f32 v[118:119], v[6:7], v[118:119] op_sel:[0,1] op_sel_hi:[1,0]
	v_sub_f32_e32 v121, v134, v135
	v_add_f32_e32 v118, v118, v119
	v_add_f32_e32 v118, v118, v21
	v_add_f32_e32 v134, v121, v20
	v_pk_mul_f32 v[118:119], v[6:7], v[118:119] op_sel:[1,0] op_sel_hi:[0,0]
	v_pk_fma_f32 v[136:137], v[6:7], v[134:135], v[118:119] neg_lo:[0,0,1] neg_hi:[0,0,1]
	v_pk_fma_f32 v[118:119], v[6:7], v[134:135], v[118:119] op_sel_hi:[1,0,1]
	s_nop 0
	v_mov_b32_e32 v137, v119
	v_pk_add_f32 v[118:119], v[136:137], v[18:19]
	s_nop 0
	v_pk_mul_f32 v[134:135], v[6:7], v[118:119]
	v_pk_mul_f32 v[118:119], v[6:7], v[118:119] op_sel:[0,1] op_sel_hi:[1,0]
	v_sub_f32_e32 v121, v134, v135
	v_add_f32_e32 v118, v118, v119
	v_add_f32_e32 v118, v118, v17
	v_add_f32_e32 v134, v121, v16
	v_pk_mul_f32 v[118:119], v[6:7], v[118:119] op_sel:[1,0] op_sel_hi:[0,0]
	v_pk_fma_f32 v[136:137], v[6:7], v[134:135], v[118:119] neg_lo:[0,0,1] neg_hi:[0,0,1]
	v_pk_fma_f32 v[118:119], v[6:7], v[134:135], v[118:119] op_sel_hi:[1,0,1]
	s_nop 0
	v_mov_b32_e32 v137, v119
	v_pk_add_f32 v[118:119], v[136:137], v[14:15]
	s_nop 0
	v_pk_mul_f32 v[134:135], v[6:7], v[118:119]
	v_pk_mul_f32 v[118:119], v[6:7], v[118:119] op_sel:[0,1] op_sel_hi:[1,0]
	v_sub_f32_e32 v121, v134, v135
	v_add_f32_e32 v118, v118, v119
	v_add_f32_e32 v118, v118, v13
	v_add_f32_e32 v134, v121, v12
	v_pk_mul_f32 v[118:119], v[6:7], v[118:119] op_sel:[1,0] op_sel_hi:[0,0]
	v_pk_fma_f32 v[136:137], v[6:7], v[134:135], v[118:119] neg_lo:[0,0,1] neg_hi:[0,0,1]
	v_pk_fma_f32 v[118:119], v[6:7], v[134:135], v[118:119] op_sel_hi:[1,0,1]
	s_nop 0
	v_mov_b32_e32 v137, v119
	v_pk_add_f32 v[118:119], v[136:137], v[10:11]
	v_lshlrev_b32_e32 v136, 16, v133
	v_pk_mul_f32 v[134:135], v[6:7], v[118:119]
	v_pk_mul_f32 v[118:119], v[6:7], v[118:119] op_sel:[0,1] op_sel_hi:[1,0]
	v_sub_f32_e32 v121, v134, v135
	v_add_f32_e32 v118, v118, v119
	v_add_f32_e32 v118, v118, v9
	v_add_f32_e32 v134, v121, v8
	v_pk_mul_f32 v[118:119], v[6:7], v[118:119] op_sel:[1,0] op_sel_hi:[0,0]
	v_pk_fma_f32 v[138:139], v[6:7], v[134:135], v[118:119] neg_lo:[0,0,1] neg_hi:[0,0,1]
	v_pk_fma_f32 v[118:119], v[6:7], v[134:135], v[118:119] op_sel_hi:[1,0,1]
	v_and_b32_e32 v137, 0xffff0000, v133
	v_mov_b32_e32 v139, v119
	v_pk_add_f32 v[118:119], v[138:139], v[136:137]
	v_lshlrev_b32_e32 v121, 16, v132
	v_pk_mul_f32 v[134:135], v[6:7], v[118:119]
	v_pk_mul_f32 v[118:119], v[6:7], v[118:119] op_sel:[0,1] op_sel_hi:[1,0]
	v_sub_f32_e32 v134, v134, v135
	v_add_f32_e32 v118, v118, v119
	v_add_f32_e32 v118, v118, v140
	v_add_f32_e32 v134, v134, v121
	v_pk_mul_f32 v[118:119], v[6:7], v[118:119] op_sel:[1,0] op_sel_hi:[0,0]
	v_pk_fma_f32 v[138:139], v[6:7], v[134:135], v[118:119] neg_lo:[0,0,1] neg_hi:[0,0,1]
	v_pk_fma_f32 v[118:119], v[6:7], v[134:135], v[118:119] op_sel_hi:[1,0,1]
	v_lshlrev_b32_e32 v136, 16, v131
	v_and_b32_e32 v137, 0xffff0000, v131
	v_mov_b32_e32 v139, v119
	v_pk_add_f32 v[118:119], v[138:139], v[136:137]
	v_and_b32_e32 v140, 0xffff0000, v130
	v_pk_mul_f32 v[134:135], v[6:7], v[118:119]
	v_pk_mul_f32 v[118:119], v[6:7], v[118:119] op_sel:[0,1] op_sel_hi:[1,0]
	v_lshlrev_b32_e32 v121, 16, v130
	v_add_f32_e32 v118, v118, v119
	v_sub_f32_e32 v134, v134, v135
	v_add_f32_e32 v118, v118, v140
	v_add_f32_e32 v134, v134, v121
	v_pk_mul_f32 v[118:119], v[6:7], v[118:119] op_sel:[1,0] op_sel_hi:[0,0]
	v_pk_fma_f32 v[138:139], v[6:7], v[134:135], v[118:119] neg_lo:[0,0,1] neg_hi:[0,0,1]
	v_pk_fma_f32 v[118:119], v[6:7], v[134:135], v[118:119] op_sel_hi:[1,0,1]
	v_lshlrev_b32_e32 v136, 16, v129
	v_and_b32_e32 v137, 0xffff0000, v129
	v_mov_b32_e32 v139, v119
	v_pk_add_f32 v[118:119], v[138:139], v[136:137]
	v_and_b32_e32 v140, 0xffff0000, v128
	v_pk_mul_f32 v[134:135], v[6:7], v[118:119]
	v_pk_mul_f32 v[118:119], v[6:7], v[118:119] op_sel:[0,1] op_sel_hi:[1,0]
	v_lshlrev_b32_e32 v121, 16, v128
	v_add_f32_e32 v118, v118, v119
	v_sub_f32_e32 v134, v134, v135
	v_add_f32_e32 v118, v118, v140
	v_add_f32_e32 v134, v134, v121
	v_pk_mul_f32 v[118:119], v[6:7], v[118:119] op_sel:[1,0] op_sel_hi:[0,0]
	v_pk_fma_f32 v[138:139], v[6:7], v[134:135], v[118:119] neg_lo:[0,0,1] neg_hi:[0,0,1]
	v_pk_fma_f32 v[118:119], v[6:7], v[134:135], v[118:119] op_sel_hi:[1,0,1]
	v_lshlrev_b32_e32 v136, 16, v127
	v_and_b32_e32 v137, 0xffff0000, v127
	v_mov_b32_e32 v139, v119
	v_pk_add_f32 v[118:119], v[138:139], v[136:137]
	v_and_b32_e32 v140, 0xffff0000, v126
	v_pk_mul_f32 v[134:135], v[6:7], v[118:119]
	v_pk_mul_f32 v[118:119], v[6:7], v[118:119] op_sel:[0,1] op_sel_hi:[1,0]
	v_lshlrev_b32_e32 v121, 16, v126
	v_add_f32_e32 v118, v118, v119
	v_sub_f32_e32 v134, v134, v135
	v_add_f32_e32 v118, v118, v140
	v_add_f32_e32 v134, v134, v121
	v_pk_mul_f32 v[118:119], v[6:7], v[118:119] op_sel:[1,0] op_sel_hi:[0,0]
	v_pk_fma_f32 v[138:139], v[6:7], v[134:135], v[118:119] neg_lo:[0,0,1] neg_hi:[0,0,1]
	v_pk_fma_f32 v[118:119], v[6:7], v[134:135], v[118:119] op_sel_hi:[1,0,1]
	v_lshlrev_b32_e32 v136, 16, v125
	v_and_b32_e32 v137, 0xffff0000, v125
	v_mov_b32_e32 v139, v119
	v_pk_add_f32 v[118:119], v[138:139], v[136:137]
	v_and_b32_e32 v140, 0xffff0000, v124
	v_pk_mul_f32 v[134:135], v[6:7], v[118:119]
	v_pk_mul_f32 v[118:119], v[6:7], v[118:119] op_sel:[0,1] op_sel_hi:[1,0]
	v_lshlrev_b32_e32 v121, 16, v124
	v_add_f32_e32 v118, v118, v119
	v_sub_f32_e32 v134, v134, v135
	v_add_f32_e32 v118, v118, v140
	v_add_f32_e32 v134, v134, v121
	v_pk_mul_f32 v[118:119], v[6:7], v[118:119] op_sel:[1,0] op_sel_hi:[0,0]
	v_pk_fma_f32 v[138:139], v[6:7], v[134:135], v[118:119] op_sel_hi:[1,0,1]
	v_pk_fma_f32 v[118:119], v[6:7], v[134:135], v[118:119] op_sel_hi:[1,0,1] neg_lo:[0,0,1] neg_hi:[0,0,1]
	v_lshlrev_b32_e32 v136, 16, v120
	v_and_b32_e32 v137, 0xffff0000, v120
	v_mov_b32_e32 v119, v139
	v_pk_add_f32 v[118:119], v[118:119], v[136:137]
.LBB0_1304:
	s_andn2_b64 vcc, exec, s[2:3]
	s_cbranch_vccnz .LBB0_1306
	s_lshl_b32 s27, s27, 6
	s_and_b64 s[0:1], s[20:21], exec
	s_cselect_b32 s0, 0, 15
	s_lshl_b32 s1, s26, 5
	s_lshl_b32 s2, s25, 4
	s_or_b32 s1, s1, s2
	s_or_b32 s0, s0, s1
	s_ashr_i32 s1, s0, 31
	s_lshl_b64 s[2:3], s[0:1], 9
	v_readlane_b32 s20, v253, 34
	v_readlane_b32 s21, v253, 35
	s_add_u32 s2, s20, s2
	s_addc_u32 s3, s21, s3
	s_lshl_b32 s20, s27, 2
	s_add_u32 s2, s2, s20
	s_addc_u32 s3, s3, 0
	global_load_dword v119, v202, s[2:3] nt
	v_lshl_add_u64 v[116:117], s[2:3], 0, v[202:203]
	v_lshl_add_u64 v[116:117], v[116:117], 0, s[18:19]
	global_load_dword v147, v[116:117], off nt
	v_lshl_add_u64 v[116:117], v[116:117], 0, s[18:19]
	global_load_dword v146, v[116:117], off nt
	v_lshl_add_u64 v[116:117], v[116:117], 0, s[18:19]
	global_load_dword v145, v[116:117], off nt
	v_lshl_add_u64 v[116:117], v[116:117], 0, s[18:19]
	global_load_dword v144, v[116:117], off nt
	v_lshl_add_u64 v[116:117], v[116:117], 0, s[18:19]
	global_load_dword v143, v[116:117], off nt
	v_lshl_add_u64 v[116:117], v[116:117], 0, s[18:19]
	global_load_dword v142, v[116:117], off nt
	v_lshl_add_u64 v[116:117], v[116:117], 0, s[18:19]
	global_load_dword v141, v[116:117], off nt
	v_lshl_add_u64 v[116:117], v[116:117], 0, s[18:19]
	global_load_dword v140, v[116:117], off nt
	v_lshl_add_u64 v[116:117], v[116:117], 0, s[18:19]
	global_load_dword v139, v[116:117], off nt
	v_lshl_add_u64 v[116:117], v[116:117], 0, s[18:19]
	global_load_dword v138, v[116:117], off nt
	v_lshl_add_u64 v[116:117], v[116:117], 0, s[18:19]
	global_load_dword v137, v[116:117], off nt
	v_lshl_add_u64 v[116:117], v[116:117], 0, s[18:19]
	global_load_dword v136, v[116:117], off nt
	v_lshl_add_u64 v[116:117], v[116:117], 0, s[18:19]
	global_load_dword v135, v[116:117], off nt
	v_lshl_add_u64 v[116:117], v[116:117], 0, s[18:19]
	s_lshl_b64 s[0:1], s[0:1], 10
	v_readlane_b32 s26, v252, 26
	v_readlane_b32 s27, v252, 27
	s_add_u32 s0, s26, s0
	global_load_dword v134, v[116:117], off nt
	v_lshl_add_u64 v[116:117], v[116:117], 0, s[18:19]
	v_mul_f32_e32 v148, 0, v6
	v_mul_f32_e32 v149, 0, v7
	s_addc_u32 s1, s27, s1
	v_sub_f32_e32 v148, v148, v149
	v_fmac_f32_e32 v149, 0, v6
	s_add_u32 s0, s0, s20
	global_load_dword v121, v[116:117], off nt
	v_lshl_add_u64 v[116:117], v[116:117], 0, s[18:19]
	s_addc_u32 s1, s1, 0
	s_lshl_b64 s[18:19], s[16:17], 2
	v_lshl_add_u64 v[116:117], s[0:1], 0, v[202:203]
	global_store_dword v202, v203, s[0:1] offset:512
	v_lshl_add_u64 v[116:117], v[116:117], 0, s[18:19]
	s_mov_b64 s[0:1], 0x200
	v_lshl_add_u64 v[116:117], v[116:117], 0, s[0:1]
	s_waitcnt vmcnt(16)
	v_lshlrev_b32_e32 v118, 16, v119
	v_and_b32_e32 v119, 0xffff0000, v119
	v_pk_add_f32 v[118:119], v[148:149], v[118:119]
	s_nop 0
	v_and_b32_sdwa v149, v118, v1 dst_sel:DWORD dst_unused:UNUSED_PAD src0_sel:WORD_1 src1_sel:DWORD
	v_and_b32_sdwa v148, v119, v1 dst_sel:DWORD dst_unused:UNUSED_PAD src0_sel:WORD_1 src1_sel:DWORD
	v_add3_u32 v149, v118, v149, s53
	v_add3_u32 v148, v119, v148, s53
	v_lshrrev_b32_e32 v149, 16, v149
	v_pk_mul_f32 v[150:151], v[6:7], v[118:119] op_sel:[1,0]
	v_and_or_b32 v148, v148, s77, v149
	v_pk_fma_f32 v[152:153], v[6:7], v[118:119], v[150:151] op_sel:[0,0,1] op_sel_hi:[1,1,0] neg_lo:[0,0,1] neg_hi:[0,0,1]
	v_pk_fma_f32 v[118:119], v[6:7], v[118:119], v[150:151] op_sel:[0,0,1] op_sel_hi:[0,1,0]
	global_store_dword v[116:117], v148, off
	s_waitcnt vmcnt(16)
	v_lshlrev_b32_e32 v148, 16, v147
	v_and_b32_e32 v149, 0xffff0000, v147
	v_mov_b32_e32 v153, v119
	v_pk_add_f32 v[118:119], v[152:153], v[148:149]
	v_lshl_add_u64 v[116:117], v[116:117], 0, s[18:19]
	v_and_b32_sdwa v148, v118, v1 dst_sel:DWORD dst_unused:UNUSED_PAD src0_sel:WORD_1 src1_sel:DWORD
	v_and_b32_sdwa v147, v119, v1 dst_sel:DWORD dst_unused:UNUSED_PAD src0_sel:WORD_1 src1_sel:DWORD
	v_add3_u32 v148, v118, v148, s53
	v_add3_u32 v147, v119, v147, s53
	v_lshrrev_b32_e32 v148, 16, v148
	v_and_or_b32 v147, v147, s77, v148
	global_store_dword v[116:117], v147, off
	s_waitcnt vmcnt(16)
	v_lshlrev_b32_e32 v148, 16, v146
	v_and_b32_e32 v149, 0xffff0000, v146
	v_pk_mul_f32 v[146:147], v[6:7], v[118:119] op_sel:[1,0]
	v_lshl_add_u64 v[116:117], v[116:117], 0, s[18:19]
	v_pk_fma_f32 v[150:151], v[6:7], v[118:119], v[146:147] op_sel:[0,0,1] op_sel_hi:[1,1,0] neg_lo:[0,0,1] neg_hi:[0,0,1]
	v_pk_fma_f32 v[118:119], v[6:7], v[118:119], v[146:147] op_sel:[0,0,1] op_sel_hi:[0,1,0]
	v_mov_b32_e32 v151, v119
	v_pk_add_f32 v[118:119], v[150:151], v[148:149]
	s_nop 0
	v_and_b32_sdwa v147, v118, v1 dst_sel:DWORD dst_unused:UNUSED_PAD src0_sel:WORD_1 src1_sel:DWORD
	v_and_b32_sdwa v146, v119, v1 dst_sel:DWORD dst_unused:UNUSED_PAD src0_sel:WORD_1 src1_sel:DWORD
	v_add3_u32 v147, v118, v147, s53
	v_add3_u32 v146, v119, v146, s53
	v_lshrrev_b32_e32 v147, 16, v147
	v_pk_mul_f32 v[148:149], v[6:7], v[118:119] op_sel:[1,0]
	v_and_or_b32 v146, v146, s77, v147
	v_pk_fma_f32 v[150:151], v[6:7], v[118:119], v[148:149] op_sel:[0,0,1] op_sel_hi:[1,1,0] neg_lo:[0,0,1] neg_hi:[0,0,1]
	v_pk_fma_f32 v[118:119], v[6:7], v[118:119], v[148:149] op_sel:[0,0,1] op_sel_hi:[0,1,0]
	global_store_dword v[116:117], v146, off
	s_waitcnt vmcnt(16)
	v_lshlrev_b32_e32 v146, 16, v145
	v_and_b32_e32 v147, 0xffff0000, v145
	v_mov_b32_e32 v151, v119
	v_pk_add_f32 v[118:119], v[150:151], v[146:147]
	v_lshl_add_u64 v[116:117], v[116:117], 0, s[18:19]
	v_and_b32_sdwa v146, v118, v1 dst_sel:DWORD dst_unused:UNUSED_PAD src0_sel:WORD_1 src1_sel:DWORD
	v_and_b32_sdwa v145, v119, v1 dst_sel:DWORD dst_unused:UNUSED_PAD src0_sel:WORD_1 src1_sel:DWORD
	v_add3_u32 v146, v118, v146, s53
	v_add3_u32 v145, v119, v145, s53
	v_lshrrev_b32_e32 v146, 16, v146
	v_and_or_b32 v145, v145, s77, v146
	global_store_dword v[116:117], v145, off
	s_waitcnt vmcnt(16)
	v_lshlrev_b32_e32 v146, 16, v144
	v_and_b32_e32 v147, 0xffff0000, v144
	v_pk_mul_f32 v[144:145], v[6:7], v[118:119] op_sel:[1,0]
	v_lshl_add_u64 v[116:117], v[116:117], 0, s[18:19]
	v_pk_fma_f32 v[148:149], v[6:7], v[118:119], v[144:145] op_sel:[0,0,1] op_sel_hi:[1,1,0] neg_lo:[0,0,1] neg_hi:[0,0,1]
	v_pk_fma_f32 v[118:119], v[6:7], v[118:119], v[144:145] op_sel:[0,0,1] op_sel_hi:[0,1,0]
	v_mov_b32_e32 v149, v119
	v_pk_add_f32 v[118:119], v[148:149], v[146:147]
	s_nop 0
	v_and_b32_sdwa v145, v118, v1 dst_sel:DWORD dst_unused:UNUSED_PAD src0_sel:WORD_1 src1_sel:DWORD
	v_and_b32_sdwa v144, v119, v1 dst_sel:DWORD dst_unused:UNUSED_PAD src0_sel:WORD_1 src1_sel:DWORD
	v_add3_u32 v145, v118, v145, s53
	v_add3_u32 v144, v119, v144, s53
	v_lshrrev_b32_e32 v145, 16, v145
	v_pk_mul_f32 v[146:147], v[6:7], v[118:119] op_sel:[1,0]
	v_and_or_b32 v144, v144, s77, v145
	v_pk_fma_f32 v[148:149], v[6:7], v[118:119], v[146:147] op_sel:[0,0,1] op_sel_hi:[1,1,0] neg_lo:[0,0,1] neg_hi:[0,0,1]
	v_pk_fma_f32 v[118:119], v[6:7], v[118:119], v[146:147] op_sel:[0,0,1] op_sel_hi:[0,1,0]
	global_store_dword v[116:117], v144, off
	s_waitcnt vmcnt(16)
	v_lshlrev_b32_e32 v144, 16, v143
	v_and_b32_e32 v145, 0xffff0000, v143
	v_mov_b32_e32 v149, v119
	v_pk_add_f32 v[118:119], v[148:149], v[144:145]
	v_lshl_add_u64 v[116:117], v[116:117], 0, s[18:19]
	v_and_b32_sdwa v144, v118, v1 dst_sel:DWORD dst_unused:UNUSED_PAD src0_sel:WORD_1 src1_sel:DWORD
	v_and_b32_sdwa v143, v119, v1 dst_sel:DWORD dst_unused:UNUSED_PAD src0_sel:WORD_1 src1_sel:DWORD
	v_add3_u32 v144, v118, v144, s53
	v_add3_u32 v143, v119, v143, s53
	v_lshrrev_b32_e32 v144, 16, v144
	v_and_or_b32 v143, v143, s77, v144
	global_store_dword v[116:117], v143, off
	s_waitcnt vmcnt(16)
	v_lshlrev_b32_e32 v144, 16, v142
	v_and_b32_e32 v145, 0xffff0000, v142
	v_pk_mul_f32 v[142:143], v[6:7], v[118:119] op_sel:[1,0]
	v_lshl_add_u64 v[116:117], v[116:117], 0, s[18:19]
	v_pk_fma_f32 v[146:147], v[6:7], v[118:119], v[142:143] op_sel:[0,0,1] op_sel_hi:[1,1,0] neg_lo:[0,0,1] neg_hi:[0,0,1]
	v_pk_fma_f32 v[118:119], v[6:7], v[118:119], v[142:143] op_sel:[0,0,1] op_sel_hi:[0,1,0]
	v_mov_b32_e32 v147, v119
	v_pk_add_f32 v[118:119], v[146:147], v[144:145]
	s_nop 0
	v_and_b32_sdwa v143, v118, v1 dst_sel:DWORD dst_unused:UNUSED_PAD src0_sel:WORD_1 src1_sel:DWORD
	v_and_b32_sdwa v142, v119, v1 dst_sel:DWORD dst_unused:UNUSED_PAD src0_sel:WORD_1 src1_sel:DWORD
	v_add3_u32 v143, v118, v143, s53
	v_add3_u32 v142, v119, v142, s53
	v_lshrrev_b32_e32 v143, 16, v143
	v_pk_mul_f32 v[144:145], v[6:7], v[118:119] op_sel:[1,0]
	v_and_or_b32 v142, v142, s77, v143
	v_pk_fma_f32 v[146:147], v[6:7], v[118:119], v[144:145] op_sel:[0,0,1] op_sel_hi:[1,1,0] neg_lo:[0,0,1] neg_hi:[0,0,1]
	v_pk_fma_f32 v[118:119], v[6:7], v[118:119], v[144:145] op_sel:[0,0,1] op_sel_hi:[0,1,0]
	global_store_dword v[116:117], v142, off
	s_waitcnt vmcnt(16)
	v_lshlrev_b32_e32 v142, 16, v141
	v_and_b32_e32 v143, 0xffff0000, v141
	v_mov_b32_e32 v147, v119
	v_pk_add_f32 v[118:119], v[146:147], v[142:143]
	v_lshl_add_u64 v[116:117], v[116:117], 0, s[18:19]
	v_and_b32_sdwa v142, v118, v1 dst_sel:DWORD dst_unused:UNUSED_PAD src0_sel:WORD_1 src1_sel:DWORD
	v_and_b32_sdwa v141, v119, v1 dst_sel:DWORD dst_unused:UNUSED_PAD src0_sel:WORD_1 src1_sel:DWORD
	v_add3_u32 v142, v118, v142, s53
	v_add3_u32 v141, v119, v141, s53
	v_lshrrev_b32_e32 v142, 16, v142
	v_and_or_b32 v141, v141, s77, v142
	global_store_dword v[116:117], v141, off
	s_waitcnt vmcnt(16)
	v_lshlrev_b32_e32 v142, 16, v140
	v_and_b32_e32 v143, 0xffff0000, v140
	v_pk_mul_f32 v[140:141], v[6:7], v[118:119] op_sel:[1,0]
	v_lshl_add_u64 v[116:117], v[116:117], 0, s[18:19]
	v_pk_fma_f32 v[144:145], v[6:7], v[118:119], v[140:141] op_sel:[0,0,1] op_sel_hi:[1,1,0] neg_lo:[0,0,1] neg_hi:[0,0,1]
	v_pk_fma_f32 v[118:119], v[6:7], v[118:119], v[140:141] op_sel:[0,0,1] op_sel_hi:[0,1,0]
	v_mov_b32_e32 v145, v119
	v_pk_add_f32 v[118:119], v[144:145], v[142:143]
	s_nop 0
	v_and_b32_sdwa v141, v118, v1 dst_sel:DWORD dst_unused:UNUSED_PAD src0_sel:WORD_1 src1_sel:DWORD
	v_and_b32_sdwa v140, v119, v1 dst_sel:DWORD dst_unused:UNUSED_PAD src0_sel:WORD_1 src1_sel:DWORD
	v_add3_u32 v141, v118, v141, s53
	v_add3_u32 v140, v119, v140, s53
	v_lshrrev_b32_e32 v141, 16, v141
	v_pk_mul_f32 v[142:143], v[6:7], v[118:119] op_sel:[1,0]
	v_and_or_b32 v140, v140, s77, v141
	v_pk_fma_f32 v[144:145], v[6:7], v[118:119], v[142:143] op_sel:[0,0,1] op_sel_hi:[1,1,0] neg_lo:[0,0,1] neg_hi:[0,0,1]
	v_pk_fma_f32 v[118:119], v[6:7], v[118:119], v[142:143] op_sel:[0,0,1] op_sel_hi:[0,1,0]
	global_store_dword v[116:117], v140, off
	s_waitcnt vmcnt(16)
	v_lshlrev_b32_e32 v140, 16, v139
	v_and_b32_e32 v141, 0xffff0000, v139
	v_mov_b32_e32 v145, v119
	v_pk_add_f32 v[118:119], v[144:145], v[140:141]
	v_lshl_add_u64 v[116:117], v[116:117], 0, s[18:19]
	v_and_b32_sdwa v140, v118, v1 dst_sel:DWORD dst_unused:UNUSED_PAD src0_sel:WORD_1 src1_sel:DWORD
	v_and_b32_sdwa v139, v119, v1 dst_sel:DWORD dst_unused:UNUSED_PAD src0_sel:WORD_1 src1_sel:DWORD
	v_add3_u32 v140, v118, v140, s53
	v_add3_u32 v139, v119, v139, s53
	v_lshrrev_b32_e32 v140, 16, v140
	v_and_or_b32 v139, v139, s77, v140
	global_store_dword v[116:117], v139, off
	s_waitcnt vmcnt(16)
	v_lshlrev_b32_e32 v140, 16, v138
	v_and_b32_e32 v141, 0xffff0000, v138
	v_pk_mul_f32 v[138:139], v[6:7], v[118:119] op_sel:[1,0]
	v_lshl_add_u64 v[116:117], v[116:117], 0, s[18:19]
	v_pk_fma_f32 v[142:143], v[6:7], v[118:119], v[138:139] op_sel:[0,0,1] op_sel_hi:[1,1,0] neg_lo:[0,0,1] neg_hi:[0,0,1]
	v_pk_fma_f32 v[118:119], v[6:7], v[118:119], v[138:139] op_sel:[0,0,1] op_sel_hi:[0,1,0]
	v_mov_b32_e32 v143, v119
	v_pk_add_f32 v[118:119], v[142:143], v[140:141]
	s_nop 0
	v_and_b32_sdwa v139, v118, v1 dst_sel:DWORD dst_unused:UNUSED_PAD src0_sel:WORD_1 src1_sel:DWORD
	v_and_b32_sdwa v138, v119, v1 dst_sel:DWORD dst_unused:UNUSED_PAD src0_sel:WORD_1 src1_sel:DWORD
	v_add3_u32 v139, v118, v139, s53
	v_add3_u32 v138, v119, v138, s53
	v_lshrrev_b32_e32 v139, 16, v139
	v_pk_mul_f32 v[140:141], v[6:7], v[118:119] op_sel:[1,0]
	v_and_or_b32 v138, v138, s77, v139
	v_pk_fma_f32 v[142:143], v[6:7], v[118:119], v[140:141] op_sel:[0,0,1] op_sel_hi:[1,1,0] neg_lo:[0,0,1] neg_hi:[0,0,1]
	v_pk_fma_f32 v[118:119], v[6:7], v[118:119], v[140:141] op_sel:[0,0,1] op_sel_hi:[0,1,0]
	global_store_dword v[116:117], v138, off
	s_waitcnt vmcnt(16)
	v_lshlrev_b32_e32 v138, 16, v137
	v_and_b32_e32 v139, 0xffff0000, v137
	v_mov_b32_e32 v143, v119
	v_pk_add_f32 v[118:119], v[142:143], v[138:139]
	v_lshl_add_u64 v[116:117], v[116:117], 0, s[18:19]
	v_and_b32_sdwa v138, v118, v1 dst_sel:DWORD dst_unused:UNUSED_PAD src0_sel:WORD_1 src1_sel:DWORD
	v_and_b32_sdwa v137, v119, v1 dst_sel:DWORD dst_unused:UNUSED_PAD src0_sel:WORD_1 src1_sel:DWORD
	v_add3_u32 v138, v118, v138, s53
	v_add3_u32 v137, v119, v137, s53
	v_lshrrev_b32_e32 v138, 16, v138
	v_and_or_b32 v137, v137, s77, v138
	global_store_dword v[116:117], v137, off
	s_waitcnt vmcnt(16)
	v_lshlrev_b32_e32 v138, 16, v136
	v_and_b32_e32 v139, 0xffff0000, v136
	v_pk_mul_f32 v[136:137], v[6:7], v[118:119] op_sel:[1,0]
	v_lshl_add_u64 v[116:117], v[116:117], 0, s[18:19]
	v_pk_fma_f32 v[140:141], v[6:7], v[118:119], v[136:137] op_sel:[0,0,1] op_sel_hi:[1,1,0] neg_lo:[0,0,1] neg_hi:[0,0,1]
	v_pk_fma_f32 v[118:119], v[6:7], v[118:119], v[136:137] op_sel:[0,0,1] op_sel_hi:[0,1,0]
	v_mov_b32_e32 v141, v119
	v_pk_add_f32 v[118:119], v[140:141], v[138:139]
	s_nop 0
	v_and_b32_sdwa v137, v118, v1 dst_sel:DWORD dst_unused:UNUSED_PAD src0_sel:WORD_1 src1_sel:DWORD
	v_and_b32_sdwa v136, v119, v1 dst_sel:DWORD dst_unused:UNUSED_PAD src0_sel:WORD_1 src1_sel:DWORD
	v_add3_u32 v137, v118, v137, s53
	v_add3_u32 v136, v119, v136, s53
	v_lshrrev_b32_e32 v137, 16, v137
	v_pk_mul_f32 v[138:139], v[6:7], v[118:119] op_sel:[1,0]
	v_and_or_b32 v136, v136, s77, v137
	v_pk_fma_f32 v[140:141], v[6:7], v[118:119], v[138:139] op_sel:[0,0,1] op_sel_hi:[1,1,0] neg_lo:[0,0,1] neg_hi:[0,0,1]
	v_pk_fma_f32 v[118:119], v[6:7], v[118:119], v[138:139] op_sel:[0,0,1] op_sel_hi:[0,1,0]
	global_store_dword v[116:117], v136, off
	s_waitcnt vmcnt(16)
	v_lshlrev_b32_e32 v136, 16, v135
	v_and_b32_e32 v137, 0xffff0000, v135
	v_mov_b32_e32 v141, v119
	v_pk_add_f32 v[118:119], v[140:141], v[136:137]
	v_lshl_add_u64 v[116:117], v[116:117], 0, s[18:19]
	v_and_b32_sdwa v136, v118, v1 dst_sel:DWORD dst_unused:UNUSED_PAD src0_sel:WORD_1 src1_sel:DWORD
	v_and_b32_sdwa v135, v119, v1 dst_sel:DWORD dst_unused:UNUSED_PAD src0_sel:WORD_1 src1_sel:DWORD
	v_add3_u32 v136, v118, v136, s53
	v_add3_u32 v135, v119, v135, s53
	v_lshrrev_b32_e32 v136, 16, v136
	v_and_or_b32 v135, v135, s77, v136
	global_store_dword v[116:117], v135, off
	s_waitcnt vmcnt(16)
	v_lshlrev_b32_e32 v136, 16, v134
	v_and_b32_e32 v137, 0xffff0000, v134
	v_pk_mul_f32 v[134:135], v[6:7], v[118:119] op_sel:[1,0]
	v_lshl_add_u64 v[116:117], v[116:117], 0, s[18:19]
	v_pk_fma_f32 v[138:139], v[6:7], v[118:119], v[134:135] op_sel:[0,0,1] op_sel_hi:[1,1,0] neg_lo:[0,0,1] neg_hi:[0,0,1]
	v_pk_fma_f32 v[118:119], v[6:7], v[118:119], v[134:135] op_sel:[0,0,1] op_sel_hi:[0,1,0]
	v_mov_b32_e32 v139, v119
	v_pk_add_f32 v[118:119], v[138:139], v[136:137]
	s_nop 0
	v_and_b32_sdwa v135, v118, v1 dst_sel:DWORD dst_unused:UNUSED_PAD src0_sel:WORD_1 src1_sel:DWORD
	v_and_b32_sdwa v134, v119, v1 dst_sel:DWORD dst_unused:UNUSED_PAD src0_sel:WORD_1 src1_sel:DWORD
	v_add3_u32 v135, v118, v135, s53
	v_add3_u32 v134, v119, v134, s53
	v_lshrrev_b32_e32 v135, 16, v135
	v_and_or_b32 v134, v134, s77, v135
	global_store_dword v[116:117], v134, off
	v_lshl_add_u64 v[116:117], v[116:117], 0, s[18:19]
	s_waitcnt vmcnt(16)
	v_lshlrev_b32_e32 v134, 16, v121
	v_pk_mul_f32 v[116:117], v[6:7], v[118:119]
	v_pk_mul_f32 v[118:119], v[6:7], v[118:119] op_sel:[0,1] op_sel_hi:[1,0]
	v_sub_f32_e32 v116, v116, v117
	v_and_b32_e32 v121, 0xffff0000, v121
	v_add_f32_e32 v116, v116, v134
	v_add_f32_e32 v117, v118, v119
	v_add_f32_e32 v118, v117, v121
	v_bfe_u32 v117, v116, 16, 1
	v_add3_u32 v117, v116, v117, s53
	v_bfe_u32 v119, v118, 16, 1
	v_lshrrev_b32_e32 v117, 16, v117
	v_add3_u32 v119, v118, v119, s53
	v_and_or_b32 v117, v119, s77, v117
	v_pk_mul_f32 v[118:119], v[6:7], v[118:119] op_sel:[1,0] op_sel_hi:[0,0]
	global_store_dword v[114:115], v117, off offset:512
	v_pk_fma_f32 v[134:135], v[6:7], v[116:117], v[118:119] neg_lo:[0,0,1] neg_hi:[0,0,1]
	v_pk_fma_f32 v[116:117], v[6:7], v[116:117], v[118:119] op_sel_hi:[1,0,1]
	v_lshl_add_u64 v[114:115], v[114:115], 0, s[18:19]
	v_mov_b32_e32 v135, v117
	v_pk_add_f32 v[116:117], v[134:135], v[112:113]
	v_lshl_add_u64 v[114:115], v[114:115], 0, s[0:1]
	v_and_b32_sdwa v119, v116, v1 dst_sel:DWORD dst_unused:UNUSED_PAD src0_sel:WORD_1 src1_sel:DWORD
	v_and_b32_sdwa v118, v117, v1 dst_sel:DWORD dst_unused:UNUSED_PAD src0_sel:WORD_1 src1_sel:DWORD
	v_add3_u32 v119, v116, v119, s53
	v_add3_u32 v118, v117, v118, s53
	v_lshrrev_b32_e32 v119, 16, v119
	v_and_or_b32 v118, v118, s77, v119
	global_store_dword v[114:115], v118, off
	v_pk_mul_f32 v[118:119], v[6:7], v[116:117] op_sel:[1,0]
	v_lshl_add_u64 v[114:115], v[114:115], 0, s[18:19]
	v_pk_fma_f32 v[134:135], v[6:7], v[116:117], v[118:119] op_sel:[0,0,1] op_sel_hi:[1,1,0] neg_lo:[0,0,1] neg_hi:[0,0,1]
	v_pk_fma_f32 v[116:117], v[6:7], v[116:117], v[118:119] op_sel:[0,0,1] op_sel_hi:[0,1,0]
	v_mov_b32_e32 v135, v117
	v_pk_add_f32 v[116:117], v[134:135], v[110:111]
	s_nop 0
	v_and_b32_sdwa v119, v116, v1 dst_sel:DWORD dst_unused:UNUSED_PAD src0_sel:WORD_1 src1_sel:DWORD
	v_and_b32_sdwa v118, v117, v1 dst_sel:DWORD dst_unused:UNUSED_PAD src0_sel:WORD_1 src1_sel:DWORD
	v_add3_u32 v119, v116, v119, s53
	v_add3_u32 v118, v117, v118, s53
	v_lshrrev_b32_e32 v119, 16, v119
	v_and_or_b32 v118, v118, s77, v119
	global_store_dword v[114:115], v118, off
	v_pk_mul_f32 v[118:119], v[6:7], v[116:117] op_sel:[1,0]
	v_lshl_add_u64 v[114:115], v[114:115], 0, s[18:19]
	v_pk_fma_f32 v[134:135], v[6:7], v[116:117], v[118:119] op_sel:[0,0,1] op_sel_hi:[1,1,0] neg_lo:[0,0,1] neg_hi:[0,0,1]
	v_pk_fma_f32 v[116:117], v[6:7], v[116:117], v[118:119] op_sel:[0,0,1] op_sel_hi:[0,1,0]
	v_mov_b32_e32 v135, v117
	v_pk_add_f32 v[116:117], v[134:135], v[108:109]
	s_nop 0
	v_and_b32_sdwa v119, v116, v1 dst_sel:DWORD dst_unused:UNUSED_PAD src0_sel:WORD_1 src1_sel:DWORD
	v_and_b32_sdwa v118, v117, v1 dst_sel:DWORD dst_unused:UNUSED_PAD src0_sel:WORD_1 src1_sel:DWORD
	v_add3_u32 v119, v116, v119, s53
	v_add3_u32 v118, v117, v118, s53
	v_lshrrev_b32_e32 v119, 16, v119
	v_and_or_b32 v118, v118, s77, v119
	global_store_dword v[114:115], v118, off
	v_pk_mul_f32 v[118:119], v[6:7], v[116:117] op_sel:[1,0]
	v_lshl_add_u64 v[114:115], v[114:115], 0, s[18:19]
	v_pk_fma_f32 v[134:135], v[6:7], v[116:117], v[118:119] op_sel:[0,0,1] op_sel_hi:[1,1,0] neg_lo:[0,0,1] neg_hi:[0,0,1]
	v_pk_fma_f32 v[116:117], v[6:7], v[116:117], v[118:119] op_sel:[0,0,1] op_sel_hi:[0,1,0]
	v_mov_b32_e32 v135, v117
	v_pk_add_f32 v[116:117], v[134:135], v[106:107]
	s_nop 0
	v_and_b32_sdwa v119, v116, v1 dst_sel:DWORD dst_unused:UNUSED_PAD src0_sel:WORD_1 src1_sel:DWORD
	v_and_b32_sdwa v118, v117, v1 dst_sel:DWORD dst_unused:UNUSED_PAD src0_sel:WORD_1 src1_sel:DWORD
	v_add3_u32 v119, v116, v119, s53
	v_add3_u32 v118, v117, v118, s53
	v_lshrrev_b32_e32 v119, 16, v119
	v_and_or_b32 v118, v118, s77, v119
	global_store_dword v[114:115], v118, off
	v_pk_mul_f32 v[118:119], v[6:7], v[116:117] op_sel:[1,0]
	v_lshl_add_u64 v[114:115], v[114:115], 0, s[18:19]
	v_pk_fma_f32 v[134:135], v[6:7], v[116:117], v[118:119] op_sel:[0,0,1] op_sel_hi:[1,1,0] neg_lo:[0,0,1] neg_hi:[0,0,1]
	v_pk_fma_f32 v[116:117], v[6:7], v[116:117], v[118:119] op_sel:[0,0,1] op_sel_hi:[0,1,0]
	v_mov_b32_e32 v135, v117
	v_pk_add_f32 v[116:117], v[134:135], v[104:105]
	s_nop 0
	v_and_b32_sdwa v119, v116, v1 dst_sel:DWORD dst_unused:UNUSED_PAD src0_sel:WORD_1 src1_sel:DWORD
	v_and_b32_sdwa v118, v117, v1 dst_sel:DWORD dst_unused:UNUSED_PAD src0_sel:WORD_1 src1_sel:DWORD
	v_add3_u32 v119, v116, v119, s53
	v_add3_u32 v118, v117, v118, s53
	v_lshrrev_b32_e32 v119, 16, v119
	v_and_or_b32 v118, v118, s77, v119
	global_store_dword v[114:115], v118, off
	v_pk_mul_f32 v[118:119], v[6:7], v[116:117] op_sel:[1,0]
	v_lshl_add_u64 v[114:115], v[114:115], 0, s[18:19]
	v_pk_fma_f32 v[134:135], v[6:7], v[116:117], v[118:119] op_sel:[0,0,1] op_sel_hi:[1,1,0] neg_lo:[0,0,1] neg_hi:[0,0,1]
	v_pk_fma_f32 v[116:117], v[6:7], v[116:117], v[118:119] op_sel:[0,0,1] op_sel_hi:[0,1,0]
	v_mov_b32_e32 v135, v117
	v_pk_add_f32 v[116:117], v[134:135], v[102:103]
	s_nop 0
	v_and_b32_sdwa v119, v116, v1 dst_sel:DWORD dst_unused:UNUSED_PAD src0_sel:WORD_1 src1_sel:DWORD
	v_and_b32_sdwa v118, v117, v1 dst_sel:DWORD dst_unused:UNUSED_PAD src0_sel:WORD_1 src1_sel:DWORD
	v_add3_u32 v119, v116, v119, s53
	v_add3_u32 v118, v117, v118, s53
	v_lshrrev_b32_e32 v119, 16, v119
	v_and_or_b32 v118, v118, s77, v119
	global_store_dword v[114:115], v118, off
	v_pk_mul_f32 v[118:119], v[6:7], v[116:117] op_sel:[1,0]
	v_lshl_add_u64 v[114:115], v[114:115], 0, s[18:19]
	v_pk_fma_f32 v[134:135], v[6:7], v[116:117], v[118:119] op_sel:[0,0,1] op_sel_hi:[1,1,0] neg_lo:[0,0,1] neg_hi:[0,0,1]
	v_pk_fma_f32 v[116:117], v[6:7], v[116:117], v[118:119] op_sel:[0,0,1] op_sel_hi:[0,1,0]
	v_mov_b32_e32 v135, v117
	v_pk_add_f32 v[116:117], v[134:135], v[100:101]
	s_nop 0
	v_and_b32_sdwa v119, v116, v1 dst_sel:DWORD dst_unused:UNUSED_PAD src0_sel:WORD_1 src1_sel:DWORD
	v_and_b32_sdwa v118, v117, v1 dst_sel:DWORD dst_unused:UNUSED_PAD src0_sel:WORD_1 src1_sel:DWORD
	v_add3_u32 v119, v116, v119, s53
	v_add3_u32 v118, v117, v118, s53
	v_lshrrev_b32_e32 v119, 16, v119
	v_and_or_b32 v118, v118, s77, v119
	global_store_dword v[114:115], v118, off
	v_pk_mul_f32 v[118:119], v[6:7], v[116:117] op_sel:[1,0]
	v_lshl_add_u64 v[114:115], v[114:115], 0, s[18:19]
	v_pk_fma_f32 v[134:135], v[6:7], v[116:117], v[118:119] op_sel:[0,0,1] op_sel_hi:[1,1,0] neg_lo:[0,0,1] neg_hi:[0,0,1]
	v_pk_fma_f32 v[116:117], v[6:7], v[116:117], v[118:119] op_sel:[0,0,1] op_sel_hi:[0,1,0]
	v_mov_b32_e32 v135, v117
	v_pk_add_f32 v[116:117], v[134:135], v[98:99]
	s_nop 0
	v_and_b32_sdwa v119, v116, v1 dst_sel:DWORD dst_unused:UNUSED_PAD src0_sel:WORD_1 src1_sel:DWORD
	v_and_b32_sdwa v118, v117, v1 dst_sel:DWORD dst_unused:UNUSED_PAD src0_sel:WORD_1 src1_sel:DWORD
	v_add3_u32 v119, v116, v119, s53
	v_add3_u32 v118, v117, v118, s53
	v_lshrrev_b32_e32 v119, 16, v119
	v_and_or_b32 v118, v118, s77, v119
	global_store_dword v[114:115], v118, off
	v_pk_mul_f32 v[118:119], v[6:7], v[116:117] op_sel:[1,0]
	v_lshl_add_u64 v[114:115], v[114:115], 0, s[18:19]
	v_pk_fma_f32 v[134:135], v[6:7], v[116:117], v[118:119] op_sel:[0,0,1] op_sel_hi:[1,1,0] neg_lo:[0,0,1] neg_hi:[0,0,1]
	v_pk_fma_f32 v[116:117], v[6:7], v[116:117], v[118:119] op_sel:[0,0,1] op_sel_hi:[0,1,0]
	v_mov_b32_e32 v135, v117
	v_pk_add_f32 v[116:117], v[134:135], v[96:97]
	s_nop 0
	v_and_b32_sdwa v119, v116, v1 dst_sel:DWORD dst_unused:UNUSED_PAD src0_sel:WORD_1 src1_sel:DWORD
	v_and_b32_sdwa v118, v117, v1 dst_sel:DWORD dst_unused:UNUSED_PAD src0_sel:WORD_1 src1_sel:DWORD
	v_add3_u32 v119, v116, v119, s53
	v_add3_u32 v118, v117, v118, s53
	v_lshrrev_b32_e32 v119, 16, v119
	v_and_or_b32 v118, v118, s77, v119
	global_store_dword v[114:115], v118, off
	v_pk_mul_f32 v[118:119], v[6:7], v[116:117] op_sel:[1,0]
	v_lshl_add_u64 v[114:115], v[114:115], 0, s[18:19]
	v_pk_fma_f32 v[134:135], v[6:7], v[116:117], v[118:119] op_sel:[0,0,1] op_sel_hi:[1,1,0] neg_lo:[0,0,1] neg_hi:[0,0,1]
	v_pk_fma_f32 v[116:117], v[6:7], v[116:117], v[118:119] op_sel:[0,0,1] op_sel_hi:[0,1,0]
	v_mov_b32_e32 v135, v117
	v_pk_add_f32 v[116:117], v[134:135], v[94:95]
	s_nop 0
	v_and_b32_sdwa v119, v116, v1 dst_sel:DWORD dst_unused:UNUSED_PAD src0_sel:WORD_1 src1_sel:DWORD
	v_and_b32_sdwa v118, v117, v1 dst_sel:DWORD dst_unused:UNUSED_PAD src0_sel:WORD_1 src1_sel:DWORD
	v_add3_u32 v119, v116, v119, s53
	v_add3_u32 v118, v117, v118, s53
	v_lshrrev_b32_e32 v119, 16, v119
	v_and_or_b32 v118, v118, s77, v119
	global_store_dword v[114:115], v118, off
	v_pk_mul_f32 v[118:119], v[6:7], v[116:117] op_sel:[1,0]
	v_lshl_add_u64 v[114:115], v[114:115], 0, s[18:19]
	v_pk_fma_f32 v[134:135], v[6:7], v[116:117], v[118:119] op_sel:[0,0,1] op_sel_hi:[1,1,0] neg_lo:[0,0,1] neg_hi:[0,0,1]
	v_pk_fma_f32 v[116:117], v[6:7], v[116:117], v[118:119] op_sel:[0,0,1] op_sel_hi:[0,1,0]
	v_mov_b32_e32 v135, v117
	v_pk_add_f32 v[116:117], v[134:135], v[92:93]
	s_nop 0
	v_and_b32_sdwa v119, v116, v1 dst_sel:DWORD dst_unused:UNUSED_PAD src0_sel:WORD_1 src1_sel:DWORD
	v_and_b32_sdwa v118, v117, v1 dst_sel:DWORD dst_unused:UNUSED_PAD src0_sel:WORD_1 src1_sel:DWORD
	v_add3_u32 v119, v116, v119, s53
	v_add3_u32 v118, v117, v118, s53
	v_lshrrev_b32_e32 v119, 16, v119
	v_and_or_b32 v118, v118, s77, v119
	global_store_dword v[114:115], v118, off
	v_pk_mul_f32 v[118:119], v[6:7], v[116:117] op_sel:[1,0]
	v_lshl_add_u64 v[114:115], v[114:115], 0, s[18:19]
	v_pk_fma_f32 v[134:135], v[6:7], v[116:117], v[118:119] op_sel:[0,0,1] op_sel_hi:[1,1,0] neg_lo:[0,0,1] neg_hi:[0,0,1]
	v_pk_fma_f32 v[116:117], v[6:7], v[116:117], v[118:119] op_sel:[0,0,1] op_sel_hi:[0,1,0]
	v_mov_b32_e32 v135, v117
	v_pk_add_f32 v[116:117], v[134:135], v[90:91]
	s_nop 0
	v_and_b32_sdwa v119, v116, v1 dst_sel:DWORD dst_unused:UNUSED_PAD src0_sel:WORD_1 src1_sel:DWORD
	v_and_b32_sdwa v118, v117, v1 dst_sel:DWORD dst_unused:UNUSED_PAD src0_sel:WORD_1 src1_sel:DWORD
	v_add3_u32 v119, v116, v119, s53
	v_add3_u32 v118, v117, v118, s53
	v_lshrrev_b32_e32 v119, 16, v119
	v_and_or_b32 v118, v118, s77, v119
	global_store_dword v[114:115], v118, off
	v_pk_mul_f32 v[118:119], v[6:7], v[116:117] op_sel:[1,0]
	v_lshl_add_u64 v[114:115], v[114:115], 0, s[18:19]
	v_pk_fma_f32 v[134:135], v[6:7], v[116:117], v[118:119] op_sel:[0,0,1] op_sel_hi:[1,1,0] neg_lo:[0,0,1] neg_hi:[0,0,1]
	v_pk_fma_f32 v[116:117], v[6:7], v[116:117], v[118:119] op_sel:[0,0,1] op_sel_hi:[0,1,0]
	v_mov_b32_e32 v135, v117
	v_pk_add_f32 v[116:117], v[134:135], v[88:89]
	s_nop 0
	v_and_b32_sdwa v119, v116, v1 dst_sel:DWORD dst_unused:UNUSED_PAD src0_sel:WORD_1 src1_sel:DWORD
	v_and_b32_sdwa v118, v117, v1 dst_sel:DWORD dst_unused:UNUSED_PAD src0_sel:WORD_1 src1_sel:DWORD
	v_add3_u32 v119, v116, v119, s53
	v_add3_u32 v118, v117, v118, s53
	v_lshrrev_b32_e32 v119, 16, v119
	v_and_or_b32 v118, v118, s77, v119
	global_store_dword v[114:115], v118, off
	v_pk_mul_f32 v[118:119], v[6:7], v[116:117] op_sel:[1,0]
	v_lshl_add_u64 v[114:115], v[114:115], 0, s[18:19]
	v_pk_fma_f32 v[134:135], v[6:7], v[116:117], v[118:119] op_sel:[0,0,1] op_sel_hi:[1,1,0] neg_lo:[0,0,1] neg_hi:[0,0,1]
	v_pk_fma_f32 v[116:117], v[6:7], v[116:117], v[118:119] op_sel:[0,0,1] op_sel_hi:[0,1,0]
	v_mov_b32_e32 v135, v117
	v_pk_add_f32 v[116:117], v[134:135], v[86:87]
	s_nop 0
	v_and_b32_sdwa v119, v116, v1 dst_sel:DWORD dst_unused:UNUSED_PAD src0_sel:WORD_1 src1_sel:DWORD
	v_and_b32_sdwa v118, v117, v1 dst_sel:DWORD dst_unused:UNUSED_PAD src0_sel:WORD_1 src1_sel:DWORD
	v_add3_u32 v119, v116, v119, s53
	v_add3_u32 v118, v117, v118, s53
	v_lshrrev_b32_e32 v119, 16, v119
	v_and_or_b32 v118, v118, s77, v119
	global_store_dword v[114:115], v118, off
	v_pk_mul_f32 v[118:119], v[6:7], v[116:117] op_sel:[1,0]
	v_lshl_add_u64 v[114:115], v[114:115], 0, s[18:19]
	v_pk_fma_f32 v[134:135], v[6:7], v[116:117], v[118:119] op_sel:[0,0,1] op_sel_hi:[1,1,0] neg_lo:[0,0,1] neg_hi:[0,0,1]
	v_pk_fma_f32 v[116:117], v[6:7], v[116:117], v[118:119] op_sel:[0,0,1] op_sel_hi:[0,1,0]
	v_mov_b32_e32 v135, v117
	v_pk_add_f32 v[116:117], v[134:135], v[84:85]
	s_nop 0
	v_and_b32_sdwa v119, v116, v1 dst_sel:DWORD dst_unused:UNUSED_PAD src0_sel:WORD_1 src1_sel:DWORD
	v_and_b32_sdwa v118, v117, v1 dst_sel:DWORD dst_unused:UNUSED_PAD src0_sel:WORD_1 src1_sel:DWORD
	v_add3_u32 v119, v116, v119, s53
	v_add3_u32 v118, v117, v118, s53
	v_lshrrev_b32_e32 v119, 16, v119
	v_and_or_b32 v118, v118, s77, v119
	global_store_dword v[114:115], v118, off
	v_pk_mul_f32 v[118:119], v[6:7], v[116:117] op_sel:[1,0]
	v_lshl_add_u64 v[114:115], v[114:115], 0, s[18:19]
	v_pk_fma_f32 v[134:135], v[6:7], v[116:117], v[118:119] op_sel:[0,0,1] op_sel_hi:[1,1,0] neg_lo:[0,0,1] neg_hi:[0,0,1]
	v_pk_fma_f32 v[116:117], v[6:7], v[116:117], v[118:119] op_sel:[0,0,1] op_sel_hi:[0,1,0]
	v_mov_b32_e32 v135, v117
	v_pk_add_f32 v[116:117], v[134:135], v[82:83]
	s_nop 0
	v_and_b32_sdwa v119, v116, v1 dst_sel:DWORD dst_unused:UNUSED_PAD src0_sel:WORD_1 src1_sel:DWORD
	v_and_b32_sdwa v118, v117, v1 dst_sel:DWORD dst_unused:UNUSED_PAD src0_sel:WORD_1 src1_sel:DWORD
	v_add3_u32 v119, v116, v119, s53
	v_add3_u32 v118, v117, v118, s53
	v_lshrrev_b32_e32 v119, 16, v119
	v_and_or_b32 v118, v118, s77, v119
	global_store_dword v[114:115], v118, off
	v_pk_mul_f32 v[118:119], v[6:7], v[116:117] op_sel:[1,0]
	v_lshl_add_u64 v[114:115], v[114:115], 0, s[18:19]
	v_pk_fma_f32 v[134:135], v[6:7], v[116:117], v[118:119] op_sel:[0,0,1] op_sel_hi:[1,1,0] neg_lo:[0,0,1] neg_hi:[0,0,1]
	v_pk_fma_f32 v[116:117], v[6:7], v[116:117], v[118:119] op_sel:[0,0,1] op_sel_hi:[0,1,0]
	v_mov_b32_e32 v135, v117
	v_pk_add_f32 v[116:117], v[134:135], v[80:81]
	s_nop 0
	v_and_b32_sdwa v119, v116, v1 dst_sel:DWORD dst_unused:UNUSED_PAD src0_sel:WORD_1 src1_sel:DWORD
	v_and_b32_sdwa v118, v117, v1 dst_sel:DWORD dst_unused:UNUSED_PAD src0_sel:WORD_1 src1_sel:DWORD
	v_add3_u32 v119, v116, v119, s53
	v_add3_u32 v118, v117, v118, s53
	v_lshrrev_b32_e32 v119, 16, v119
	v_and_or_b32 v118, v118, s77, v119
	global_store_dword v[114:115], v118, off
	v_pk_mul_f32 v[118:119], v[6:7], v[116:117] op_sel:[1,0]
	v_lshl_add_u64 v[114:115], v[114:115], 0, s[18:19]
	v_pk_fma_f32 v[134:135], v[6:7], v[116:117], v[118:119] op_sel:[0,0,1] op_sel_hi:[1,1,0] neg_lo:[0,0,1] neg_hi:[0,0,1]
	v_pk_fma_f32 v[116:117], v[6:7], v[116:117], v[118:119] op_sel:[0,0,1] op_sel_hi:[0,1,0]
	v_mov_b32_e32 v135, v117
	v_pk_add_f32 v[116:117], v[134:135], v[78:79]
	s_nop 0
	v_and_b32_sdwa v119, v116, v1 dst_sel:DWORD dst_unused:UNUSED_PAD src0_sel:WORD_1 src1_sel:DWORD
	v_and_b32_sdwa v118, v117, v1 dst_sel:DWORD dst_unused:UNUSED_PAD src0_sel:WORD_1 src1_sel:DWORD
	v_add3_u32 v119, v116, v119, s53
	v_add3_u32 v118, v117, v118, s53
	v_lshrrev_b32_e32 v119, 16, v119
	v_and_or_b32 v118, v118, s77, v119
	global_store_dword v[114:115], v118, off
	v_pk_mul_f32 v[118:119], v[6:7], v[116:117] op_sel:[1,0]
	v_lshl_add_u64 v[114:115], v[114:115], 0, s[18:19]
	v_pk_fma_f32 v[134:135], v[6:7], v[116:117], v[118:119] op_sel:[0,0,1] op_sel_hi:[1,1,0] neg_lo:[0,0,1] neg_hi:[0,0,1]
	v_pk_fma_f32 v[116:117], v[6:7], v[116:117], v[118:119] op_sel:[0,0,1] op_sel_hi:[0,1,0]
	v_mov_b32_e32 v135, v117
	v_pk_add_f32 v[116:117], v[134:135], v[76:77]
	s_nop 0
	v_and_b32_sdwa v119, v116, v1 dst_sel:DWORD dst_unused:UNUSED_PAD src0_sel:WORD_1 src1_sel:DWORD
	v_and_b32_sdwa v118, v117, v1 dst_sel:DWORD dst_unused:UNUSED_PAD src0_sel:WORD_1 src1_sel:DWORD
	v_add3_u32 v119, v116, v119, s53
	v_add3_u32 v118, v117, v118, s53
	v_lshrrev_b32_e32 v119, 16, v119
	v_and_or_b32 v118, v118, s77, v119
	global_store_dword v[114:115], v118, off
	v_pk_mul_f32 v[118:119], v[6:7], v[116:117] op_sel:[1,0]
	v_lshl_add_u64 v[114:115], v[114:115], 0, s[18:19]
	v_pk_fma_f32 v[134:135], v[6:7], v[116:117], v[118:119] op_sel:[0,0,1] op_sel_hi:[1,1,0] neg_lo:[0,0,1] neg_hi:[0,0,1]
	v_pk_fma_f32 v[116:117], v[6:7], v[116:117], v[118:119] op_sel:[0,0,1] op_sel_hi:[0,1,0]
	v_mov_b32_e32 v135, v117
	v_pk_add_f32 v[116:117], v[134:135], v[74:75]
	s_nop 0
	v_and_b32_sdwa v119, v116, v1 dst_sel:DWORD dst_unused:UNUSED_PAD src0_sel:WORD_1 src1_sel:DWORD
	v_and_b32_sdwa v118, v117, v1 dst_sel:DWORD dst_unused:UNUSED_PAD src0_sel:WORD_1 src1_sel:DWORD
	v_add3_u32 v119, v116, v119, s53
	v_add3_u32 v118, v117, v118, s53
	v_lshrrev_b32_e32 v119, 16, v119
	v_and_or_b32 v118, v118, s77, v119
	global_store_dword v[114:115], v118, off
	v_pk_mul_f32 v[118:119], v[6:7], v[116:117] op_sel:[1,0]
	v_lshl_add_u64 v[114:115], v[114:115], 0, s[18:19]
	v_pk_fma_f32 v[134:135], v[6:7], v[116:117], v[118:119] op_sel:[0,0,1] op_sel_hi:[1,1,0] neg_lo:[0,0,1] neg_hi:[0,0,1]
	v_pk_fma_f32 v[116:117], v[6:7], v[116:117], v[118:119] op_sel:[0,0,1] op_sel_hi:[0,1,0]
	v_mov_b32_e32 v135, v117
	v_pk_add_f32 v[116:117], v[134:135], v[72:73]
	s_nop 0
	v_and_b32_sdwa v119, v116, v1 dst_sel:DWORD dst_unused:UNUSED_PAD src0_sel:WORD_1 src1_sel:DWORD
	v_and_b32_sdwa v118, v117, v1 dst_sel:DWORD dst_unused:UNUSED_PAD src0_sel:WORD_1 src1_sel:DWORD
	v_add3_u32 v119, v116, v119, s53
	v_add3_u32 v118, v117, v118, s53
	v_lshrrev_b32_e32 v119, 16, v119
	v_and_or_b32 v118, v118, s77, v119
	global_store_dword v[114:115], v118, off
	v_pk_mul_f32 v[118:119], v[6:7], v[116:117] op_sel:[1,0]
	v_lshl_add_u64 v[114:115], v[114:115], 0, s[18:19]
	v_pk_fma_f32 v[134:135], v[6:7], v[116:117], v[118:119] op_sel:[0,0,1] op_sel_hi:[1,1,0] neg_lo:[0,0,1] neg_hi:[0,0,1]
	v_pk_fma_f32 v[116:117], v[6:7], v[116:117], v[118:119] op_sel:[0,0,1] op_sel_hi:[0,1,0]
	v_mov_b32_e32 v135, v117
	v_pk_add_f32 v[116:117], v[134:135], v[70:71]
	s_nop 0
	v_and_b32_sdwa v119, v116, v1 dst_sel:DWORD dst_unused:UNUSED_PAD src0_sel:WORD_1 src1_sel:DWORD
	v_and_b32_sdwa v118, v117, v1 dst_sel:DWORD dst_unused:UNUSED_PAD src0_sel:WORD_1 src1_sel:DWORD
	v_add3_u32 v119, v116, v119, s53
	v_add3_u32 v118, v117, v118, s53
	v_lshrrev_b32_e32 v119, 16, v119
	v_and_or_b32 v118, v118, s77, v119
	global_store_dword v[114:115], v118, off
	v_pk_mul_f32 v[118:119], v[6:7], v[116:117] op_sel:[1,0]
	v_lshl_add_u64 v[114:115], v[114:115], 0, s[18:19]
	v_pk_fma_f32 v[134:135], v[6:7], v[116:117], v[118:119] op_sel:[0,0,1] op_sel_hi:[1,1,0] neg_lo:[0,0,1] neg_hi:[0,0,1]
	v_pk_fma_f32 v[116:117], v[6:7], v[116:117], v[118:119] op_sel:[0,0,1] op_sel_hi:[0,1,0]
	v_mov_b32_e32 v135, v117
	v_pk_add_f32 v[116:117], v[134:135], v[68:69]
	s_nop 0
	v_and_b32_sdwa v119, v116, v1 dst_sel:DWORD dst_unused:UNUSED_PAD src0_sel:WORD_1 src1_sel:DWORD
	v_and_b32_sdwa v118, v117, v1 dst_sel:DWORD dst_unused:UNUSED_PAD src0_sel:WORD_1 src1_sel:DWORD
	v_add3_u32 v119, v116, v119, s53
	v_add3_u32 v118, v117, v118, s53
	v_lshrrev_b32_e32 v119, 16, v119
	v_and_or_b32 v118, v118, s77, v119
	global_store_dword v[114:115], v118, off
	v_pk_mul_f32 v[118:119], v[6:7], v[116:117] op_sel:[1,0]
	v_lshl_add_u64 v[114:115], v[114:115], 0, s[18:19]
	v_pk_fma_f32 v[134:135], v[6:7], v[116:117], v[118:119] op_sel:[0,0,1] op_sel_hi:[1,1,0] neg_lo:[0,0,1] neg_hi:[0,0,1]
	v_pk_fma_f32 v[116:117], v[6:7], v[116:117], v[118:119] op_sel:[0,0,1] op_sel_hi:[0,1,0]
	v_mov_b32_e32 v135, v117
	v_pk_add_f32 v[116:117], v[134:135], v[66:67]
	s_nop 0
	v_and_b32_sdwa v119, v116, v1 dst_sel:DWORD dst_unused:UNUSED_PAD src0_sel:WORD_1 src1_sel:DWORD
	v_and_b32_sdwa v118, v117, v1 dst_sel:DWORD dst_unused:UNUSED_PAD src0_sel:WORD_1 src1_sel:DWORD
	v_add3_u32 v119, v116, v119, s53
	v_add3_u32 v118, v117, v118, s53
	v_lshrrev_b32_e32 v119, 16, v119
	v_and_or_b32 v118, v118, s77, v119
	global_store_dword v[114:115], v118, off
	v_pk_mul_f32 v[118:119], v[6:7], v[116:117] op_sel:[1,0]
	v_lshl_add_u64 v[114:115], v[114:115], 0, s[18:19]
	v_pk_fma_f32 v[134:135], v[6:7], v[116:117], v[118:119] op_sel:[0,0,1] op_sel_hi:[1,1,0] neg_lo:[0,0,1] neg_hi:[0,0,1]
	v_pk_fma_f32 v[116:117], v[6:7], v[116:117], v[118:119] op_sel:[0,0,1] op_sel_hi:[0,1,0]
	v_mov_b32_e32 v135, v117
	v_pk_add_f32 v[116:117], v[134:135], v[64:65]
	s_nop 0
	v_and_b32_sdwa v119, v116, v1 dst_sel:DWORD dst_unused:UNUSED_PAD src0_sel:WORD_1 src1_sel:DWORD
	v_and_b32_sdwa v118, v117, v1 dst_sel:DWORD dst_unused:UNUSED_PAD src0_sel:WORD_1 src1_sel:DWORD
	v_add3_u32 v119, v116, v119, s53
	v_add3_u32 v118, v117, v118, s53
	v_lshrrev_b32_e32 v119, 16, v119
	v_and_or_b32 v118, v118, s77, v119
	global_store_dword v[114:115], v118, off
	v_pk_mul_f32 v[118:119], v[6:7], v[116:117] op_sel:[1,0]
	v_lshl_add_u64 v[114:115], v[114:115], 0, s[18:19]
	v_pk_fma_f32 v[134:135], v[6:7], v[116:117], v[118:119] op_sel:[0,0,1] op_sel_hi:[1,1,0] neg_lo:[0,0,1] neg_hi:[0,0,1]
	v_pk_fma_f32 v[116:117], v[6:7], v[116:117], v[118:119] op_sel:[0,0,1] op_sel_hi:[0,1,0]
	v_mov_b32_e32 v135, v117
	v_pk_add_f32 v[116:117], v[134:135], v[62:63]
	s_nop 0
	v_and_b32_sdwa v119, v116, v1 dst_sel:DWORD dst_unused:UNUSED_PAD src0_sel:WORD_1 src1_sel:DWORD
	v_and_b32_sdwa v118, v117, v1 dst_sel:DWORD dst_unused:UNUSED_PAD src0_sel:WORD_1 src1_sel:DWORD
	v_add3_u32 v119, v116, v119, s53
	v_add3_u32 v118, v117, v118, s53
	v_lshrrev_b32_e32 v119, 16, v119
	v_and_or_b32 v118, v118, s77, v119
	global_store_dword v[114:115], v118, off
	v_pk_mul_f32 v[118:119], v[6:7], v[116:117] op_sel:[1,0]
	v_lshl_add_u64 v[114:115], v[114:115], 0, s[18:19]
	v_pk_fma_f32 v[134:135], v[6:7], v[116:117], v[118:119] op_sel:[0,0,1] op_sel_hi:[1,1,0] neg_lo:[0,0,1] neg_hi:[0,0,1]
	v_pk_fma_f32 v[116:117], v[6:7], v[116:117], v[118:119] op_sel:[0,0,1] op_sel_hi:[0,1,0]
	v_mov_b32_e32 v135, v117
	v_pk_add_f32 v[116:117], v[134:135], v[60:61]
	s_nop 0
	v_and_b32_sdwa v119, v116, v1 dst_sel:DWORD dst_unused:UNUSED_PAD src0_sel:WORD_1 src1_sel:DWORD
	v_and_b32_sdwa v118, v117, v1 dst_sel:DWORD dst_unused:UNUSED_PAD src0_sel:WORD_1 src1_sel:DWORD
	v_add3_u32 v119, v116, v119, s53
	v_add3_u32 v118, v117, v118, s53
	v_lshrrev_b32_e32 v119, 16, v119
	v_and_or_b32 v118, v118, s77, v119
	global_store_dword v[114:115], v118, off
	v_pk_mul_f32 v[118:119], v[6:7], v[116:117] op_sel:[1,0]
	v_lshl_add_u64 v[114:115], v[114:115], 0, s[18:19]
	v_pk_fma_f32 v[134:135], v[6:7], v[116:117], v[118:119] op_sel:[0,0,1] op_sel_hi:[1,1,0] neg_lo:[0,0,1] neg_hi:[0,0,1]
	v_pk_fma_f32 v[116:117], v[6:7], v[116:117], v[118:119] op_sel:[0,0,1] op_sel_hi:[0,1,0]
	v_mov_b32_e32 v135, v117
	v_pk_add_f32 v[116:117], v[134:135], v[58:59]
	s_nop 0
	v_and_b32_sdwa v119, v116, v1 dst_sel:DWORD dst_unused:UNUSED_PAD src0_sel:WORD_1 src1_sel:DWORD
	v_and_b32_sdwa v118, v117, v1 dst_sel:DWORD dst_unused:UNUSED_PAD src0_sel:WORD_1 src1_sel:DWORD
	v_add3_u32 v119, v116, v119, s53
	v_add3_u32 v118, v117, v118, s53
	v_lshrrev_b32_e32 v119, 16, v119
	v_and_or_b32 v118, v118, s77, v119
	global_store_dword v[114:115], v118, off
	v_pk_mul_f32 v[118:119], v[6:7], v[116:117] op_sel:[1,0]
	v_lshl_add_u64 v[114:115], v[114:115], 0, s[18:19]
	v_pk_fma_f32 v[134:135], v[6:7], v[116:117], v[118:119] op_sel:[0,0,1] op_sel_hi:[1,1,0] neg_lo:[0,0,1] neg_hi:[0,0,1]
	v_pk_fma_f32 v[116:117], v[6:7], v[116:117], v[118:119] op_sel:[0,0,1] op_sel_hi:[0,1,0]
	v_mov_b32_e32 v135, v117
	v_pk_add_f32 v[116:117], v[134:135], v[54:55]
	s_nop 0
	v_and_b32_sdwa v119, v116, v1 dst_sel:DWORD dst_unused:UNUSED_PAD src0_sel:WORD_1 src1_sel:DWORD
	v_and_b32_sdwa v118, v117, v1 dst_sel:DWORD dst_unused:UNUSED_PAD src0_sel:WORD_1 src1_sel:DWORD
	v_add3_u32 v119, v116, v119, s53
	v_add3_u32 v118, v117, v118, s53
	v_lshrrev_b32_e32 v119, 16, v119
	v_and_or_b32 v118, v118, s77, v119
	global_store_dword v[114:115], v118, off
	v_pk_mul_f32 v[118:119], v[6:7], v[116:117] op_sel:[1,0]
	v_lshl_add_u64 v[114:115], v[114:115], 0, s[18:19]
	v_pk_fma_f32 v[134:135], v[6:7], v[116:117], v[118:119] op_sel:[0,0,1] op_sel_hi:[1,1,0] neg_lo:[0,0,1] neg_hi:[0,0,1]
	v_pk_fma_f32 v[116:117], v[6:7], v[116:117], v[118:119] op_sel:[0,0,1] op_sel_hi:[0,1,0]
	v_mov_b32_e32 v135, v117
	v_pk_add_f32 v[116:117], v[134:135], v[56:57]
	s_nop 0
	v_and_b32_sdwa v119, v116, v1 dst_sel:DWORD dst_unused:UNUSED_PAD src0_sel:WORD_1 src1_sel:DWORD
	v_and_b32_sdwa v118, v117, v1 dst_sel:DWORD dst_unused:UNUSED_PAD src0_sel:WORD_1 src1_sel:DWORD
	v_add3_u32 v119, v116, v119, s53
	v_add3_u32 v118, v117, v118, s53
	v_lshrrev_b32_e32 v119, 16, v119
	v_and_or_b32 v118, v118, s77, v119
	global_store_dword v[114:115], v118, off
	v_pk_mul_f32 v[118:119], v[6:7], v[116:117] op_sel:[1,0]
	v_lshl_add_u64 v[114:115], v[114:115], 0, s[18:19]
	v_pk_fma_f32 v[134:135], v[6:7], v[116:117], v[118:119] op_sel:[0,0,1] op_sel_hi:[1,1,0] neg_lo:[0,0,1] neg_hi:[0,0,1]
	v_pk_fma_f32 v[116:117], v[6:7], v[116:117], v[118:119] op_sel:[0,0,1] op_sel_hi:[0,1,0]
	v_mov_b32_e32 v135, v117
	v_pk_add_f32 v[116:117], v[134:135], v[52:53]
	s_nop 0
	v_and_b32_sdwa v119, v116, v1 dst_sel:DWORD dst_unused:UNUSED_PAD src0_sel:WORD_1 src1_sel:DWORD
	v_and_b32_sdwa v118, v117, v1 dst_sel:DWORD dst_unused:UNUSED_PAD src0_sel:WORD_1 src1_sel:DWORD
	v_add3_u32 v119, v116, v119, s53
	v_add3_u32 v118, v117, v118, s53
	v_lshrrev_b32_e32 v119, 16, v119
	v_and_or_b32 v118, v118, s77, v119
	global_store_dword v[114:115], v118, off
	v_pk_mul_f32 v[118:119], v[6:7], v[116:117] op_sel:[1,0]
	v_lshl_add_u64 v[114:115], v[114:115], 0, s[18:19]
	v_pk_fma_f32 v[134:135], v[6:7], v[116:117], v[118:119] op_sel:[0,0,1] op_sel_hi:[1,1,0] neg_lo:[0,0,1] neg_hi:[0,0,1]
	v_pk_fma_f32 v[116:117], v[6:7], v[116:117], v[118:119] op_sel:[0,0,1] op_sel_hi:[0,1,0]
	v_mov_b32_e32 v135, v117
	v_pk_add_f32 v[116:117], v[134:135], v[50:51]
	s_nop 0
	v_and_b32_sdwa v119, v116, v1 dst_sel:DWORD dst_unused:UNUSED_PAD src0_sel:WORD_1 src1_sel:DWORD
	v_and_b32_sdwa v118, v117, v1 dst_sel:DWORD dst_unused:UNUSED_PAD src0_sel:WORD_1 src1_sel:DWORD
	v_add3_u32 v119, v116, v119, s53
	v_add3_u32 v118, v117, v118, s53
	v_lshrrev_b32_e32 v119, 16, v119
	v_and_or_b32 v118, v118, s77, v119
	global_store_dword v[114:115], v118, off
	v_pk_mul_f32 v[118:119], v[6:7], v[116:117] op_sel:[1,0]
	v_lshl_add_u64 v[114:115], v[114:115], 0, s[18:19]
	v_pk_fma_f32 v[134:135], v[6:7], v[116:117], v[118:119] op_sel:[0,0,1] op_sel_hi:[1,1,0] neg_lo:[0,0,1] neg_hi:[0,0,1]
	v_pk_fma_f32 v[116:117], v[6:7], v[116:117], v[118:119] op_sel:[0,0,1] op_sel_hi:[0,1,0]
	v_mov_b32_e32 v135, v117
	v_pk_add_f32 v[116:117], v[134:135], v[48:49]
	s_nop 0
	v_and_b32_sdwa v119, v116, v1 dst_sel:DWORD dst_unused:UNUSED_PAD src0_sel:WORD_1 src1_sel:DWORD
	v_and_b32_sdwa v118, v117, v1 dst_sel:DWORD dst_unused:UNUSED_PAD src0_sel:WORD_1 src1_sel:DWORD
	v_add3_u32 v119, v116, v119, s53
	v_add3_u32 v118, v117, v118, s53
	v_lshrrev_b32_e32 v119, 16, v119
	v_and_or_b32 v118, v118, s77, v119
	global_store_dword v[114:115], v118, off
	v_pk_mul_f32 v[118:119], v[6:7], v[116:117] op_sel:[1,0]
	v_lshl_add_u64 v[114:115], v[114:115], 0, s[18:19]
	v_pk_fma_f32 v[134:135], v[6:7], v[116:117], v[118:119] op_sel:[0,0,1] op_sel_hi:[1,1,0] neg_lo:[0,0,1] neg_hi:[0,0,1]
	v_pk_fma_f32 v[116:117], v[6:7], v[116:117], v[118:119] op_sel:[0,0,1] op_sel_hi:[0,1,0]
	v_mov_b32_e32 v135, v117
	v_pk_add_f32 v[116:117], v[134:135], v[46:47]
	s_nop 0
	v_and_b32_sdwa v119, v116, v1 dst_sel:DWORD dst_unused:UNUSED_PAD src0_sel:WORD_1 src1_sel:DWORD
	v_and_b32_sdwa v118, v117, v1 dst_sel:DWORD dst_unused:UNUSED_PAD src0_sel:WORD_1 src1_sel:DWORD
	v_add3_u32 v119, v116, v119, s53
	v_add3_u32 v118, v117, v118, s53
	v_lshrrev_b32_e32 v119, 16, v119
	v_and_or_b32 v118, v118, s77, v119
	global_store_dword v[114:115], v118, off
	v_pk_mul_f32 v[118:119], v[6:7], v[116:117] op_sel:[1,0]
	v_lshl_add_u64 v[114:115], v[114:115], 0, s[18:19]
	v_pk_fma_f32 v[134:135], v[6:7], v[116:117], v[118:119] op_sel:[0,0,1] op_sel_hi:[1,1,0] neg_lo:[0,0,1] neg_hi:[0,0,1]
	v_pk_fma_f32 v[116:117], v[6:7], v[116:117], v[118:119] op_sel:[0,0,1] op_sel_hi:[0,1,0]
	v_mov_b32_e32 v135, v117
	v_pk_add_f32 v[116:117], v[134:135], v[44:45]
	s_nop 0
	v_and_b32_sdwa v119, v116, v1 dst_sel:DWORD dst_unused:UNUSED_PAD src0_sel:WORD_1 src1_sel:DWORD
	v_and_b32_sdwa v118, v117, v1 dst_sel:DWORD dst_unused:UNUSED_PAD src0_sel:WORD_1 src1_sel:DWORD
	v_add3_u32 v119, v116, v119, s53
	v_add3_u32 v118, v117, v118, s53
	v_lshrrev_b32_e32 v119, 16, v119
	v_and_or_b32 v118, v118, s77, v119
	global_store_dword v[114:115], v118, off
	v_pk_mul_f32 v[118:119], v[6:7], v[116:117] op_sel:[1,0]
	v_lshl_add_u64 v[114:115], v[114:115], 0, s[18:19]
	v_pk_fma_f32 v[134:135], v[6:7], v[116:117], v[118:119] op_sel:[0,0,1] op_sel_hi:[1,1,0] neg_lo:[0,0,1] neg_hi:[0,0,1]
	v_pk_fma_f32 v[116:117], v[6:7], v[116:117], v[118:119] op_sel:[0,0,1] op_sel_hi:[0,1,0]
	v_mov_b32_e32 v135, v117
	v_pk_add_f32 v[116:117], v[134:135], v[42:43]
	s_nop 0
	v_and_b32_sdwa v119, v116, v1 dst_sel:DWORD dst_unused:UNUSED_PAD src0_sel:WORD_1 src1_sel:DWORD
	v_and_b32_sdwa v118, v117, v1 dst_sel:DWORD dst_unused:UNUSED_PAD src0_sel:WORD_1 src1_sel:DWORD
	v_add3_u32 v119, v116, v119, s53
	v_add3_u32 v118, v117, v118, s53
	v_lshrrev_b32_e32 v119, 16, v119
	v_and_or_b32 v118, v118, s77, v119
	global_store_dword v[114:115], v118, off
	v_pk_mul_f32 v[118:119], v[6:7], v[116:117] op_sel:[1,0]
	v_lshl_add_u64 v[114:115], v[114:115], 0, s[18:19]
	v_pk_fma_f32 v[134:135], v[6:7], v[116:117], v[118:119] op_sel:[0,0,1] op_sel_hi:[1,1,0] neg_lo:[0,0,1] neg_hi:[0,0,1]
	v_pk_fma_f32 v[116:117], v[6:7], v[116:117], v[118:119] op_sel:[0,0,1] op_sel_hi:[0,1,0]
	v_mov_b32_e32 v135, v117
	v_pk_add_f32 v[116:117], v[134:135], v[40:41]
	s_nop 0
	v_and_b32_sdwa v119, v116, v1 dst_sel:DWORD dst_unused:UNUSED_PAD src0_sel:WORD_1 src1_sel:DWORD
	v_and_b32_sdwa v118, v117, v1 dst_sel:DWORD dst_unused:UNUSED_PAD src0_sel:WORD_1 src1_sel:DWORD
	v_add3_u32 v119, v116, v119, s53
	v_add3_u32 v118, v117, v118, s53
	v_lshrrev_b32_e32 v119, 16, v119
	v_and_or_b32 v118, v118, s77, v119
	global_store_dword v[114:115], v118, off
	v_pk_mul_f32 v[118:119], v[6:7], v[116:117] op_sel:[1,0]
	v_lshl_add_u64 v[114:115], v[114:115], 0, s[18:19]
	v_pk_fma_f32 v[134:135], v[6:7], v[116:117], v[118:119] op_sel:[0,0,1] op_sel_hi:[1,1,0] neg_lo:[0,0,1] neg_hi:[0,0,1]
	v_pk_fma_f32 v[116:117], v[6:7], v[116:117], v[118:119] op_sel:[0,0,1] op_sel_hi:[0,1,0]
	v_mov_b32_e32 v135, v117
	v_pk_add_f32 v[116:117], v[134:135], v[38:39]
	s_nop 0
	v_and_b32_sdwa v119, v116, v1 dst_sel:DWORD dst_unused:UNUSED_PAD src0_sel:WORD_1 src1_sel:DWORD
	v_and_b32_sdwa v118, v117, v1 dst_sel:DWORD dst_unused:UNUSED_PAD src0_sel:WORD_1 src1_sel:DWORD
	v_add3_u32 v119, v116, v119, s53
	v_add3_u32 v118, v117, v118, s53
	v_lshrrev_b32_e32 v119, 16, v119
	v_and_or_b32 v118, v118, s77, v119
	global_store_dword v[114:115], v118, off
	v_pk_mul_f32 v[118:119], v[6:7], v[116:117] op_sel:[1,0]
	v_lshl_add_u64 v[114:115], v[114:115], 0, s[18:19]
	v_pk_fma_f32 v[134:135], v[6:7], v[116:117], v[118:119] op_sel:[0,0,1] op_sel_hi:[1,1,0] neg_lo:[0,0,1] neg_hi:[0,0,1]
	v_pk_fma_f32 v[116:117], v[6:7], v[116:117], v[118:119] op_sel:[0,0,1] op_sel_hi:[0,1,0]
	v_mov_b32_e32 v135, v117
	v_pk_add_f32 v[116:117], v[134:135], v[36:37]
	s_nop 0
	v_and_b32_sdwa v119, v116, v1 dst_sel:DWORD dst_unused:UNUSED_PAD src0_sel:WORD_1 src1_sel:DWORD
	v_and_b32_sdwa v118, v117, v1 dst_sel:DWORD dst_unused:UNUSED_PAD src0_sel:WORD_1 src1_sel:DWORD
	v_add3_u32 v119, v116, v119, s53
	v_add3_u32 v118, v117, v118, s53
	v_lshrrev_b32_e32 v119, 16, v119
	v_and_or_b32 v118, v118, s77, v119
	global_store_dword v[114:115], v118, off
	v_pk_mul_f32 v[118:119], v[6:7], v[116:117] op_sel:[1,0]
	v_lshl_add_u64 v[114:115], v[114:115], 0, s[18:19]
	v_pk_fma_f32 v[134:135], v[6:7], v[116:117], v[118:119] op_sel:[0,0,1] op_sel_hi:[1,1,0] neg_lo:[0,0,1] neg_hi:[0,0,1]
	v_pk_fma_f32 v[116:117], v[6:7], v[116:117], v[118:119] op_sel:[0,0,1] op_sel_hi:[0,1,0]
	v_mov_b32_e32 v135, v117
	v_pk_add_f32 v[116:117], v[134:135], v[34:35]
	s_nop 0
	v_and_b32_sdwa v119, v116, v1 dst_sel:DWORD dst_unused:UNUSED_PAD src0_sel:WORD_1 src1_sel:DWORD
	v_and_b32_sdwa v118, v117, v1 dst_sel:DWORD dst_unused:UNUSED_PAD src0_sel:WORD_1 src1_sel:DWORD
	v_add3_u32 v119, v116, v119, s53
	v_add3_u32 v118, v117, v118, s53
	v_lshrrev_b32_e32 v119, 16, v119
	v_and_or_b32 v118, v118, s77, v119
	global_store_dword v[114:115], v118, off
	v_pk_mul_f32 v[118:119], v[6:7], v[116:117] op_sel:[1,0]
	v_lshl_add_u64 v[114:115], v[114:115], 0, s[18:19]
	v_pk_fma_f32 v[134:135], v[6:7], v[116:117], v[118:119] op_sel:[0,0,1] op_sel_hi:[1,1,0] neg_lo:[0,0,1] neg_hi:[0,0,1]
	v_pk_fma_f32 v[116:117], v[6:7], v[116:117], v[118:119] op_sel:[0,0,1] op_sel_hi:[0,1,0]
	v_mov_b32_e32 v135, v117
	v_pk_add_f32 v[116:117], v[134:135], v[32:33]
	s_nop 0
	v_and_b32_sdwa v119, v116, v1 dst_sel:DWORD dst_unused:UNUSED_PAD src0_sel:WORD_1 src1_sel:DWORD
	v_and_b32_sdwa v118, v117, v1 dst_sel:DWORD dst_unused:UNUSED_PAD src0_sel:WORD_1 src1_sel:DWORD
	v_add3_u32 v119, v116, v119, s53
	v_add3_u32 v118, v117, v118, s53
	v_lshrrev_b32_e32 v119, 16, v119
	v_and_or_b32 v118, v118, s77, v119
	global_store_dword v[114:115], v118, off
	v_pk_mul_f32 v[118:119], v[6:7], v[116:117] op_sel:[1,0]
	v_lshl_add_u64 v[114:115], v[114:115], 0, s[18:19]
	v_pk_fma_f32 v[134:135], v[6:7], v[116:117], v[118:119] op_sel:[0,0,1] op_sel_hi:[1,1,0] neg_lo:[0,0,1] neg_hi:[0,0,1]
	v_pk_fma_f32 v[116:117], v[6:7], v[116:117], v[118:119] op_sel:[0,0,1] op_sel_hi:[0,1,0]
	v_mov_b32_e32 v135, v117
	v_pk_add_f32 v[116:117], v[134:135], v[30:31]
	s_nop 0
	v_and_b32_sdwa v119, v116, v1 dst_sel:DWORD dst_unused:UNUSED_PAD src0_sel:WORD_1 src1_sel:DWORD
	v_and_b32_sdwa v118, v117, v1 dst_sel:DWORD dst_unused:UNUSED_PAD src0_sel:WORD_1 src1_sel:DWORD
	v_add3_u32 v119, v116, v119, s53
	v_add3_u32 v118, v117, v118, s53
	v_lshrrev_b32_e32 v119, 16, v119
	v_and_or_b32 v118, v118, s77, v119
	global_store_dword v[114:115], v118, off
	v_pk_mul_f32 v[118:119], v[6:7], v[116:117] op_sel:[1,0]
	v_lshl_add_u64 v[114:115], v[114:115], 0, s[18:19]
	v_pk_fma_f32 v[134:135], v[6:7], v[116:117], v[118:119] op_sel:[0,0,1] op_sel_hi:[1,1,0] neg_lo:[0,0,1] neg_hi:[0,0,1]
	v_pk_fma_f32 v[116:117], v[6:7], v[116:117], v[118:119] op_sel:[0,0,1] op_sel_hi:[0,1,0]
	v_mov_b32_e32 v135, v117
	v_pk_add_f32 v[116:117], v[134:135], v[28:29]
	s_nop 0
	v_and_b32_sdwa v119, v116, v1 dst_sel:DWORD dst_unused:UNUSED_PAD src0_sel:WORD_1 src1_sel:DWORD
	v_and_b32_sdwa v118, v117, v1 dst_sel:DWORD dst_unused:UNUSED_PAD src0_sel:WORD_1 src1_sel:DWORD
	v_add3_u32 v119, v116, v119, s53
	v_add3_u32 v118, v117, v118, s53
	v_lshrrev_b32_e32 v119, 16, v119
	v_and_or_b32 v118, v118, s77, v119
	global_store_dword v[114:115], v118, off
	v_pk_mul_f32 v[118:119], v[6:7], v[116:117] op_sel:[1,0]
	v_lshl_add_u64 v[114:115], v[114:115], 0, s[18:19]
	v_pk_fma_f32 v[134:135], v[6:7], v[116:117], v[118:119] op_sel:[0,0,1] op_sel_hi:[1,1,0] neg_lo:[0,0,1] neg_hi:[0,0,1]
	v_pk_fma_f32 v[116:117], v[6:7], v[116:117], v[118:119] op_sel:[0,0,1] op_sel_hi:[0,1,0]
	v_mov_b32_e32 v135, v117
	v_pk_add_f32 v[116:117], v[134:135], v[26:27]
	s_nop 0
	v_and_b32_sdwa v119, v116, v1 dst_sel:DWORD dst_unused:UNUSED_PAD src0_sel:WORD_1 src1_sel:DWORD
	v_and_b32_sdwa v118, v117, v1 dst_sel:DWORD dst_unused:UNUSED_PAD src0_sel:WORD_1 src1_sel:DWORD
	v_add3_u32 v119, v116, v119, s53
	v_add3_u32 v118, v117, v118, s53
	v_lshrrev_b32_e32 v119, 16, v119
	v_and_or_b32 v118, v118, s77, v119
	global_store_dword v[114:115], v118, off
	v_pk_mul_f32 v[118:119], v[6:7], v[116:117] op_sel:[1,0]
	v_lshl_add_u64 v[114:115], v[114:115], 0, s[18:19]
	v_pk_fma_f32 v[134:135], v[6:7], v[116:117], v[118:119] op_sel:[0,0,1] op_sel_hi:[1,1,0] neg_lo:[0,0,1] neg_hi:[0,0,1]
	v_pk_fma_f32 v[116:117], v[6:7], v[116:117], v[118:119] op_sel:[0,0,1] op_sel_hi:[0,1,0]
	v_mov_b32_e32 v135, v117
	v_pk_add_f32 v[116:117], v[134:135], v[24:25]
	s_nop 0
	v_and_b32_sdwa v119, v116, v1 dst_sel:DWORD dst_unused:UNUSED_PAD src0_sel:WORD_1 src1_sel:DWORD
	v_and_b32_sdwa v118, v117, v1 dst_sel:DWORD dst_unused:UNUSED_PAD src0_sel:WORD_1 src1_sel:DWORD
	v_add3_u32 v119, v116, v119, s53
	v_add3_u32 v118, v117, v118, s53
	v_lshrrev_b32_e32 v119, 16, v119
	v_and_or_b32 v118, v118, s77, v119
	global_store_dword v[114:115], v118, off
	v_pk_mul_f32 v[118:119], v[6:7], v[116:117] op_sel:[1,0]
	v_lshl_add_u64 v[114:115], v[114:115], 0, s[18:19]
	v_pk_fma_f32 v[134:135], v[6:7], v[116:117], v[118:119] op_sel:[0,0,1] op_sel_hi:[1,1,0] neg_lo:[0,0,1] neg_hi:[0,0,1]
	v_pk_fma_f32 v[116:117], v[6:7], v[116:117], v[118:119] op_sel:[0,0,1] op_sel_hi:[0,1,0]
	v_mov_b32_e32 v135, v117
	v_pk_add_f32 v[116:117], v[134:135], v[22:23]
	s_nop 0
	v_and_b32_sdwa v119, v116, v1 dst_sel:DWORD dst_unused:UNUSED_PAD src0_sel:WORD_1 src1_sel:DWORD
	v_and_b32_sdwa v118, v117, v1 dst_sel:DWORD dst_unused:UNUSED_PAD src0_sel:WORD_1 src1_sel:DWORD
	v_add3_u32 v119, v116, v119, s53
	v_add3_u32 v118, v117, v118, s53
	v_lshrrev_b32_e32 v119, 16, v119
	v_and_or_b32 v118, v118, s77, v119
	global_store_dword v[114:115], v118, off
	v_pk_mul_f32 v[118:119], v[6:7], v[116:117] op_sel:[1,0]
	v_lshl_add_u64 v[114:115], v[114:115], 0, s[18:19]
	v_pk_fma_f32 v[134:135], v[6:7], v[116:117], v[118:119] op_sel:[0,0,1] op_sel_hi:[1,1,0] neg_lo:[0,0,1] neg_hi:[0,0,1]
	v_pk_fma_f32 v[116:117], v[6:7], v[116:117], v[118:119] op_sel:[0,0,1] op_sel_hi:[0,1,0]
	v_mov_b32_e32 v135, v117
	v_pk_add_f32 v[116:117], v[134:135], v[20:21]
	s_nop 0
	v_and_b32_sdwa v119, v116, v1 dst_sel:DWORD dst_unused:UNUSED_PAD src0_sel:WORD_1 src1_sel:DWORD
	v_and_b32_sdwa v118, v117, v1 dst_sel:DWORD dst_unused:UNUSED_PAD src0_sel:WORD_1 src1_sel:DWORD
	v_add3_u32 v119, v116, v119, s53
	v_add3_u32 v118, v117, v118, s53
	v_lshrrev_b32_e32 v119, 16, v119
	v_and_or_b32 v118, v118, s77, v119
	global_store_dword v[114:115], v118, off
	v_pk_mul_f32 v[118:119], v[6:7], v[116:117] op_sel:[1,0]
	v_lshl_add_u64 v[114:115], v[114:115], 0, s[18:19]
	v_pk_fma_f32 v[134:135], v[6:7], v[116:117], v[118:119] op_sel:[0,0,1] op_sel_hi:[1,1,0] neg_lo:[0,0,1] neg_hi:[0,0,1]
	v_pk_fma_f32 v[116:117], v[6:7], v[116:117], v[118:119] op_sel:[0,0,1] op_sel_hi:[0,1,0]
	v_mov_b32_e32 v135, v117
	v_pk_add_f32 v[116:117], v[134:135], v[18:19]
	s_nop 0
	v_and_b32_sdwa v119, v116, v1 dst_sel:DWORD dst_unused:UNUSED_PAD src0_sel:WORD_1 src1_sel:DWORD
	v_and_b32_sdwa v118, v117, v1 dst_sel:DWORD dst_unused:UNUSED_PAD src0_sel:WORD_1 src1_sel:DWORD
	v_add3_u32 v119, v116, v119, s53
	v_add3_u32 v118, v117, v118, s53
	v_lshrrev_b32_e32 v119, 16, v119
	v_and_or_b32 v118, v118, s77, v119
	global_store_dword v[114:115], v118, off
	v_pk_mul_f32 v[118:119], v[6:7], v[116:117] op_sel:[1,0]
	v_lshl_add_u64 v[114:115], v[114:115], 0, s[18:19]
	v_pk_fma_f32 v[134:135], v[6:7], v[116:117], v[118:119] op_sel:[0,0,1] op_sel_hi:[1,1,0] neg_lo:[0,0,1] neg_hi:[0,0,1]
	v_pk_fma_f32 v[116:117], v[6:7], v[116:117], v[118:119] op_sel:[0,0,1] op_sel_hi:[0,1,0]
	v_mov_b32_e32 v135, v117
	v_pk_add_f32 v[116:117], v[134:135], v[16:17]
	s_nop 0
	v_and_b32_sdwa v119, v116, v1 dst_sel:DWORD dst_unused:UNUSED_PAD src0_sel:WORD_1 src1_sel:DWORD
	v_and_b32_sdwa v118, v117, v1 dst_sel:DWORD dst_unused:UNUSED_PAD src0_sel:WORD_1 src1_sel:DWORD
	v_add3_u32 v119, v116, v119, s53
	v_add3_u32 v118, v117, v118, s53
	v_lshrrev_b32_e32 v119, 16, v119
	v_and_or_b32 v118, v118, s77, v119
	global_store_dword v[114:115], v118, off
	v_pk_mul_f32 v[118:119], v[6:7], v[116:117] op_sel:[1,0]
	v_lshl_add_u64 v[114:115], v[114:115], 0, s[18:19]
	v_pk_fma_f32 v[134:135], v[6:7], v[116:117], v[118:119] op_sel:[0,0,1] op_sel_hi:[1,1,0] neg_lo:[0,0,1] neg_hi:[0,0,1]
	v_pk_fma_f32 v[116:117], v[6:7], v[116:117], v[118:119] op_sel:[0,0,1] op_sel_hi:[0,1,0]
	v_mov_b32_e32 v135, v117
	v_pk_add_f32 v[116:117], v[134:135], v[14:15]
	s_nop 0
	v_and_b32_sdwa v119, v116, v1 dst_sel:DWORD dst_unused:UNUSED_PAD src0_sel:WORD_1 src1_sel:DWORD
	v_and_b32_sdwa v118, v117, v1 dst_sel:DWORD dst_unused:UNUSED_PAD src0_sel:WORD_1 src1_sel:DWORD
	v_add3_u32 v119, v116, v119, s53
	v_add3_u32 v118, v117, v118, s53
	v_lshrrev_b32_e32 v119, 16, v119
	v_and_or_b32 v118, v118, s77, v119
	global_store_dword v[114:115], v118, off
	v_pk_mul_f32 v[118:119], v[6:7], v[116:117] op_sel:[1,0]
	v_lshl_add_u64 v[114:115], v[114:115], 0, s[18:19]
	v_pk_fma_f32 v[134:135], v[6:7], v[116:117], v[118:119] op_sel:[0,0,1] op_sel_hi:[1,1,0] neg_lo:[0,0,1] neg_hi:[0,0,1]
	v_pk_fma_f32 v[116:117], v[6:7], v[116:117], v[118:119] op_sel:[0,0,1] op_sel_hi:[0,1,0]
	v_mov_b32_e32 v135, v117
	v_pk_add_f32 v[116:117], v[134:135], v[12:13]
	s_nop 0
	v_and_b32_sdwa v119, v116, v1 dst_sel:DWORD dst_unused:UNUSED_PAD src0_sel:WORD_1 src1_sel:DWORD
	v_and_b32_sdwa v118, v117, v1 dst_sel:DWORD dst_unused:UNUSED_PAD src0_sel:WORD_1 src1_sel:DWORD
	v_add3_u32 v119, v116, v119, s53
	v_add3_u32 v118, v117, v118, s53
	v_lshrrev_b32_e32 v119, 16, v119
	v_and_or_b32 v118, v118, s77, v119
	global_store_dword v[114:115], v118, off
	v_pk_mul_f32 v[118:119], v[6:7], v[116:117] op_sel:[1,0]
	v_lshl_add_u64 v[114:115], v[114:115], 0, s[18:19]
	v_pk_fma_f32 v[134:135], v[6:7], v[116:117], v[118:119] op_sel:[0,0,1] op_sel_hi:[1,1,0] neg_lo:[0,0,1] neg_hi:[0,0,1]
	v_pk_fma_f32 v[116:117], v[6:7], v[116:117], v[118:119] op_sel:[0,0,1] op_sel_hi:[0,1,0]
	v_mov_b32_e32 v135, v117
	v_pk_add_f32 v[116:117], v[134:135], v[10:11]
	s_nop 0
	v_and_b32_sdwa v119, v116, v1 dst_sel:DWORD dst_unused:UNUSED_PAD src0_sel:WORD_1 src1_sel:DWORD
	v_and_b32_sdwa v118, v117, v1 dst_sel:DWORD dst_unused:UNUSED_PAD src0_sel:WORD_1 src1_sel:DWORD
	v_add3_u32 v119, v116, v119, s53
	v_add3_u32 v118, v117, v118, s53
	v_lshrrev_b32_e32 v119, 16, v119
	v_and_or_b32 v118, v118, s77, v119
	global_store_dword v[114:115], v118, off
	v_pk_mul_f32 v[118:119], v[6:7], v[116:117] op_sel:[1,0]
	v_lshl_add_u64 v[114:115], v[114:115], 0, s[18:19]
	v_pk_fma_f32 v[134:135], v[6:7], v[116:117], v[118:119] op_sel:[0,0,1] op_sel_hi:[1,1,0] neg_lo:[0,0,1] neg_hi:[0,0,1]
	v_pk_fma_f32 v[116:117], v[6:7], v[116:117], v[118:119] op_sel:[0,0,1] op_sel_hi:[0,1,0]
	v_mov_b32_e32 v135, v117
	v_pk_add_f32 v[116:117], v[134:135], v[8:9]
	s_nop 0
	v_and_b32_sdwa v119, v116, v1 dst_sel:DWORD dst_unused:UNUSED_PAD src0_sel:WORD_1 src1_sel:DWORD
	v_and_b32_sdwa v118, v117, v1 dst_sel:DWORD dst_unused:UNUSED_PAD src0_sel:WORD_1 src1_sel:DWORD
	v_add3_u32 v119, v116, v119, s53
	v_add3_u32 v118, v117, v118, s53
	v_lshrrev_b32_e32 v119, 16, v119
	v_pk_mul_f32 v[134:135], v[6:7], v[116:117] op_sel:[1,0]
	v_and_or_b32 v118, v118, s77, v119
	v_pk_fma_f32 v[136:137], v[6:7], v[116:117], v[134:135] op_sel:[0,0,1] op_sel_hi:[1,1,0] neg_lo:[0,0,1] neg_hi:[0,0,1]
	v_pk_fma_f32 v[116:117], v[6:7], v[116:117], v[134:135] op_sel:[0,0,1] op_sel_hi:[0,1,0]
	global_store_dword v[114:115], v118, off
	v_lshlrev_b32_e32 v118, 16, v133
	v_and_b32_e32 v119, 0xffff0000, v133
	v_mov_b32_e32 v137, v117
	v_pk_add_f32 v[116:117], v[136:137], v[118:119]
	v_lshl_add_u64 v[114:115], v[114:115], 0, s[18:19]
	v_and_b32_sdwa v119, v116, v1 dst_sel:DWORD dst_unused:UNUSED_PAD src0_sel:WORD_1 src1_sel:DWORD
	v_and_b32_sdwa v118, v117, v1 dst_sel:DWORD dst_unused:UNUSED_PAD src0_sel:WORD_1 src1_sel:DWORD
	v_add3_u32 v119, v116, v119, s53
	v_add3_u32 v118, v117, v118, s53
	v_lshrrev_b32_e32 v119, 16, v119
	v_pk_mul_f32 v[134:135], v[6:7], v[116:117] op_sel:[1,0]
	v_and_or_b32 v118, v118, s77, v119
	v_pk_fma_f32 v[136:137], v[6:7], v[116:117], v[134:135] op_sel:[0,0,1] op_sel_hi:[1,1,0] neg_lo:[0,0,1] neg_hi:[0,0,1]
	v_pk_fma_f32 v[116:117], v[6:7], v[116:117], v[134:135] op_sel:[0,0,1] op_sel_hi:[0,1,0]
	global_store_dword v[114:115], v118, off
	v_lshlrev_b32_e32 v118, 16, v132
	v_and_b32_e32 v119, 0xffff0000, v132
	v_mov_b32_e32 v137, v117
	v_pk_add_f32 v[116:117], v[136:137], v[118:119]
	v_lshl_add_u64 v[114:115], v[114:115], 0, s[18:19]
	v_and_b32_sdwa v119, v116, v1 dst_sel:DWORD dst_unused:UNUSED_PAD src0_sel:WORD_1 src1_sel:DWORD
	v_and_b32_sdwa v118, v117, v1 dst_sel:DWORD dst_unused:UNUSED_PAD src0_sel:WORD_1 src1_sel:DWORD
	v_add3_u32 v119, v116, v119, s53
	v_add3_u32 v118, v117, v118, s53
	v_lshrrev_b32_e32 v119, 16, v119
	v_pk_mul_f32 v[134:135], v[6:7], v[116:117] op_sel:[1,0]
	v_and_or_b32 v118, v118, s77, v119
	v_pk_fma_f32 v[136:137], v[6:7], v[116:117], v[134:135] op_sel:[0,0,1] op_sel_hi:[1,1,0] neg_lo:[0,0,1] neg_hi:[0,0,1]
	v_pk_fma_f32 v[116:117], v[6:7], v[116:117], v[134:135] op_sel:[0,0,1] op_sel_hi:[0,1,0]
	global_store_dword v[114:115], v118, off
	v_lshlrev_b32_e32 v118, 16, v131
	v_and_b32_e32 v119, 0xffff0000, v131
	v_mov_b32_e32 v137, v117
	v_pk_add_f32 v[116:117], v[136:137], v[118:119]
	v_lshl_add_u64 v[114:115], v[114:115], 0, s[18:19]
	v_and_b32_sdwa v119, v116, v1 dst_sel:DWORD dst_unused:UNUSED_PAD src0_sel:WORD_1 src1_sel:DWORD
	v_and_b32_sdwa v118, v117, v1 dst_sel:DWORD dst_unused:UNUSED_PAD src0_sel:WORD_1 src1_sel:DWORD
	v_add3_u32 v119, v116, v119, s53
	v_add3_u32 v118, v117, v118, s53
	v_lshrrev_b32_e32 v119, 16, v119
	v_pk_mul_f32 v[134:135], v[6:7], v[116:117] op_sel:[1,0]
	v_and_or_b32 v118, v118, s77, v119
	v_pk_fma_f32 v[136:137], v[6:7], v[116:117], v[134:135] op_sel:[0,0,1] op_sel_hi:[1,1,0] neg_lo:[0,0,1] neg_hi:[0,0,1]
	v_pk_fma_f32 v[116:117], v[6:7], v[116:117], v[134:135] op_sel:[0,0,1] op_sel_hi:[0,1,0]
	global_store_dword v[114:115], v118, off
	v_lshlrev_b32_e32 v118, 16, v130
	v_and_b32_e32 v119, 0xffff0000, v130
	v_mov_b32_e32 v137, v117
	v_pk_add_f32 v[116:117], v[136:137], v[118:119]
	v_lshl_add_u64 v[114:115], v[114:115], 0, s[18:19]
	v_and_b32_sdwa v119, v116, v1 dst_sel:DWORD dst_unused:UNUSED_PAD src0_sel:WORD_1 src1_sel:DWORD
	v_and_b32_sdwa v118, v117, v1 dst_sel:DWORD dst_unused:UNUSED_PAD src0_sel:WORD_1 src1_sel:DWORD
	v_add3_u32 v119, v116, v119, s53
	v_add3_u32 v118, v117, v118, s53
	v_lshrrev_b32_e32 v119, 16, v119
	v_pk_mul_f32 v[134:135], v[6:7], v[116:117] op_sel:[1,0]
	v_and_or_b32 v118, v118, s77, v119
	v_pk_fma_f32 v[136:137], v[6:7], v[116:117], v[134:135] op_sel:[0,0,1] op_sel_hi:[1,1,0] neg_lo:[0,0,1] neg_hi:[0,0,1]
	v_pk_fma_f32 v[116:117], v[6:7], v[116:117], v[134:135] op_sel:[0,0,1] op_sel_hi:[0,1,0]
	global_store_dword v[114:115], v118, off
	v_lshlrev_b32_e32 v118, 16, v129
	v_and_b32_e32 v119, 0xffff0000, v129
	v_mov_b32_e32 v137, v117
	v_pk_add_f32 v[116:117], v[136:137], v[118:119]
	v_lshl_add_u64 v[114:115], v[114:115], 0, s[18:19]
	v_and_b32_sdwa v119, v116, v1 dst_sel:DWORD dst_unused:UNUSED_PAD src0_sel:WORD_1 src1_sel:DWORD
	v_and_b32_sdwa v118, v117, v1 dst_sel:DWORD dst_unused:UNUSED_PAD src0_sel:WORD_1 src1_sel:DWORD
	v_add3_u32 v119, v116, v119, s53
	v_add3_u32 v118, v117, v118, s53
	v_lshrrev_b32_e32 v119, 16, v119
	v_pk_mul_f32 v[134:135], v[6:7], v[116:117] op_sel:[1,0]
	v_and_or_b32 v118, v118, s77, v119
	v_pk_fma_f32 v[136:137], v[6:7], v[116:117], v[134:135] op_sel:[0,0,1] op_sel_hi:[1,1,0] neg_lo:[0,0,1] neg_hi:[0,0,1]
	v_pk_fma_f32 v[116:117], v[6:7], v[116:117], v[134:135] op_sel:[0,0,1] op_sel_hi:[0,1,0]
	global_store_dword v[114:115], v118, off
	v_lshlrev_b32_e32 v118, 16, v128
	v_and_b32_e32 v119, 0xffff0000, v128
	v_mov_b32_e32 v137, v117
	v_pk_add_f32 v[116:117], v[136:137], v[118:119]
	v_lshl_add_u64 v[114:115], v[114:115], 0, s[18:19]
	v_and_b32_sdwa v119, v116, v1 dst_sel:DWORD dst_unused:UNUSED_PAD src0_sel:WORD_1 src1_sel:DWORD
	v_and_b32_sdwa v118, v117, v1 dst_sel:DWORD dst_unused:UNUSED_PAD src0_sel:WORD_1 src1_sel:DWORD
	v_add3_u32 v119, v116, v119, s53
	v_add3_u32 v118, v117, v118, s53
	v_lshrrev_b32_e32 v119, 16, v119
	v_pk_mul_f32 v[134:135], v[6:7], v[116:117] op_sel:[1,0]
	v_and_or_b32 v118, v118, s77, v119
	v_pk_fma_f32 v[136:137], v[6:7], v[116:117], v[134:135] op_sel:[0,0,1] op_sel_hi:[1,1,0] neg_lo:[0,0,1] neg_hi:[0,0,1]
	v_pk_fma_f32 v[116:117], v[6:7], v[116:117], v[134:135] op_sel:[0,0,1] op_sel_hi:[0,1,0]
	global_store_dword v[114:115], v118, off
	v_lshlrev_b32_e32 v118, 16, v127
	v_and_b32_e32 v119, 0xffff0000, v127
	v_mov_b32_e32 v137, v117
	v_pk_add_f32 v[116:117], v[136:137], v[118:119]
	v_lshl_add_u64 v[114:115], v[114:115], 0, s[18:19]
	v_and_b32_sdwa v119, v116, v1 dst_sel:DWORD dst_unused:UNUSED_PAD src0_sel:WORD_1 src1_sel:DWORD
	v_and_b32_sdwa v118, v117, v1 dst_sel:DWORD dst_unused:UNUSED_PAD src0_sel:WORD_1 src1_sel:DWORD
	v_add3_u32 v119, v116, v119, s53
	v_add3_u32 v118, v117, v118, s53
	v_lshrrev_b32_e32 v119, 16, v119
	v_pk_mul_f32 v[134:135], v[6:7], v[116:117] op_sel:[1,0]
	v_and_or_b32 v118, v118, s77, v119
	v_pk_fma_f32 v[136:137], v[6:7], v[116:117], v[134:135] op_sel:[0,0,1] op_sel_hi:[1,1,0] neg_lo:[0,0,1] neg_hi:[0,0,1]
	v_pk_fma_f32 v[116:117], v[6:7], v[116:117], v[134:135] op_sel:[0,0,1] op_sel_hi:[0,1,0]
	global_store_dword v[114:115], v118, off
	v_lshlrev_b32_e32 v118, 16, v126
	v_and_b32_e32 v119, 0xffff0000, v126
	v_mov_b32_e32 v137, v117
	v_pk_add_f32 v[116:117], v[136:137], v[118:119]
	v_lshl_add_u64 v[114:115], v[114:115], 0, s[18:19]
	v_and_b32_sdwa v119, v116, v1 dst_sel:DWORD dst_unused:UNUSED_PAD src0_sel:WORD_1 src1_sel:DWORD
	v_and_b32_sdwa v118, v117, v1 dst_sel:DWORD dst_unused:UNUSED_PAD src0_sel:WORD_1 src1_sel:DWORD
	v_add3_u32 v119, v116, v119, s53
	v_add3_u32 v118, v117, v118, s53
	v_lshrrev_b32_e32 v119, 16, v119
	v_pk_mul_f32 v[134:135], v[6:7], v[116:117] op_sel:[1,0]
	v_and_or_b32 v118, v118, s77, v119
	v_pk_fma_f32 v[136:137], v[6:7], v[116:117], v[134:135] op_sel:[0,0,1] op_sel_hi:[1,1,0] neg_lo:[0,0,1] neg_hi:[0,0,1]
	v_pk_fma_f32 v[116:117], v[6:7], v[116:117], v[134:135] op_sel:[0,0,1] op_sel_hi:[0,1,0]
	global_store_dword v[114:115], v118, off
	v_lshlrev_b32_e32 v118, 16, v125
	v_and_b32_e32 v119, 0xffff0000, v125
	v_mov_b32_e32 v137, v117
	v_pk_add_f32 v[116:117], v[136:137], v[118:119]
	v_lshl_add_u64 v[114:115], v[114:115], 0, s[18:19]
	v_and_b32_sdwa v119, v116, v1 dst_sel:DWORD dst_unused:UNUSED_PAD src0_sel:WORD_1 src1_sel:DWORD
	v_and_b32_sdwa v118, v117, v1 dst_sel:DWORD dst_unused:UNUSED_PAD src0_sel:WORD_1 src1_sel:DWORD
	v_add3_u32 v119, v116, v119, s53
	v_add3_u32 v118, v117, v118, s53
	v_lshrrev_b32_e32 v119, 16, v119
	v_pk_mul_f32 v[134:135], v[6:7], v[116:117] op_sel:[1,0]
	v_and_or_b32 v118, v118, s77, v119
	v_pk_fma_f32 v[136:137], v[6:7], v[116:117], v[134:135] op_sel:[0,0,1] op_sel_hi:[1,1,0] neg_lo:[0,0,1] neg_hi:[0,0,1]
	v_pk_fma_f32 v[116:117], v[6:7], v[116:117], v[134:135] op_sel:[0,0,1] op_sel_hi:[0,1,0]
	global_store_dword v[114:115], v118, off
	v_lshlrev_b32_e32 v118, 16, v124
	v_and_b32_e32 v119, 0xffff0000, v124
	v_mov_b32_e32 v137, v117
	v_pk_add_f32 v[118:119], v[136:137], v[118:119]
	v_lshl_add_u64 v[114:115], v[114:115], 0, s[18:19]
	v_and_b32_sdwa v117, v118, v1 dst_sel:DWORD dst_unused:UNUSED_PAD src0_sel:WORD_1 src1_sel:DWORD
	v_and_b32_sdwa v116, v119, v1 dst_sel:DWORD dst_unused:UNUSED_PAD src0_sel:WORD_1 src1_sel:DWORD
	v_add3_u32 v117, v118, v117, s53
	v_add3_u32 v116, v119, v116, s53
	v_lshrrev_b32_e32 v117, 16, v117
	v_and_or_b32 v116, v116, s77, v117
	global_store_dword v[114:115], v116, off
	v_lshl_add_u64 v[116:117], v[114:115], 0, s[18:19]
	v_and_b32_e32 v115, 0xffff0000, v120
	v_lshlrev_b32_e32 v114, 16, v120
	v_pk_mul_f32 v[120:121], v[6:7], v[118:119] op_sel:[1,1] op_sel_hi:[0,1]
	v_pk_fma_f32 v[134:135], v[6:7], v[118:119], v[120:121] op_sel_hi:[1,0,1]
	v_pk_fma_f32 v[118:119], v[6:7], v[118:119], v[120:121] op_sel_hi:[1,0,1] neg_lo:[0,0,1] neg_hi:[0,0,1]
	s_nop 0
	v_mov_b32_e32 v119, v135
	v_pk_add_f32 v[118:119], v[118:119], v[114:115]

.LBB0_1806:
	s_add_i32 s14, s4, s94
	s_cmpk_lt_i32 s14, 0x4200
	s_cselect_b64 s[8:9], -1, 0
	s_and_b64 s[0:1], s[8:9], exec
	s_cselect_b32 s6, s14, s4
	s_ashr_i32 s7, s6, 31
	s_lshl_b64 s[0:1], s[6:7], 12
	v_lshl_add_u64 v[32:33], v[80:81], 0, s[0:1]
	s_waitcnt vmcnt(0)
	global_load_dwordx4 v[62:65], v[32:33], off
	global_load_dwordx4 v[58:61], v[32:33], off offset:1024
	global_load_dwordx4 v[54:57], v[32:33], off offset:2048
	global_load_dwordx4 v[50:53], v[32:33], off offset:3072
	v_cvt_f32_f16_sdwa v167, v46 dst_sel:DWORD dst_unused:UNUSED_PAD src0_sel:WORD_1
	v_cvt_f32_f16_e32 v166, v46
	v_cvt_f32_f16_sdwa v163, v47 dst_sel:DWORD dst_unused:UNUSED_PAD src0_sel:WORD_1
	v_cvt_f32_f16_e32 v162, v47
	v_cvt_f32_f16_sdwa v161, v48 dst_sel:DWORD dst_unused:UNUSED_PAD src0_sel:WORD_1
	v_cvt_f32_f16_e32 v160, v48
	v_cvt_f32_f16_sdwa v165, v49 dst_sel:DWORD dst_unused:UNUSED_PAD src0_sel:WORD_1
	v_cvt_f32_f16_e32 v164, v49
	v_cvt_f32_f16_sdwa v155, v42 dst_sel:DWORD dst_unused:UNUSED_PAD src0_sel:WORD_1
	v_cvt_f32_f16_e32 v154, v42
	v_cvt_f32_f16_sdwa v157, v43 dst_sel:DWORD dst_unused:UNUSED_PAD src0_sel:WORD_1
	v_cvt_f32_f16_e32 v156, v43
	v_cvt_f32_f16_sdwa v153, v44 dst_sel:DWORD dst_unused:UNUSED_PAD src0_sel:WORD_1
	v_cvt_f32_f16_e32 v152, v44
	v_cvt_f32_f16_sdwa v159, v45 dst_sel:DWORD dst_unused:UNUSED_PAD src0_sel:WORD_1
	v_cvt_f32_f16_e32 v158, v45
	v_cvt_f32_f16_sdwa v45, v38 dst_sel:DWORD dst_unused:UNUSED_PAD src0_sel:WORD_1
	v_cvt_f32_f16_e32 v44, v38
	v_cvt_f32_f16_sdwa v47, v39 dst_sel:DWORD dst_unused:UNUSED_PAD src0_sel:WORD_1
	v_cvt_f32_f16_e32 v46, v39
	v_cvt_f32_f16_sdwa v43, v40 dst_sel:DWORD dst_unused:UNUSED_PAD src0_sel:WORD_1
	v_cvt_f32_f16_e32 v42, v40
	v_cvt_f32_f16_sdwa v49, v41 dst_sel:DWORD dst_unused:UNUSED_PAD src0_sel:WORD_1
	v_cvt_f32_f16_e32 v48, v41
	v_cvt_f32_f16_sdwa v39, v34 dst_sel:DWORD dst_unused:UNUSED_PAD src0_sel:WORD_1
	v_cvt_f32_f16_e32 v38, v34
	v_cvt_f32_f16_sdwa v41, v35 dst_sel:DWORD dst_unused:UNUSED_PAD src0_sel:WORD_1
	v_cvt_f32_f16_e32 v40, v35
	v_cvt_f32_f16_sdwa v33, v36 dst_sel:DWORD dst_unused:UNUSED_PAD src0_sel:WORD_1
	v_cvt_f32_f16_e32 v32, v36
	v_cvt_f32_f16_sdwa v35, v37 dst_sel:DWORD dst_unused:UNUSED_PAD src0_sel:WORD_1
	v_cvt_f32_f16_e32 v34, v37
	s_cmpk_gt_i32 s4, 0x3fff
	s_cselect_b64 s[2:3], -1, 0
	s_cmpk_lt_i32 s4, 0x4000
	s_cbranch_scc1 .LBB0_1808
	s_add_i32 s86, s4, 0xffffc000
	s_lshl_b64 s[0:1], s[86:87], 13
	v_lshl_add_u64 v[36:37], v[82:83], 0, s[0:1]
	global_load_dwordx4 v[190:193], v[36:37], off nt
	global_load_dwordx4 v[194:197], v[36:37], off offset:16 nt
	global_load_dwordx4 v[198:201], v[36:37], off offset:2048 nt
	global_load_dwordx4 v[204:207], v[36:37], off offset:2064 nt
	s_mov_b64 s[0:1], 0x400000
	v_lshl_add_u64 v[232:233], v[36:37], 0, s[0:1]
	global_load_dwordx4 v[208:211], v[232:233], off nt
	global_load_dwordx4 v[212:215], v[232:233], off offset:16 nt
	global_load_dwordx4 v[216:219], v[232:233], off offset:2048 nt
	global_load_dwordx4 v[220:223], v[232:233], off offset:2064 nt
	s_mov_b64 s[0:1], 0x800000
	v_lshl_add_u64 v[232:233], v[36:37], 0, s[0:1]
	global_load_dwordx4 v[224:227], v[232:233], off nt
	global_load_dwordx4 v[228:231], v[232:233], off offset:16 nt
	global_load_dwordx4 v[238:241], v[232:233], off offset:2048 nt
	global_load_dwordx4 v[242:245], v[232:233], off offset:2064 nt
	s_waitcnt vmcnt(8)
	v_mov_b64_e32 v[174:175], v[190:191]
	v_mov_b64_e32 v[176:177], v[192:193]
	v_mov_b64_e32 v[178:179], v[194:195]
	v_mov_b64_e32 v[180:181], v[196:197]
	v_mov_b64_e32 v[182:183], v[198:199]
	v_mov_b64_e32 v[184:185], v[200:201]
	v_mov_b64_e32 v[186:187], v[204:205]
	v_mov_b64_e32 v[188:189], v[206:207]
	s_mov_b64 s[0:1], 0xc00000
	v_lshl_add_u64 v[232:233], v[36:37], 0, s[0:1]
	global_load_dwordx4 v[190:193], v[232:233], off nt
	global_load_dwordx4 v[194:197], v[232:233], off offset:16 nt
	global_load_dwordx4 v[198:201], v[232:233], off offset:2048 nt
	global_load_dwordx4 v[204:207], v[232:233], off offset:2064 nt
	s_waitcnt vmcnt(8)
	v_pk_add_f32 v[174:175], v[174:175], v[208:209]
	v_pk_add_f32 v[176:177], v[176:177], v[210:211]
	v_pk_add_f32 v[178:179], v[178:179], v[212:213]
	v_pk_add_f32 v[180:181], v[180:181], v[214:215]
	v_pk_add_f32 v[182:183], v[182:183], v[216:217]
	v_pk_add_f32 v[184:185], v[184:185], v[218:219]
	v_pk_add_f32 v[186:187], v[186:187], v[220:221]
	v_pk_add_f32 v[188:189], v[188:189], v[222:223]
	s_mov_b64 s[0:1], 0x1000000
	v_lshl_add_u64 v[232:233], v[36:37], 0, s[0:1]
	global_load_dwordx4 v[208:211], v[232:233], off nt
	global_load_dwordx4 v[212:215], v[232:233], off offset:16 nt
	global_load_dwordx4 v[216:219], v[232:233], off offset:2048 nt
	global_load_dwordx4 v[220:223], v[232:233], off offset:2064 nt
	s_waitcnt vmcnt(8)
	v_pk_add_f32 v[174:175], v[174:175], v[224:225]
	v_pk_add_f32 v[176:177], v[176:177], v[226:227]
	v_pk_add_f32 v[178:179], v[178:179], v[228:229]
	v_pk_add_f32 v[180:181], v[180:181], v[230:231]
	v_pk_add_f32 v[182:183], v[182:183], v[238:239]
	v_pk_add_f32 v[184:185], v[184:185], v[240:241]
	v_pk_add_f32 v[186:187], v[186:187], v[242:243]
	v_pk_add_f32 v[188:189], v[188:189], v[244:245]
	s_mov_b64 s[0:1], 0x1400000
	v_lshl_add_u64 v[232:233], v[36:37], 0, s[0:1]
	global_load_dwordx4 v[224:227], v[232:233], off nt
	global_load_dwordx4 v[228:231], v[232:233], off offset:16 nt
	global_load_dwordx4 v[238:241], v[232:233], off offset:2048 nt
	global_load_dwordx4 v[242:245], v[232:233], off offset:2064 nt
	s_waitcnt vmcnt(8)
	v_pk_add_f32 v[174:175], v[174:175], v[190:191]
	v_pk_add_f32 v[176:177], v[176:177], v[192:193]
	v_pk_add_f32 v[178:179], v[178:179], v[194:195]
	v_pk_add_f32 v[180:181], v[180:181], v[196:197]
	v_pk_add_f32 v[182:183], v[182:183], v[198:199]
	v_pk_add_f32 v[184:185], v[184:185], v[200:201]
	v_pk_add_f32 v[186:187], v[186:187], v[204:205]
	v_pk_add_f32 v[188:189], v[188:189], v[206:207]
	s_mov_b64 s[0:1], 0x1800000
	v_lshl_add_u64 v[232:233], v[36:37], 0, s[0:1]
	global_load_dwordx4 v[190:193], v[232:233], off nt
	global_load_dwordx4 v[194:197], v[232:233], off offset:16 nt
	global_load_dwordx4 v[198:201], v[232:233], off offset:2048 nt
	global_load_dwordx4 v[204:207], v[232:233], off offset:2064 nt
	s_waitcnt vmcnt(8)
	v_pk_add_f32 v[174:175], v[174:175], v[208:209]
	v_pk_add_f32 v[176:177], v[176:177], v[210:211]
	v_pk_add_f32 v[178:179], v[178:179], v[212:213]
	v_pk_add_f32 v[180:181], v[180:181], v[214:215]
	v_pk_add_f32 v[182:183], v[182:183], v[216:217]
	v_pk_add_f32 v[184:185], v[184:185], v[218:219]
	v_pk_add_f32 v[186:187], v[186:187], v[220:221]
	v_pk_add_f32 v[188:189], v[188:189], v[222:223]
	s_mov_b64 s[0:1], 0x1c00000
	v_lshl_add_u64 v[232:233], v[36:37], 0, s[0:1]
	global_load_dwordx4 v[208:211], v[232:233], off nt
	global_load_dwordx4 v[212:215], v[232:233], off offset:16 nt
	global_load_dwordx4 v[216:219], v[232:233], off offset:2048 nt
	global_load_dwordx4 v[220:223], v[232:233], off offset:2064 nt
	s_waitcnt vmcnt(8)
	v_pk_add_f32 v[174:175], v[174:175], v[224:225]
	v_pk_add_f32 v[176:177], v[176:177], v[226:227]
	v_pk_add_f32 v[178:179], v[178:179], v[228:229]
	v_pk_add_f32 v[180:181], v[180:181], v[230:231]
	v_pk_add_f32 v[182:183], v[182:183], v[238:239]
	v_pk_add_f32 v[184:185], v[184:185], v[240:241]
	v_pk_add_f32 v[186:187], v[186:187], v[242:243]
	v_pk_add_f32 v[188:189], v[188:189], v[244:245]
	s_mov_b64 s[0:1], 0x2000000
	v_lshl_add_u64 v[232:233], v[36:37], 0, s[0:1]
	global_load_dwordx4 v[224:227], v[232:233], off nt
	global_load_dwordx4 v[228:231], v[232:233], off offset:16 nt
	global_load_dwordx4 v[238:241], v[232:233], off offset:2048 nt
	global_load_dwordx4 v[242:245], v[232:233], off offset:2064 nt
	s_waitcnt vmcnt(8)
	v_pk_add_f32 v[174:175], v[174:175], v[190:191]
	v_pk_add_f32 v[176:177], v[176:177], v[192:193]
	v_pk_add_f32 v[178:179], v[178:179], v[194:195]
	v_pk_add_f32 v[180:181], v[180:181], v[196:197]
	v_pk_add_f32 v[182:183], v[182:183], v[198:199]
	v_pk_add_f32 v[184:185], v[184:185], v[200:201]
	v_pk_add_f32 v[186:187], v[186:187], v[204:205]
	v_pk_add_f32 v[188:189], v[188:189], v[206:207]
	s_mov_b64 s[0:1], 0x2400000
	v_lshl_add_u64 v[232:233], v[36:37], 0, s[0:1]
	global_load_dwordx4 v[190:193], v[232:233], off nt
	global_load_dwordx4 v[194:197], v[232:233], off offset:16 nt
	global_load_dwordx4 v[198:201], v[232:233], off offset:2048 nt
	global_load_dwordx4 v[204:207], v[232:233], off offset:2064 nt
	s_waitcnt vmcnt(8)
	v_pk_add_f32 v[174:175], v[174:175], v[208:209]
	v_pk_add_f32 v[176:177], v[176:177], v[210:211]
	v_pk_add_f32 v[178:179], v[178:179], v[212:213]
	v_pk_add_f32 v[180:181], v[180:181], v[214:215]
	v_pk_add_f32 v[182:183], v[182:183], v[216:217]
	v_pk_add_f32 v[184:185], v[184:185], v[218:219]
	v_pk_add_f32 v[186:187], v[186:187], v[220:221]
	v_pk_add_f32 v[188:189], v[188:189], v[222:223]
	s_mov_b64 s[0:1], 0x2800000
	v_lshl_add_u64 v[232:233], v[36:37], 0, s[0:1]
	global_load_dwordx4 v[208:211], v[232:233], off nt
	global_load_dwordx4 v[212:215], v[232:233], off offset:16 nt
	global_load_dwordx4 v[216:219], v[232:233], off offset:2048 nt
	global_load_dwordx4 v[220:223], v[232:233], off offset:2064 nt
	s_waitcnt vmcnt(8)
	v_pk_add_f32 v[174:175], v[174:175], v[224:225]
	v_pk_add_f32 v[176:177], v[176:177], v[226:227]
	v_pk_add_f32 v[178:179], v[178:179], v[228:229]
	v_pk_add_f32 v[180:181], v[180:181], v[230:231]
	v_pk_add_f32 v[182:183], v[182:183], v[238:239]
	v_pk_add_f32 v[184:185], v[184:185], v[240:241]
	v_pk_add_f32 v[186:187], v[186:187], v[242:243]
	v_pk_add_f32 v[188:189], v[188:189], v[244:245]
	global_load_dwordx4 v[224:227], v[74:75], off
	global_load_dwordx4 v[228:231], v[74:75], off offset:16
	global_load_dwordx4 v[238:241], v[74:75], off offset:2048
	global_load_dwordx4 v[242:245], v[74:75], off offset:2064
	s_waitcnt vmcnt(8)
	v_pk_add_f32 v[174:175], v[174:175], v[190:191]
	v_pk_add_f32 v[176:177], v[176:177], v[192:193]
	v_pk_add_f32 v[178:179], v[178:179], v[194:195]
	v_pk_add_f32 v[180:181], v[180:181], v[196:197]
	v_pk_add_f32 v[182:183], v[182:183], v[198:199]
	v_pk_add_f32 v[184:185], v[184:185], v[200:201]
	v_pk_add_f32 v[186:187], v[186:187], v[204:205]
	v_pk_add_f32 v[188:189], v[188:189], v[206:207]
	s_mov_b64 s[0:1], 0x1000
	v_lshl_add_u64 v[232:233], v[36:37], 0, s[0:1]
	global_load_dwordx4 v[190:193], v[232:233], off nt
	global_load_dwordx4 v[194:197], v[232:233], off offset:16 nt
	global_load_dwordx4 v[198:201], v[232:233], off offset:2048 nt
	global_load_dwordx4 v[204:207], v[232:233], off offset:2064 nt
	s_waitcnt vmcnt(8)
	v_pk_add_f32 v[174:175], v[174:175], v[208:209]
	v_pk_add_f32 v[176:177], v[176:177], v[210:211]
	v_pk_add_f32 v[178:179], v[178:179], v[212:213]
	v_pk_add_f32 v[180:181], v[180:181], v[214:215]
	v_pk_add_f32 v[182:183], v[182:183], v[216:217]
	v_pk_add_f32 v[184:185], v[184:185], v[218:219]
	v_pk_add_f32 v[186:187], v[186:187], v[220:221]
	v_pk_add_f32 v[188:189], v[188:189], v[222:223]
	s_mov_b64 s[0:1], 0x401000
	v_lshl_add_u64 v[232:233], v[36:37], 0, s[0:1]
	global_load_dwordx4 v[208:211], v[232:233], off nt
	global_load_dwordx4 v[212:215], v[232:233], off offset:16 nt
	global_load_dwordx4 v[216:219], v[232:233], off offset:2048 nt
	global_load_dwordx4 v[220:223], v[232:233], off offset:2064 nt
	s_waitcnt vmcnt(8)
	v_pk_fma_f32 v[166:167], v[174:175], v[224:225], v[166:167]
	v_pk_fma_f32 v[162:163], v[176:177], v[226:227], v[162:163]
	v_pk_fma_f32 v[160:161], v[178:179], v[228:229], v[160:161]
	v_pk_fma_f32 v[164:165], v[180:181], v[230:231], v[164:165]
	v_pk_fma_f32 v[154:155], v[182:183], v[238:239], v[154:155]
	v_pk_fma_f32 v[156:157], v[184:185], v[240:241], v[156:157]
	v_pk_fma_f32 v[152:153], v[186:187], v[242:243], v[152:153]
	v_pk_fma_f32 v[158:159], v[188:189], v[244:245], v[158:159]
	s_mov_b64 s[0:1], 0x801000
	v_lshl_add_u64 v[232:233], v[36:37], 0, s[0:1]
	global_load_dwordx4 v[224:227], v[232:233], off nt
	global_load_dwordx4 v[228:231], v[232:233], off offset:16 nt
	global_load_dwordx4 v[238:241], v[232:233], off offset:2048 nt
	global_load_dwordx4 v[242:245], v[232:233], off offset:2064 nt
	s_waitcnt vmcnt(8)
	v_mov_b64_e32 v[174:175], v[190:191]
	v_mov_b64_e32 v[176:177], v[192:193]
	v_mov_b64_e32 v[178:179], v[194:195]
	v_mov_b64_e32 v[180:181], v[196:197]
	v_mov_b64_e32 v[182:183], v[198:199]
	v_mov_b64_e32 v[184:185], v[200:201]
	v_mov_b64_e32 v[186:187], v[204:205]
	v_mov_b64_e32 v[188:189], v[206:207]
	s_mov_b64 s[0:1], 0xc01000
	v_lshl_add_u64 v[232:233], v[36:37], 0, s[0:1]
	global_load_dwordx4 v[190:193], v[232:233], off nt
	global_load_dwordx4 v[194:197], v[232:233], off offset:16 nt
	global_load_dwordx4 v[198:201], v[232:233], off offset:2048 nt
	global_load_dwordx4 v[204:207], v[232:233], off offset:2064 nt
	s_waitcnt vmcnt(8)
	v_pk_add_f32 v[174:175], v[174:175], v[208:209]
	v_pk_add_f32 v[176:177], v[176:177], v[210:211]
	v_pk_add_f32 v[178:179], v[178:179], v[212:213]
	v_pk_add_f32 v[180:181], v[180:181], v[214:215]
	v_pk_add_f32 v[182:183], v[182:183], v[216:217]
	v_pk_add_f32 v[184:185], v[184:185], v[218:219]
	v_pk_add_f32 v[186:187], v[186:187], v[220:221]
	v_pk_add_f32 v[188:189], v[188:189], v[222:223]
	s_mov_b64 s[0:1], 0x1001000
	v_lshl_add_u64 v[232:233], v[36:37], 0, s[0:1]
	global_load_dwordx4 v[208:211], v[232:233], off nt
	global_load_dwordx4 v[212:215], v[232:233], off offset:16 nt
	global_load_dwordx4 v[216:219], v[232:233], off offset:2048 nt
	global_load_dwordx4 v[220:223], v[232:233], off offset:2064 nt
	s_waitcnt vmcnt(8)
	v_pk_add_f32 v[174:175], v[174:175], v[224:225]
	v_pk_add_f32 v[176:177], v[176:177], v[226:227]
	v_pk_add_f32 v[178:179], v[178:179], v[228:229]
	v_pk_add_f32 v[180:181], v[180:181], v[230:231]
	v_pk_add_f32 v[182:183], v[182:183], v[238:239]
	v_pk_add_f32 v[184:185], v[184:185], v[240:241]
	v_pk_add_f32 v[186:187], v[186:187], v[242:243]
	v_pk_add_f32 v[188:189], v[188:189], v[244:245]
	s_mov_b64 s[0:1], 0x1401000
	v_lshl_add_u64 v[232:233], v[36:37], 0, s[0:1]
	global_load_dwordx4 v[224:227], v[232:233], off nt
	global_load_dwordx4 v[228:231], v[232:233], off offset:16 nt
	global_load_dwordx4 v[238:241], v[232:233], off offset:2048 nt
	global_load_dwordx4 v[242:245], v[232:233], off offset:2064 nt
	s_waitcnt vmcnt(8)
	v_pk_add_f32 v[174:175], v[174:175], v[190:191]
	v_pk_add_f32 v[176:177], v[176:177], v[192:193]
	v_pk_add_f32 v[178:179], v[178:179], v[194:195]
	v_pk_add_f32 v[180:181], v[180:181], v[196:197]
	v_pk_add_f32 v[182:183], v[182:183], v[198:199]
	v_pk_add_f32 v[184:185], v[184:185], v[200:201]
	v_pk_add_f32 v[186:187], v[186:187], v[204:205]
	v_pk_add_f32 v[188:189], v[188:189], v[206:207]
	s_mov_b64 s[0:1], 0x1801000
	v_lshl_add_u64 v[232:233], v[36:37], 0, s[0:1]
	global_load_dwordx4 v[190:193], v[232:233], off nt
	global_load_dwordx4 v[194:197], v[232:233], off offset:16 nt
	global_load_dwordx4 v[198:201], v[232:233], off offset:2048 nt
	global_load_dwordx4 v[204:207], v[232:233], off offset:2064 nt
	s_waitcnt vmcnt(8)
	v_pk_add_f32 v[174:175], v[174:175], v[208:209]
	v_pk_add_f32 v[176:177], v[176:177], v[210:211]
	v_pk_add_f32 v[178:179], v[178:179], v[212:213]
	v_pk_add_f32 v[180:181], v[180:181], v[214:215]
	v_pk_add_f32 v[182:183], v[182:183], v[216:217]
	v_pk_add_f32 v[184:185], v[184:185], v[218:219]
	v_pk_add_f32 v[186:187], v[186:187], v[220:221]
	v_pk_add_f32 v[188:189], v[188:189], v[222:223]
	s_mov_b64 s[0:1], 0x1c01000
	v_lshl_add_u64 v[232:233], v[36:37], 0, s[0:1]
	global_load_dwordx4 v[208:211], v[232:233], off nt
	global_load_dwordx4 v[212:215], v[232:233], off offset:16 nt
	global_load_dwordx4 v[216:219], v[232:233], off offset:2048 nt
	global_load_dwordx4 v[220:223], v[232:233], off offset:2064 nt
	s_waitcnt vmcnt(8)
	v_pk_add_f32 v[174:175], v[174:175], v[224:225]
	v_pk_add_f32 v[176:177], v[176:177], v[226:227]
	v_pk_add_f32 v[178:179], v[178:179], v[228:229]
	v_pk_add_f32 v[180:181], v[180:181], v[230:231]
	v_pk_add_f32 v[182:183], v[182:183], v[238:239]
	v_pk_add_f32 v[184:185], v[184:185], v[240:241]
	v_pk_add_f32 v[186:187], v[186:187], v[242:243]
	v_pk_add_f32 v[188:189], v[188:189], v[244:245]
	s_mov_b64 s[0:1], 0x2001000
	v_lshl_add_u64 v[232:233], v[36:37], 0, s[0:1]
	global_load_dwordx4 v[224:227], v[232:233], off nt
	global_load_dwordx4 v[228:231], v[232:233], off offset:16 nt
	global_load_dwordx4 v[238:241], v[232:233], off offset:2048 nt
	global_load_dwordx4 v[242:245], v[232:233], off offset:2064 nt
	s_waitcnt vmcnt(8)
	v_pk_add_f32 v[174:175], v[174:175], v[190:191]
	v_pk_add_f32 v[176:177], v[176:177], v[192:193]
	v_pk_add_f32 v[178:179], v[178:179], v[194:195]
	v_pk_add_f32 v[180:181], v[180:181], v[196:197]
	v_pk_add_f32 v[182:183], v[182:183], v[198:199]
	v_pk_add_f32 v[184:185], v[184:185], v[200:201]
	v_pk_add_f32 v[186:187], v[186:187], v[204:205]
	v_pk_add_f32 v[188:189], v[188:189], v[206:207]
	s_mov_b64 s[0:1], 0x2401000
	v_lshl_add_u64 v[232:233], v[36:37], 0, s[0:1]
	global_load_dwordx4 v[190:193], v[232:233], off nt
	global_load_dwordx4 v[194:197], v[232:233], off offset:16 nt
	global_load_dwordx4 v[198:201], v[232:233], off offset:2048 nt
	global_load_dwordx4 v[204:207], v[232:233], off offset:2064 nt
	s_waitcnt vmcnt(8)
	v_pk_add_f32 v[174:175], v[174:175], v[208:209]
	v_pk_add_f32 v[176:177], v[176:177], v[210:211]
	v_pk_add_f32 v[178:179], v[178:179], v[212:213]
	v_pk_add_f32 v[180:181], v[180:181], v[214:215]
	v_pk_add_f32 v[182:183], v[182:183], v[216:217]
	v_pk_add_f32 v[184:185], v[184:185], v[218:219]
	v_pk_add_f32 v[186:187], v[186:187], v[220:221]
	v_pk_add_f32 v[188:189], v[188:189], v[222:223]
	s_mov_b64 s[0:1], 0x2801000
	v_lshl_add_u64 v[232:233], v[36:37], 0, s[0:1]
	global_load_dwordx4 v[208:211], v[232:233], off nt
	global_load_dwordx4 v[212:215], v[232:233], off offset:16 nt
	global_load_dwordx4 v[216:219], v[232:233], off offset:2048 nt
	global_load_dwordx4 v[220:223], v[232:233], off offset:2064 nt
	s_waitcnt vmcnt(8)
	v_pk_add_f32 v[174:175], v[174:175], v[224:225]
	v_pk_add_f32 v[176:177], v[176:177], v[226:227]
	v_pk_add_f32 v[178:179], v[178:179], v[228:229]
	v_pk_add_f32 v[180:181], v[180:181], v[230:231]
	v_pk_add_f32 v[182:183], v[182:183], v[238:239]
	v_pk_add_f32 v[184:185], v[184:185], v[240:241]
	v_pk_add_f32 v[186:187], v[186:187], v[242:243]
	v_pk_add_f32 v[188:189], v[188:189], v[244:245]
	global_load_dwordx4 v[224:227], v[76:77], off
	global_load_dwordx4 v[228:231], v[76:77], off offset:16
	global_load_dwordx4 v[238:241], v[78:79], off
	global_load_dwordx4 v[242:245], v[78:79], off offset:16
	s_waitcnt vmcnt(8)
	v_pk_add_f32 v[174:175], v[174:175], v[190:191]
	v_pk_add_f32 v[176:177], v[176:177], v[192:193]
	v_pk_add_f32 v[178:179], v[178:179], v[194:195]
	v_pk_add_f32 v[180:181], v[180:181], v[196:197]
	v_pk_add_f32 v[182:183], v[182:183], v[198:199]
	v_pk_add_f32 v[184:185], v[184:185], v[200:201]
	v_pk_add_f32 v[186:187], v[186:187], v[204:205]
	v_pk_add_f32 v[188:189], v[188:189], v[206:207]
	s_waitcnt vmcnt(4)
	v_pk_add_f32 v[174:175], v[174:175], v[208:209]
	v_pk_add_f32 v[176:177], v[176:177], v[210:211]
	v_pk_add_f32 v[178:179], v[178:179], v[212:213]
	v_pk_add_f32 v[180:181], v[180:181], v[214:215]
	v_pk_add_f32 v[182:183], v[182:183], v[216:217]
	v_pk_add_f32 v[184:185], v[184:185], v[218:219]
	v_pk_add_f32 v[186:187], v[186:187], v[220:221]
	v_pk_add_f32 v[188:189], v[188:189], v[222:223]
	s_waitcnt vmcnt(0)
	v_pk_fma_f32 v[44:45], v[174:175], v[224:225], v[44:45]
	v_pk_fma_f32 v[46:47], v[176:177], v[226:227], v[46:47]
	v_pk_fma_f32 v[42:43], v[178:179], v[228:229], v[42:43]
	v_pk_fma_f32 v[48:49], v[180:181], v[230:231], v[48:49]
	v_pk_fma_f32 v[38:39], v[182:183], v[238:239], v[38:39]
	v_pk_fma_f32 v[40:41], v[184:185], v[240:241], v[40:41]
	v_pk_fma_f32 v[32:33], v[186:187], v[242:243], v[32:33]
	v_pk_fma_f32 v[34:35], v[188:189], v[244:245], v[34:35]

.LBB0_1812:
	s_add_i32 s0, s75, s4
	s_cmpk_lt_i32 s0, 0x4200
	s_cselect_b32 s0, s0, s4
	s_ashr_i32 s1, s0, 31
	s_lshl_b64 s[0:1], s[0:1], 12
	v_lshl_add_u64 v[32:33], v[80:81], 0, s[0:1]
	global_load_dwordx4 v[46:49], v[32:33], off
	global_load_dwordx4 v[42:45], v[32:33], off offset:1024
	global_load_dwordx4 v[38:41], v[32:33], off offset:2048
	global_load_dwordx4 v[34:37], v[32:33], off offset:3072
	s_waitcnt vmcnt(4)
	s_andn2_b64 vcc, exec, s[8:9]
	s_cbranch_vccnz .LBB0_1802
	v_cvt_f32_f16_sdwa v167, v62 dst_sel:DWORD dst_unused:UNUSED_PAD src0_sel:WORD_1
	v_cvt_f32_f16_e32 v166, v62
	v_cvt_f32_f16_sdwa v163, v63 dst_sel:DWORD dst_unused:UNUSED_PAD src0_sel:WORD_1
	v_cvt_f32_f16_e32 v162, v63
	v_cvt_f32_f16_sdwa v161, v64 dst_sel:DWORD dst_unused:UNUSED_PAD src0_sel:WORD_1
	v_cvt_f32_f16_e32 v160, v64
	v_cvt_f32_f16_sdwa v165, v65 dst_sel:DWORD dst_unused:UNUSED_PAD src0_sel:WORD_1
	v_cvt_f32_f16_e32 v164, v65
	v_cvt_f32_f16_sdwa v155, v58 dst_sel:DWORD dst_unused:UNUSED_PAD src0_sel:WORD_1
	v_cvt_f32_f16_e32 v154, v58
	v_cvt_f32_f16_sdwa v157, v59 dst_sel:DWORD dst_unused:UNUSED_PAD src0_sel:WORD_1
	v_cvt_f32_f16_e32 v156, v59
	v_cvt_f32_f16_sdwa v153, v60 dst_sel:DWORD dst_unused:UNUSED_PAD src0_sel:WORD_1
	v_cvt_f32_f16_e32 v152, v60
	v_cvt_f32_f16_sdwa v159, v61 dst_sel:DWORD dst_unused:UNUSED_PAD src0_sel:WORD_1
	v_cvt_f32_f16_e32 v158, v61
	v_cvt_f32_f16_sdwa v61, v54 dst_sel:DWORD dst_unused:UNUSED_PAD src0_sel:WORD_1
	v_cvt_f32_f16_e32 v60, v54
	v_cvt_f32_f16_sdwa v63, v55 dst_sel:DWORD dst_unused:UNUSED_PAD src0_sel:WORD_1
	v_cvt_f32_f16_e32 v62, v55
	v_cvt_f32_f16_sdwa v59, v56 dst_sel:DWORD dst_unused:UNUSED_PAD src0_sel:WORD_1
	v_cvt_f32_f16_e32 v58, v56
	v_cvt_f32_f16_sdwa v65, v57 dst_sel:DWORD dst_unused:UNUSED_PAD src0_sel:WORD_1
	v_cvt_f32_f16_e32 v64, v57
	v_cvt_f32_f16_sdwa v55, v50 dst_sel:DWORD dst_unused:UNUSED_PAD src0_sel:WORD_1
	v_cvt_f32_f16_e32 v54, v50
	v_cvt_f32_f16_sdwa v57, v51 dst_sel:DWORD dst_unused:UNUSED_PAD src0_sel:WORD_1
	v_cvt_f32_f16_e32 v56, v51
	v_cvt_f32_f16_sdwa v33, v52 dst_sel:DWORD dst_unused:UNUSED_PAD src0_sel:WORD_1
	v_cvt_f32_f16_e32 v32, v52
	v_cvt_f32_f16_sdwa v51, v53 dst_sel:DWORD dst_unused:UNUSED_PAD src0_sel:WORD_1
	v_cvt_f32_f16_e32 v50, v53
	s_cmpk_gt_i32 s14, 0x3fff
	s_cselect_b64 s[2:3], -1, 0
	s_cmpk_lt_i32 s14, 0x4000
	s_cbranch_scc1 .LBB0_1815
	s_add_i32 s86, s14, 0xffffc000
	s_lshl_b64 s[0:1], s[86:87], 13
	v_lshl_add_u64 v[52:53], v[82:83], 0, s[0:1]
	global_load_dwordx4 v[190:193], v[52:53], off nt
	global_load_dwordx4 v[194:197], v[52:53], off offset:16 nt
	global_load_dwordx4 v[198:201], v[52:53], off offset:2048 nt
	global_load_dwordx4 v[204:207], v[52:53], off offset:2064 nt
	s_mov_b64 s[0:1], 0x400000
	v_lshl_add_u64 v[232:233], v[52:53], 0, s[0:1]
	global_load_dwordx4 v[208:211], v[232:233], off nt
	global_load_dwordx4 v[212:215], v[232:233], off offset:16 nt
	global_load_dwordx4 v[216:219], v[232:233], off offset:2048 nt
	global_load_dwordx4 v[220:223], v[232:233], off offset:2064 nt
	s_mov_b64 s[0:1], 0x800000
	v_lshl_add_u64 v[232:233], v[52:53], 0, s[0:1]
	global_load_dwordx4 v[224:227], v[232:233], off nt
	global_load_dwordx4 v[228:231], v[232:233], off offset:16 nt
	global_load_dwordx4 v[238:241], v[232:233], off offset:2048 nt
	global_load_dwordx4 v[242:245], v[232:233], off offset:2064 nt
	s_waitcnt vmcnt(8)
	v_mov_b64_e32 v[174:175], v[190:191]
	v_mov_b64_e32 v[176:177], v[192:193]
	v_mov_b64_e32 v[178:179], v[194:195]
	v_mov_b64_e32 v[180:181], v[196:197]
	v_mov_b64_e32 v[182:183], v[198:199]
	v_mov_b64_e32 v[184:185], v[200:201]
	v_mov_b64_e32 v[186:187], v[204:205]
	v_mov_b64_e32 v[188:189], v[206:207]
	s_mov_b64 s[0:1], 0xc00000
	v_lshl_add_u64 v[232:233], v[52:53], 0, s[0:1]
	global_load_dwordx4 v[190:193], v[232:233], off nt
	global_load_dwordx4 v[194:197], v[232:233], off offset:16 nt
	global_load_dwordx4 v[198:201], v[232:233], off offset:2048 nt
	global_load_dwordx4 v[204:207], v[232:233], off offset:2064 nt
	s_waitcnt vmcnt(8)
	v_pk_add_f32 v[174:175], v[174:175], v[208:209]
	v_pk_add_f32 v[176:177], v[176:177], v[210:211]
	v_pk_add_f32 v[178:179], v[178:179], v[212:213]
	v_pk_add_f32 v[180:181], v[180:181], v[214:215]
	v_pk_add_f32 v[182:183], v[182:183], v[216:217]
	v_pk_add_f32 v[184:185], v[184:185], v[218:219]
	v_pk_add_f32 v[186:187], v[186:187], v[220:221]
	v_pk_add_f32 v[188:189], v[188:189], v[222:223]
	s_mov_b64 s[0:1], 0x1000000
	v_lshl_add_u64 v[232:233], v[52:53], 0, s[0:1]
	global_load_dwordx4 v[208:211], v[232:233], off nt
	global_load_dwordx4 v[212:215], v[232:233], off offset:16 nt
	global_load_dwordx4 v[216:219], v[232:233], off offset:2048 nt
	global_load_dwordx4 v[220:223], v[232:233], off offset:2064 nt
	s_waitcnt vmcnt(8)
	v_pk_add_f32 v[174:175], v[174:175], v[224:225]
	v_pk_add_f32 v[176:177], v[176:177], v[226:227]
	v_pk_add_f32 v[178:179], v[178:179], v[228:229]
	v_pk_add_f32 v[180:181], v[180:181], v[230:231]
	v_pk_add_f32 v[182:183], v[182:183], v[238:239]
	v_pk_add_f32 v[184:185], v[184:185], v[240:241]
	v_pk_add_f32 v[186:187], v[186:187], v[242:243]
	v_pk_add_f32 v[188:189], v[188:189], v[244:245]
	s_mov_b64 s[0:1], 0x1400000
	v_lshl_add_u64 v[232:233], v[52:53], 0, s[0:1]
	global_load_dwordx4 v[224:227], v[232:233], off nt
	global_load_dwordx4 v[228:231], v[232:233], off offset:16 nt
	global_load_dwordx4 v[238:241], v[232:233], off offset:2048 nt
	global_load_dwordx4 v[242:245], v[232:233], off offset:2064 nt
	s_waitcnt vmcnt(8)
	v_pk_add_f32 v[174:175], v[174:175], v[190:191]
	v_pk_add_f32 v[176:177], v[176:177], v[192:193]
	v_pk_add_f32 v[178:179], v[178:179], v[194:195]
	v_pk_add_f32 v[180:181], v[180:181], v[196:197]
	v_pk_add_f32 v[182:183], v[182:183], v[198:199]
	v_pk_add_f32 v[184:185], v[184:185], v[200:201]
	v_pk_add_f32 v[186:187], v[186:187], v[204:205]
	v_pk_add_f32 v[188:189], v[188:189], v[206:207]
	s_mov_b64 s[0:1], 0x1800000
	v_lshl_add_u64 v[232:233], v[52:53], 0, s[0:1]
	global_load_dwordx4 v[190:193], v[232:233], off nt
	global_load_dwordx4 v[194:197], v[232:233], off offset:16 nt
	global_load_dwordx4 v[198:201], v[232:233], off offset:2048 nt
	global_load_dwordx4 v[204:207], v[232:233], off offset:2064 nt
	s_waitcnt vmcnt(8)
	v_pk_add_f32 v[174:175], v[174:175], v[208:209]
	v_pk_add_f32 v[176:177], v[176:177], v[210:211]
	v_pk_add_f32 v[178:179], v[178:179], v[212:213]
	v_pk_add_f32 v[180:181], v[180:181], v[214:215]
	v_pk_add_f32 v[182:183], v[182:183], v[216:217]
	v_pk_add_f32 v[184:185], v[184:185], v[218:219]
	v_pk_add_f32 v[186:187], v[186:187], v[220:221]
	v_pk_add_f32 v[188:189], v[188:189], v[222:223]
	s_mov_b64 s[0:1], 0x1c00000
	v_lshl_add_u64 v[232:233], v[52:53], 0, s[0:1]
	global_load_dwordx4 v[208:211], v[232:233], off nt
	global_load_dwordx4 v[212:215], v[232:233], off offset:16 nt
	global_load_dwordx4 v[216:219], v[232:233], off offset:2048 nt
	global_load_dwordx4 v[220:223], v[232:233], off offset:2064 nt
	s_waitcnt vmcnt(8)
	v_pk_add_f32 v[174:175], v[174:175], v[224:225]
	v_pk_add_f32 v[176:177], v[176:177], v[226:227]
	v_pk_add_f32 v[178:179], v[178:179], v[228:229]
	v_pk_add_f32 v[180:181], v[180:181], v[230:231]
	v_pk_add_f32 v[182:183], v[182:183], v[238:239]
	v_pk_add_f32 v[184:185], v[184:185], v[240:241]
	v_pk_add_f32 v[186:187], v[186:187], v[242:243]
	v_pk_add_f32 v[188:189], v[188:189], v[244:245]
	s_mov_b64 s[0:1], 0x2000000
	v_lshl_add_u64 v[232:233], v[52:53], 0, s[0:1]
	global_load_dwordx4 v[224:227], v[232:233], off nt
	global_load_dwordx4 v[228:231], v[232:233], off offset:16 nt
	global_load_dwordx4 v[238:241], v[232:233], off offset:2048 nt
	global_load_dwordx4 v[242:245], v[232:233], off offset:2064 nt
	s_waitcnt vmcnt(8)
	v_pk_add_f32 v[174:175], v[174:175], v[190:191]
	v_pk_add_f32 v[176:177], v[176:177], v[192:193]
	v_pk_add_f32 v[178:179], v[178:179], v[194:195]
	v_pk_add_f32 v[180:181], v[180:181], v[196:197]
	v_pk_add_f32 v[182:183], v[182:183], v[198:199]
	v_pk_add_f32 v[184:185], v[184:185], v[200:201]
	v_pk_add_f32 v[186:187], v[186:187], v[204:205]
	v_pk_add_f32 v[188:189], v[188:189], v[206:207]
	s_mov_b64 s[0:1], 0x2400000
	v_lshl_add_u64 v[232:233], v[52:53], 0, s[0:1]
	global_load_dwordx4 v[190:193], v[232:233], off nt
	global_load_dwordx4 v[194:197], v[232:233], off offset:16 nt
	global_load_dwordx4 v[198:201], v[232:233], off offset:2048 nt
	global_load_dwordx4 v[204:207], v[232:233], off offset:2064 nt
	s_waitcnt vmcnt(8)
	v_pk_add_f32 v[174:175], v[174:175], v[208:209]
	v_pk_add_f32 v[176:177], v[176:177], v[210:211]
	v_pk_add_f32 v[178:179], v[178:179], v[212:213]
	v_pk_add_f32 v[180:181], v[180:181], v[214:215]
	v_pk_add_f32 v[182:183], v[182:183], v[216:217]
	v_pk_add_f32 v[184:185], v[184:185], v[218:219]
	v_pk_add_f32 v[186:187], v[186:187], v[220:221]
	v_pk_add_f32 v[188:189], v[188:189], v[222:223]
	s_mov_b64 s[0:1], 0x2800000
	v_lshl_add_u64 v[232:233], v[52:53], 0, s[0:1]
	global_load_dwordx4 v[208:211], v[232:233], off nt
	global_load_dwordx4 v[212:215], v[232:233], off offset:16 nt
	global_load_dwordx4 v[216:219], v[232:233], off offset:2048 nt
	global_load_dwordx4 v[220:223], v[232:233], off offset:2064 nt
	s_waitcnt vmcnt(8)
	v_pk_add_f32 v[174:175], v[174:175], v[224:225]
	v_pk_add_f32 v[176:177], v[176:177], v[226:227]
	v_pk_add_f32 v[178:179], v[178:179], v[228:229]
	v_pk_add_f32 v[180:181], v[180:181], v[230:231]
	v_pk_add_f32 v[182:183], v[182:183], v[238:239]
	v_pk_add_f32 v[184:185], v[184:185], v[240:241]
	v_pk_add_f32 v[186:187], v[186:187], v[242:243]
	v_pk_add_f32 v[188:189], v[188:189], v[244:245]
	global_load_dwordx4 v[224:227], v[74:75], off
	global_load_dwordx4 v[228:231], v[74:75], off offset:16
	global_load_dwordx4 v[238:241], v[74:75], off offset:2048
	global_load_dwordx4 v[242:245], v[74:75], off offset:2064
	s_waitcnt vmcnt(8)
	v_pk_add_f32 v[174:175], v[174:175], v[190:191]
	v_pk_add_f32 v[176:177], v[176:177], v[192:193]
	v_pk_add_f32 v[178:179], v[178:179], v[194:195]
	v_pk_add_f32 v[180:181], v[180:181], v[196:197]
	v_pk_add_f32 v[182:183], v[182:183], v[198:199]
	v_pk_add_f32 v[184:185], v[184:185], v[200:201]
	v_pk_add_f32 v[186:187], v[186:187], v[204:205]
	v_pk_add_f32 v[188:189], v[188:189], v[206:207]
	s_mov_b64 s[0:1], 0x1000
	v_lshl_add_u64 v[232:233], v[52:53], 0, s[0:1]
	global_load_dwordx4 v[190:193], v[232:233], off nt
	global_load_dwordx4 v[194:197], v[232:233], off offset:16 nt
	global_load_dwordx4 v[198:201], v[232:233], off offset:2048 nt
	global_load_dwordx4 v[204:207], v[232:233], off offset:2064 nt
	s_waitcnt vmcnt(8)
	v_pk_add_f32 v[174:175], v[174:175], v[208:209]
	v_pk_add_f32 v[176:177], v[176:177], v[210:211]
	v_pk_add_f32 v[178:179], v[178:179], v[212:213]
	v_pk_add_f32 v[180:181], v[180:181], v[214:215]
	v_pk_add_f32 v[182:183], v[182:183], v[216:217]
	v_pk_add_f32 v[184:185], v[184:185], v[218:219]
	v_pk_add_f32 v[186:187], v[186:187], v[220:221]
	v_pk_add_f32 v[188:189], v[188:189], v[222:223]
	s_mov_b64 s[0:1], 0x401000
	v_lshl_add_u64 v[232:233], v[52:53], 0, s[0:1]
	global_load_dwordx4 v[208:211], v[232:233], off nt
	global_load_dwordx4 v[212:215], v[232:233], off offset:16 nt
	global_load_dwordx4 v[216:219], v[232:233], off offset:2048 nt
	global_load_dwordx4 v[220:223], v[232:233], off offset:2064 nt
	s_waitcnt vmcnt(8)
	v_pk_fma_f32 v[166:167], v[174:175], v[224:225], v[166:167]
	v_pk_fma_f32 v[162:163], v[176:177], v[226:227], v[162:163]
	v_pk_fma_f32 v[160:161], v[178:179], v[228:229], v[160:161]
	v_pk_fma_f32 v[164:165], v[180:181], v[230:231], v[164:165]
	v_pk_fma_f32 v[154:155], v[182:183], v[238:239], v[154:155]
	v_pk_fma_f32 v[156:157], v[184:185], v[240:241], v[156:157]
	v_pk_fma_f32 v[152:153], v[186:187], v[242:243], v[152:153]
	v_pk_fma_f32 v[158:159], v[188:189], v[244:245], v[158:159]
	s_mov_b64 s[0:1], 0x801000
	v_lshl_add_u64 v[232:233], v[52:53], 0, s[0:1]
	global_load_dwordx4 v[224:227], v[232:233], off nt
	global_load_dwordx4 v[228:231], v[232:233], off offset:16 nt
	global_load_dwordx4 v[238:241], v[232:233], off offset:2048 nt
	global_load_dwordx4 v[242:245], v[232:233], off offset:2064 nt
	s_waitcnt vmcnt(8)
	v_mov_b64_e32 v[174:175], v[190:191]
	v_mov_b64_e32 v[176:177], v[192:193]
	v_mov_b64_e32 v[178:179], v[194:195]
	v_mov_b64_e32 v[180:181], v[196:197]
	v_mov_b64_e32 v[182:183], v[198:199]
	v_mov_b64_e32 v[184:185], v[200:201]
	v_mov_b64_e32 v[186:187], v[204:205]
	v_mov_b64_e32 v[188:189], v[206:207]
	s_mov_b64 s[0:1], 0xc01000
	v_lshl_add_u64 v[232:233], v[52:53], 0, s[0:1]
	global_load_dwordx4 v[190:193], v[232:233], off nt
	global_load_dwordx4 v[194:197], v[232:233], off offset:16 nt
	global_load_dwordx4 v[198:201], v[232:233], off offset:2048 nt
	global_load_dwordx4 v[204:207], v[232:233], off offset:2064 nt
	s_waitcnt vmcnt(8)
	v_pk_add_f32 v[174:175], v[174:175], v[208:209]
	v_pk_add_f32 v[176:177], v[176:177], v[210:211]
	v_pk_add_f32 v[178:179], v[178:179], v[212:213]
	v_pk_add_f32 v[180:181], v[180:181], v[214:215]
	v_pk_add_f32 v[182:183], v[182:183], v[216:217]
	v_pk_add_f32 v[184:185], v[184:185], v[218:219]
	v_pk_add_f32 v[186:187], v[186:187], v[220:221]
	v_pk_add_f32 v[188:189], v[188:189], v[222:223]
	s_mov_b64 s[0:1], 0x1001000
	v_lshl_add_u64 v[232:233], v[52:53], 0, s[0:1]
	global_load_dwordx4 v[208:211], v[232:233], off nt
	global_load_dwordx4 v[212:215], v[232:233], off offset:16 nt
	global_load_dwordx4 v[216:219], v[232:233], off offset:2048 nt
	global_load_dwordx4 v[220:223], v[232:233], off offset:2064 nt
	s_waitcnt vmcnt(8)
	v_pk_add_f32 v[174:175], v[174:175], v[224:225]
	v_pk_add_f32 v[176:177], v[176:177], v[226:227]
	v_pk_add_f32 v[178:179], v[178:179], v[228:229]
	v_pk_add_f32 v[180:181], v[180:181], v[230:231]
	v_pk_add_f32 v[182:183], v[182:183], v[238:239]
	v_pk_add_f32 v[184:185], v[184:185], v[240:241]
	v_pk_add_f32 v[186:187], v[186:187], v[242:243]
	v_pk_add_f32 v[188:189], v[188:189], v[244:245]
	s_mov_b64 s[0:1], 0x1401000
	v_lshl_add_u64 v[232:233], v[52:53], 0, s[0:1]
	global_load_dwordx4 v[224:227], v[232:233], off nt
	global_load_dwordx4 v[228:231], v[232:233], off offset:16 nt
	global_load_dwordx4 v[238:241], v[232:233], off offset:2048 nt
	global_load_dwordx4 v[242:245], v[232:233], off offset:2064 nt
	s_waitcnt vmcnt(8)
	v_pk_add_f32 v[174:175], v[174:175], v[190:191]
	v_pk_add_f32 v[176:177], v[176:177], v[192:193]
	v_pk_add_f32 v[178:179], v[178:179], v[194:195]
	v_pk_add_f32 v[180:181], v[180:181], v[196:197]
	v_pk_add_f32 v[182:183], v[182:183], v[198:199]
	v_pk_add_f32 v[184:185], v[184:185], v[200:201]
	v_pk_add_f32 v[186:187], v[186:187], v[204:205]
	v_pk_add_f32 v[188:189], v[188:189], v[206:207]
	s_mov_b64 s[0:1], 0x1801000
	v_lshl_add_u64 v[232:233], v[52:53], 0, s[0:1]
	global_load_dwordx4 v[190:193], v[232:233], off nt
	global_load_dwordx4 v[194:197], v[232:233], off offset:16 nt
	global_load_dwordx4 v[198:201], v[232:233], off offset:2048 nt
	global_load_dwordx4 v[204:207], v[232:233], off offset:2064 nt
	s_waitcnt vmcnt(8)
	v_pk_add_f32 v[174:175], v[174:175], v[208:209]
	v_pk_add_f32 v[176:177], v[176:177], v[210:211]
	v_pk_add_f32 v[178:179], v[178:179], v[212:213]
	v_pk_add_f32 v[180:181], v[180:181], v[214:215]
	v_pk_add_f32 v[182:183], v[182:183], v[216:217]
	v_pk_add_f32 v[184:185], v[184:185], v[218:219]
	v_pk_add_f32 v[186:187], v[186:187], v[220:221]
	v_pk_add_f32 v[188:189], v[188:189], v[222:223]
	s_mov_b64 s[0:1], 0x1c01000
	v_lshl_add_u64 v[232:233], v[52:53], 0, s[0:1]
	global_load_dwordx4 v[208:211], v[232:233], off nt
	global_load_dwordx4 v[212:215], v[232:233], off offset:16 nt
	global_load_dwordx4 v[216:219], v[232:233], off offset:2048 nt
	global_load_dwordx4 v[220:223], v[232:233], off offset:2064 nt
	s_waitcnt vmcnt(8)
	v_pk_add_f32 v[174:175], v[174:175], v[224:225]
	v_pk_add_f32 v[176:177], v[176:177], v[226:227]
	v_pk_add_f32 v[178:179], v[178:179], v[228:229]
	v_pk_add_f32 v[180:181], v[180:181], v[230:231]
	v_pk_add_f32 v[182:183], v[182:183], v[238:239]
	v_pk_add_f32 v[184:185], v[184:185], v[240:241]
	v_pk_add_f32 v[186:187], v[186:187], v[242:243]
	v_pk_add_f32 v[188:189], v[188:189], v[244:245]
	s_mov_b64 s[0:1], 0x2001000
	v_lshl_add_u64 v[232:233], v[52:53], 0, s[0:1]
	global_load_dwordx4 v[224:227], v[232:233], off nt
	global_load_dwordx4 v[228:231], v[232:233], off offset:16 nt
	global_load_dwordx4 v[238:241], v[232:233], off offset:2048 nt
	global_load_dwordx4 v[242:245], v[232:233], off offset:2064 nt
	s_waitcnt vmcnt(8)
	v_pk_add_f32 v[174:175], v[174:175], v[190:191]
	v_pk_add_f32 v[176:177], v[176:177], v[192:193]
	v_pk_add_f32 v[178:179], v[178:179], v[194:195]
	v_pk_add_f32 v[180:181], v[180:181], v[196:197]
	v_pk_add_f32 v[182:183], v[182:183], v[198:199]
	v_pk_add_f32 v[184:185], v[184:185], v[200:201]
	v_pk_add_f32 v[186:187], v[186:187], v[204:205]
	v_pk_add_f32 v[188:189], v[188:189], v[206:207]
	s_mov_b64 s[0:1], 0x2401000
	v_lshl_add_u64 v[232:233], v[52:53], 0, s[0:1]
	global_load_dwordx4 v[190:193], v[232:233], off nt
	global_load_dwordx4 v[194:197], v[232:233], off offset:16 nt
	global_load_dwordx4 v[198:201], v[232:233], off offset:2048 nt
	global_load_dwordx4 v[204:207], v[232:233], off offset:2064 nt
	s_waitcnt vmcnt(8)
	v_pk_add_f32 v[174:175], v[174:175], v[208:209]
	v_pk_add_f32 v[176:177], v[176:177], v[210:211]
	v_pk_add_f32 v[178:179], v[178:179], v[212:213]
	v_pk_add_f32 v[180:181], v[180:181], v[214:215]
	v_pk_add_f32 v[182:183], v[182:183], v[216:217]
	v_pk_add_f32 v[184:185], v[184:185], v[218:219]
	v_pk_add_f32 v[186:187], v[186:187], v[220:221]
	v_pk_add_f32 v[188:189], v[188:189], v[222:223]
	s_mov_b64 s[0:1], 0x2801000
	v_lshl_add_u64 v[232:233], v[52:53], 0, s[0:1]
	global_load_dwordx4 v[208:211], v[232:233], off nt
	global_load_dwordx4 v[212:215], v[232:233], off offset:16 nt
	global_load_dwordx4 v[216:219], v[232:233], off offset:2048 nt
	global_load_dwordx4 v[220:223], v[232:233], off offset:2064 nt
	s_waitcnt vmcnt(8)
	v_pk_add_f32 v[174:175], v[174:175], v[224:225]
	v_pk_add_f32 v[176:177], v[176:177], v[226:227]
	v_pk_add_f32 v[178:179], v[178:179], v[228:229]
	v_pk_add_f32 v[180:181], v[180:181], v[230:231]
	v_pk_add_f32 v[182:183], v[182:183], v[238:239]
	v_pk_add_f32 v[184:185], v[184:185], v[240:241]
	v_pk_add_f32 v[186:187], v[186:187], v[242:243]
	v_pk_add_f32 v[188:189], v[188:189], v[244:245]
	global_load_dwordx4 v[224:227], v[76:77], off
	global_load_dwordx4 v[228:231], v[76:77], off offset:16
	global_load_dwordx4 v[238:241], v[78:79], off
	global_load_dwordx4 v[242:245], v[78:79], off offset:16
	s_waitcnt vmcnt(8)
	v_pk_add_f32 v[174:175], v[174:175], v[190:191]
	v_pk_add_f32 v[176:177], v[176:177], v[192:193]
	v_pk_add_f32 v[178:179], v[178:179], v[194:195]
	v_pk_add_f32 v[180:181], v[180:181], v[196:197]
	v_pk_add_f32 v[182:183], v[182:183], v[198:199]
	v_pk_add_f32 v[184:185], v[184:185], v[200:201]
	v_pk_add_f32 v[186:187], v[186:187], v[204:205]
	v_pk_add_f32 v[188:189], v[188:189], v[206:207]
	s_waitcnt vmcnt(4)
	v_pk_add_f32 v[174:175], v[174:175], v[208:209]
	v_pk_add_f32 v[176:177], v[176:177], v[210:211]
	v_pk_add_f32 v[178:179], v[178:179], v[212:213]
	v_pk_add_f32 v[180:181], v[180:181], v[214:215]
	v_pk_add_f32 v[182:183], v[182:183], v[216:217]
	v_pk_add_f32 v[184:185], v[184:185], v[218:219]
	v_pk_add_f32 v[186:187], v[186:187], v[220:221]
	v_pk_add_f32 v[188:189], v[188:189], v[222:223]
	s_waitcnt vmcnt(0)
	v_pk_fma_f32 v[60:61], v[174:175], v[224:225], v[60:61]
	v_pk_fma_f32 v[62:63], v[176:177], v[226:227], v[62:63]
	v_pk_fma_f32 v[58:59], v[178:179], v[228:229], v[58:59]
	v_pk_fma_f32 v[64:65], v[180:181], v[230:231], v[64:65]
	v_pk_fma_f32 v[54:55], v[182:183], v[238:239], v[54:55]
	v_pk_fma_f32 v[56:57], v[184:185], v[240:241], v[56:57]
	v_pk_fma_f32 v[32:33], v[186:187], v[242:243], v[32:33]
	v_pk_fma_f32 v[50:51], v[188:189], v[244:245], v[50:51]
